# v22: split packed VOP3P fp32 ops (v_pk_add/mul/fma_f32) into scalar pairs in the attention code (doc 7.5)
# speedup vs baseline: 1.0025x; 1.0025x over previous
.LBB0_198:
	s_cmp_gt_i32 s16, 2
	s_mov_b64 s[4:5], -1
	s_cbranch_scc0 .LBB0_309
	s_lshl_b32 s23, s28, 2
	s_lshl_b32 s14, s28, 8
	s_or_b32 s30, s23, 3
	s_mul_i32 s5, s27, 0x1800000
	v_readlane_b32 s6, v255, 11
	s_mul_hi_i32 s4, s27, 0x1800000
	v_readlane_b32 s7, v255, 12
	s_add_u32 s6, s6, s5
	s_addc_u32 s7, s7, s4
	s_lshl_b32 s4, s29, 3
	s_sub_i32 s4, 0xffffffd8, s4
	v_cvt_f32_i32_e32 v0, s4
	s_mov_b32 s8, 0x41400000
	v_mov_b32_e32 v198, v241
	v_mov_b32_e32 v11, v241
	v_div_scale_f32 v1, s[4:5], s8, s8, v0
	v_rcp_f32_e32 v2, v1
	s_mov_b32 s4, 0xc2fc0000
	v_fma_f32 v3, -v1, v2, 1.0
	v_fmac_f32_e32 v2, v3, v2
	v_div_scale_f32 v3, vcc, v0, s8, v0
	v_mul_f32_e32 v4, v3, v2
	v_fma_f32 v5, -v1, v4, v3
	v_fmac_f32_e32 v4, v5, v2
	v_fma_f32 v1, -v1, v4, v3
	v_div_fmas_f32 v1, v1, v2, v4
	v_div_fixup_f32 v0, v1, s8, v0
	v_cmp_gt_f32_e32 vcc, s4, v0
	s_and_b64 s[4:5], vcc, exec
	s_cselect_b32 s4, 0xffffffc0, 0
	v_cndmask_b32_e32 v1, 0, v238, vcc
	v_add_f32_e32 v0, v0, v1
	v_exp_f32_e32 v0, v0
	v_and_b32_e32 v14, 31, v11
	v_bfe_u32 v8, v11, 5, 1
	s_movk_i32 s8, 0x3000
	v_ldexp_f32 v0, v0, s4
	s_lshl_b32 s4, s29, 7
	s_add_u32 s4, s6, s4
	s_addc_u32 s5, s7, 0
	s_add_u32 s6, s4, 0x2400
	s_addc_u32 s7, s5, 0
	s_add_u32 s90, s4, 0x2800
	s_addc_u32 s91, s5, 0
	s_add_u32 s92, s4, 0x2c00
	s_addc_u32 s93, s5, 0
	v_readfirstlane_b32 s5, v11
	s_ashr_i32 s4, s5, 6
	s_lshl_b32 s31, s4, 5
	s_add_i32 s31, s31, s14
	v_mul_f32_e32 v192, 0x3fb8aa3b, v0
	v_or_b32_e32 v199, s31, v14
	v_mov_b64_e32 v[0:1], s[6:7]
	v_mad_i64_i32 v[0:1], s[6:7], v199, s8, v[0:1]
	v_lshlrev_b32_e32 v128, 4, v8
	v_lshl_add_u64 v[0:1], v[0:1], 0, v[128:129]
	global_load_dwordx4 v[2:5], v[0:1], off
	global_load_dwordx4 v[16:19], v[0:1], off offset:32
	global_load_dwordx4 v[20:23], v[0:1], off offset:64
	global_load_dwordx4 v[24:27], v[0:1], off offset:96
	s_mov_b32 s6, 0x3e38aa3b
	v_and_b32_e32 v10, 63, v11
	s_ashr_i32 s26, s5, 7
	v_lshlrev_b32_e32 v200, 2, v8
	v_readfirstlane_b32 s15, v198
	v_xor_b32_e32 v203, 0x80000000, v192
	s_waitcnt vmcnt(3)
	v_and_b32_e32 v7, 0xffff0000, v2
	v_lshlrev_b32_e32 v6, 16, v2
	v_mul_f32_e32 v6, s6, v6
	v_mul_f32_e32 v7, s6, v7
	s_nop 0
	v_cvt_pk_bf16_f32 v144, v6, v7
	v_and_b32_e32 v7, 0xffff0000, v3
	v_lshlrev_b32_e32 v6, 16, v3
	v_mul_f32_e32 v2, s6, v6
	v_mul_f32_e32 v3, s6, v7
	s_nop 0
	v_cvt_pk_bf16_f32 v145, v2, v3
	v_and_b32_e32 v3, 0xffff0000, v4
	v_lshlrev_b32_e32 v2, 16, v4
	v_mul_f32_e32 v2, s6, v2
	v_mul_f32_e32 v3, s6, v3
	s_nop 0
	v_cvt_pk_bf16_f32 v146, v2, v3
	v_and_b32_e32 v3, 0xffff0000, v5
	v_lshlrev_b32_e32 v2, 16, v5
	v_mul_f32_e32 v2, s6, v2
	v_mul_f32_e32 v3, s6, v3
	s_nop 0
	v_cvt_pk_bf16_f32 v147, v2, v3
	s_waitcnt vmcnt(2)
	v_and_b32_e32 v7, 0xffff0000, v16
	v_lshlrev_b32_e32 v6, 16, v16
	v_mul_f32_e32 v6, s6, v6
	v_mul_f32_e32 v7, s6, v7
	s_nop 0
	v_cvt_pk_bf16_f32 v148, v6, v7
	v_and_b32_e32 v7, 0xffff0000, v17
	v_lshlrev_b32_e32 v6, 16, v17
	v_mul_f32_e32 v2, s6, v6
	v_mul_f32_e32 v3, s6, v7
	s_nop 0
	v_cvt_pk_bf16_f32 v149, v2, v3
	v_and_b32_e32 v3, 0xffff0000, v18
	v_lshlrev_b32_e32 v2, 16, v18
	v_mul_f32_e32 v2, s6, v2
	v_mul_f32_e32 v3, s6, v3
	s_nop 0
	v_cvt_pk_bf16_f32 v150, v2, v3
	v_and_b32_e32 v3, 0xffff0000, v19
	v_lshlrev_b32_e32 v2, 16, v19
	v_mul_f32_e32 v2, s6, v2
	v_mul_f32_e32 v3, s6, v3
	s_nop 0
	v_cvt_pk_bf16_f32 v151, v2, v3
	s_waitcnt vmcnt(1)
	v_and_b32_e32 v7, 0xffff0000, v20
	v_lshlrev_b32_e32 v6, 16, v20
	v_mul_f32_e32 v6, s6, v6
	v_mul_f32_e32 v7, s6, v7
	s_nop 0
	v_cvt_pk_bf16_f32 v152, v6, v7
	v_and_b32_e32 v7, 0xffff0000, v21
	v_lshlrev_b32_e32 v6, 16, v21
	v_mul_f32_e32 v2, s6, v6
	v_mul_f32_e32 v3, s6, v7
	s_nop 0
	v_cvt_pk_bf16_f32 v153, v2, v3
	v_and_b32_e32 v3, 0xffff0000, v22
	v_lshlrev_b32_e32 v2, 16, v22
	v_mul_f32_e32 v2, s6, v2
	v_mul_f32_e32 v3, s6, v3
	s_nop 0
	v_cvt_pk_bf16_f32 v154, v2, v3
	v_and_b32_e32 v3, 0xffff0000, v23
	v_lshlrev_b32_e32 v2, 16, v23
	v_mul_f32_e32 v2, s6, v2
	v_mul_f32_e32 v3, s6, v3
	s_nop 0
	v_cvt_pk_bf16_f32 v155, v2, v3
	s_waitcnt vmcnt(0)
	v_and_b32_e32 v5, 0xffff0000, v24
	v_lshlrev_b32_e32 v4, 16, v24
	v_mul_f32_e32 v4, s6, v4
	v_mul_f32_e32 v5, s6, v5
	s_nop 0
	v_cvt_pk_bf16_f32 v156, v4, v5
	v_and_b32_e32 v5, 0xffff0000, v25
	v_lshlrev_b32_e32 v4, 16, v25
	v_mul_f32_e32 v0, s6, v4
	v_mul_f32_e32 v1, s6, v5
	v_lshlrev_b32_e32 v4, 1, v11
	v_cvt_pk_bf16_f32 v157, v0, v1
	v_and_b32_e32 v1, 0xffff0000, v26
	v_lshlrev_b32_e32 v0, 16, v26
	v_mul_f32_e32 v0, s6, v0
	v_mul_f32_e32 v1, s6, v1
	s_nop 0
	v_cvt_pk_bf16_f32 v158, v0, v1
	v_and_b32_e32 v1, 0xffff0000, v27
	v_lshlrev_b32_e32 v0, 16, v27
	v_mul_u32_u24_e32 v3, 0x3000, v10
	v_mul_f32_e32 v0, s6, v0
	v_mul_f32_e32 v1, s6, v1
	v_lshl_add_u32 v12, s4, 4, v3
	v_and_b32_e32 v3, 51, v11
	v_cvt_pk_bf16_f32 v159, v0, v1
	v_lshlrev_b32_e32 v0, 4, v11
	v_and_or_b32 v3, v4, 8, v3
	v_ashrrev_i32_e32 v1, 3, v11
	v_lshlrev_b32_e32 v3, 1, v3
	v_and_b32_e32 v4, 8, v11
	v_and_b32_e32 v0, 0x70, v0
	s_mulk_i32 s4, 0x480
	s_movk_i32 s6, 0x90
	v_mul_lo_u32 v2, v1, s8
	v_or3_b32 v15, v3, v4, s4
	v_mad_u64_u32 v[8:9], s[4:5], v1, s6, v[0:1]
	v_or_b32_e32 v13, v0, v2
	s_mul_i32 s4, s30, 0xc0000
	v_add_u32_e32 v0, s4, v13
	global_load_dwordx4 v[4:7], v0, s[90:91]
	v_add_u32_e32 v9, s4, v12
	s_mul_i32 s4, s28, 0x300000
	v_add_u32_e32 v16, s4, v13
	s_add_i32 s5, s4, 0x180000
	v_add_u32_e32 v16, 0xc0000, v16
	global_load_dwordx4 v[160:163], v16, s[90:91]
	v_add_u32_e32 v0, s5, v13
	v_add_u32_e32 v201, 0, v8
	global_load_dwordx4 v[0:3], v0, s[90:91]
	v_add_u32_e32 v16, s5, v12
	global_load_dwordx4 v[164:167], v16, s[92:93]
	v_add_u32_e32 v202, 0, v15
	s_cmp_gt_i32 s26, 2
	s_waitcnt vmcnt(3)
	ds_write_b128 v201, v[4:7]
	global_load_dwordx4 v[4:7], v9, s[92:93]
	s_waitcnt vmcnt(0)
	ds_write_b16 v202, v4 offset:18432
	ds_write_b16_d16_hi v202, v4 offset:18576
	ds_write_b16 v202, v5 offset:18720
	ds_write_b16_d16_hi v202, v5 offset:18864
	ds_write_b16 v202, v6 offset:19008
	ds_write_b16_d16_hi v202, v6 offset:19152
	ds_write_b16 v202, v7 offset:19296
	ds_write_b16_d16_hi v202, v7 offset:19440
	v_mad_u32_u24 v4, v14, s6, v128
	v_add_u32_e32 v204, 0, v4
	ds_write_b128 v201, v[0:3] offset:9216
	s_waitcnt lgkmcnt(0)
	s_barrier
	s_cbranch_scc0 .LBB0_204
	v_lshl_or_b32 v0, s30, 6, v200
	v_sub_u32_e32 v0, v199, v0
	v_cvt_f32_i32_e32 v1, v0
	s_mov_b32 s4, 2.0
	s_mov_b32 s5, 0x40400000
	v_mul_f32_e64 v0, -v192, v1
	v_fma_f32 v34, v192, s4, v0
	v_fma_f32 v35, v192, s5, v0
	s_mov_b32 s4, 0x41000000
	s_mov_b32 s5, 0x41100000
	v_fma_f32 v36, v192, s4, v0
	v_fma_f32 v37, v192, s5, v0
	s_mov_b32 s4, 0x41200000
	s_mov_b32 s5, 0x41300000
	v_fma_f32 v38, v192, s4, v0
	v_fma_f32 v39, v192, s5, v0
	s_mov_b32 s4, 0x41800000
	s_mov_b32 s5, 0x41880000
	v_fma_f32 v40, v192, s4, v0
	v_fma_f32 v41, v192, s5, v0
	s_mov_b32 s4, 0x41900000
	s_mov_b32 s5, 0x41980000
	v_fma_f32 v42, v192, s4, v0
	v_fma_f32 v43, v192, s5, v0
	s_mov_b32 s4, 0x41c00000
	s_mov_b32 s5, 0x41c80000
	v_fma_f32 v44, v192, s4, v0
	v_fma_f32 v45, v192, s5, v0
	s_mov_b32 s4, 0x41d00000
	s_mov_b32 s5, 0x41d80000
	v_fma_f32 v46, v192, s4, v0
	v_fma_f32 v47, v192, s5, v0
	s_mov_b32 s4, 0x42680000
	s_mov_b32 s5, 0x426c0000
	v_fma_f32 v62, v192, s4, v0
	v_fma_f32 v63, v192, s5, v0
	s_mov_b32 s4, 0x42600000
	s_mov_b32 s5, 0x42640000
	v_fma_f32 v60, v192, s4, v0
	v_fma_f32 v61, v192, s5, v0
	s_mov_b32 s4, 0x42480000
	s_mov_b32 s5, 0x424c0000
	v_fma_f32 v58, v192, s4, v0
	v_fma_f32 v59, v192, s5, v0
	s_mov_b32 s4, 0x42400000
	s_mov_b32 s5, 0x42440000
	v_fma_f32 v56, v192, s4, v0
	v_fma_f32 v57, v192, s5, v0
	s_mov_b32 s4, 0x42280000
	s_mov_b32 s5, 0x422c0000
	v_fma_f32 v54, v192, s4, v0
	v_fma_f32 v55, v192, s5, v0
	s_mov_b32 s4, 0x42200000
	s_mov_b32 s5, 0x42240000
	v_fma_f32 v52, v192, s4, v0
	v_fma_f32 v53, v192, s5, v0
	s_mov_b32 s4, 0x42080000
	s_mov_b32 s5, 0x420c0000
	v_fma_f32 v50, v192, s4, v0
	v_fma_f32 v51, v192, s5, v0
	s_mov_b32 s4, 0x42000000
	s_mov_b32 s5, 0x42040000
	v_fma_f32 v33, -v192, v1, v192
	v_mov_b32_e32 v32, v0
	v_fma_f32 v48, v192, s4, v0
	v_fma_f32 v49, v192, s5, v0
	ds_read_b128 v[0:3], v204
	ds_read_b128 v[4:7], v204 offset:32
	v_fmac_f32_e32 v32, 0, v192
	s_waitcnt lgkmcnt(1)
	s_nop 0
	v_mfma_f32_32x32x16_bf16 v[32:47], v[0:3], v[144:147], v[32:47]
	ds_read_b128 v[0:3], v204 offset:4608
	s_waitcnt lgkmcnt(0)
	v_mfma_f32_32x32x16_bf16 v[48:63], v[0:3], v[144:147], v[48:63]
	ds_read_b128 v[0:3], v204 offset:4640
	s_waitcnt lgkmcnt(0)
	v_mfma_f32_32x32x16_bf16 v[48:63], v[0:3], v[148:151], v[48:63]
	ds_read_b128 v[0:3], v204 offset:64
	v_mfma_f32_32x32x16_bf16 v[32:47], v[4:7], v[148:151], v[32:47]
	s_waitcnt lgkmcnt(0)
	v_mfma_f32_32x32x16_bf16 v[32:47], v[0:3], v[152:155], v[32:47]
	ds_read_b128 v[0:3], v204 offset:4672
	ds_read_b128 v[4:7], v204 offset:96
	ds_read_b128 v[16:19], v204 offset:4704
	s_waitcnt lgkmcnt(2)
	v_mfma_f32_32x32x16_bf16 v[48:63], v[0:3], v[152:155], v[48:63]
	s_waitcnt lgkmcnt(1)
	v_mfma_f32_32x32x16_bf16 v[32:47], v[4:7], v[156:159], v[32:47]
	s_waitcnt lgkmcnt(0)
	v_mfma_f32_32x32x16_bf16 v[48:63], v[16:19], v[156:159], v[48:63]
	v_mov_b64_e32 v[194:195], v[192:193]
	s_lshl_b32 s22, s29, 6
	s_cbranch_execz .LBB0_205
	s_branch .LBB0_206

.LBB0_212:
	s_or_b32 s19, s25, 1
	s_cmp_lt_u32 s19, s17
	s_cselect_b64 s[88:89], -1, 0
	s_cmp_ge_u32 s19, s17
	s_cbranch_scc1 .LBB0_215
	s_add_i32 s5, s4, -1
	s_cmp_gt_i32 s5, s26
	s_cbranch_scc1 .LBB0_215
	v_lshl_or_b32 v64, s5, 6, v200
	v_sub_u32_e32 v64, v199, v64
	v_cvt_f32_i32_e32 v64, v64
	s_mov_b32 s6, 2.0
	s_mov_b32 s7, 0x40400000
	v_mov_b32_e32 v193, v192
	v_mul_f32_e32 v80, v203, v64
	v_fma_f32 v66, v194, s6, v80
	v_fma_f32 v67, v195, s7, v80
	s_mov_b32 s6, 0x41000000
	s_mov_b32 s7, 0x41100000
	v_fma_f32 v68, v194, s6, v80
	v_fma_f32 v69, v195, s7, v80
	s_mov_b32 s6, 0x41200000
	s_mov_b32 s7, 0x41300000
	v_fma_f32 v70, v194, s6, v80
	v_fma_f32 v71, v195, s7, v80
	s_mov_b32 s6, 0x41800000
	s_mov_b32 s7, 0x41880000
	v_fma_f32 v72, v194, s6, v80
	v_fma_f32 v73, v195, s7, v80
	s_mov_b32 s6, 0x41900000
	s_mov_b32 s7, 0x41980000
	v_fma_f32 v74, v194, s6, v80
	v_fma_f32 v75, v195, s7, v80
	s_mov_b32 s6, 0x41c00000
	s_mov_b32 s7, 0x41c80000
	v_fma_f32 v76, v194, s6, v80
	v_fma_f32 v77, v195, s7, v80
	s_mov_b32 s6, 0x41d00000
	s_mov_b32 s7, 0x41d80000
	v_fma_f32 v78, v194, s6, v80
	v_fma_f32 v79, v195, s7, v80
	s_mov_b32 s6, 0x42680000
	s_mov_b32 s7, 0x426c0000
	v_fma_f32 v94, v192, s6, v80
	v_fma_f32 v95, v193, s7, v80
	s_mov_b32 s6, 0x42600000
	s_mov_b32 s7, 0x42640000
	v_fma_f32 v92, v192, s6, v80
	v_fma_f32 v93, v193, s7, v80
	s_mov_b32 s6, 0x42480000
	ds_read_b128 v[96:99], v204 offset:9216
	ds_read_b128 v[100:103], v204 offset:9248
	s_mov_b32 s7, 0x424c0000
	v_fma_f32 v65, v203, v64, v192
	v_mov_b32_e32 v64, v80
	v_fma_f32 v90, v192, s6, v80
	v_fma_f32 v91, v193, s7, v80
	s_mov_b32 s6, 0x42400000
	v_fmac_f32_e32 v64, 0, v192
	s_mov_b32 s7, 0x42440000
	v_fma_f32 v88, v192, s6, v80
	v_fma_f32 v89, v193, s7, v80
	s_mov_b32 s6, 0x42280000
	s_waitcnt lgkmcnt(1)
	v_mfma_f32_32x32x16_bf16 v[64:79], v[96:99], v[144:147], v[64:79]
	ds_read_b128 v[96:99], v204 offset:13824
	s_mov_b32 s7, 0x422c0000
	v_fma_f32 v86, v192, s6, v80
	v_fma_f32 v87, v193, s7, v80
	s_mov_b32 s6, 0x42200000
	s_mov_b32 s7, 0x42240000
	v_fma_f32 v84, v192, s6, v80
	v_fma_f32 v85, v193, s7, v80
	s_mov_b32 s6, 0x42080000
	s_mov_b32 s7, 0x420c0000
	v_fma_f32 v82, v192, s6, v80
	v_fma_f32 v83, v193, s7, v80
	s_mov_b32 s6, 0x42000000
	s_mov_b32 s7, 0x42040000
	v_fma_f32 v81, v197, s7, v80
	v_fma_f32 v80, v196, s6, v80
	s_waitcnt lgkmcnt(1)
	v_mfma_f32_32x32x16_bf16 v[64:79], v[100:103], v[148:151], v[64:79]
	s_waitcnt lgkmcnt(0)
	v_mfma_f32_32x32x16_bf16 v[80:95], v[96:99], v[144:147], v[80:95]
	ds_read_b128 v[96:99], v204 offset:13856
	ds_read_b128 v[136:139], v204 offset:9280
	ds_read_b128 v[140:143], v204 offset:13888
	ds_read_b128 v[244:247], v204 offset:9312
	s_waitcnt lgkmcnt(3)
	v_mfma_f32_32x32x16_bf16 v[80:95], v[96:99], v[148:151], v[80:95]
	ds_read_b128 v[96:99], v204 offset:13920
	s_waitcnt lgkmcnt(3)
	v_mfma_f32_32x32x16_bf16 v[64:79], v[136:139], v[152:155], v[64:79]
	s_waitcnt lgkmcnt(2)
	v_mfma_f32_32x32x16_bf16 v[80:95], v[140:143], v[152:155], v[80:95]
	s_waitcnt lgkmcnt(1)
	v_mfma_f32_32x32x16_bf16 v[64:79], v[244:247], v[156:159], v[64:79]
	s_waitcnt lgkmcnt(0)
	v_mfma_f32_32x32x16_bf16 v[80:95], v[96:99], v[156:159], v[80:95]
.LBB0_215:
	s_cmp_gt_i32 s4, s26
	s_cbranch_scc1 .LBB0_227
	s_lshl_b32 s7, s4, 6
	s_or_b32 s6, s7, 63
	v_or_b32_e32 v96, s7, v200
	s_sub_i32 s8, s31, s6
	v_sub_u32_e32 v128, v199, v96
	s_cmpk_lt_i32 s8, 0x201
	s_mov_b64 s[4:5], -1
	s_cbranch_scc0 .LBB0_250
	s_sub_i32 s7, s31, s7
	s_cmpk_gt_i32 s8, 0x80
	s_cselect_b64 s[4:5], -1, 0
	s_cmpk_lt_i32 s7, 0x1e2
	s_cselect_b64 s[8:9], -1, 0
	s_and_b64 s[8:9], s[8:9], s[4:5]
	s_mov_b64 s[4:5], -1
	s_and_b64 vcc, exec, s[8:9]
	s_cbranch_vccnz .LBB0_219
	v_cmp_gt_i32_e32 vcc, s3, v128
	s_nop 1
	v_cndmask_b32_e64 v96, 0, 1.0, vcc
	v_cmp_gt_i32_e32 vcc, s33, v128
	s_and_b64 s[4:5], s[38:39], vcc
	v_cndmask_b32_e64 v97, 0, 1.0, s[4:5]
	v_add_f32_e32 v96, v96, v97
	v_add_u32_e32 v97, -1, v128
	v_cmp_gt_i32_e32 vcc, s3, v97
	v_add_f32_e32 v96, v207, v96
	v_log_f32_e32 v96, v96
	v_cndmask_b32_e64 v98, 0, 1.0, vcc
	v_cmp_gt_i32_e32 vcc, s33, v97
	s_and_b64 s[4:5], s[40:41], vcc
	v_cndmask_b32_e64 v97, 0, 1.0, s[4:5]
	v_add_f32_e32 v97, v98, v97
	v_add_u32_e32 v98, -2, v128
	v_cmp_gt_i32_e32 vcc, s3, v98
	v_add_f32_e32 v97, v208, v97
	v_log_f32_e32 v97, v97
	v_cndmask_b32_e64 v99, 0, 1.0, vcc
	v_cmp_gt_i32_e32 vcc, s33, v98
	s_and_b64 s[4:5], s[42:43], vcc
	v_cndmask_b32_e64 v98, 0, 1.0, s[4:5]
	v_add_f32_e32 v98, v99, v98
	v_add_u32_e32 v99, -3, v128
	v_cmp_gt_i32_e32 vcc, s3, v99
	v_add_f32_e32 v98, v209, v98
	v_log_f32_e32 v98, v98
	v_cndmask_b32_e64 v100, 0, 1.0, vcc
	v_cmp_gt_i32_e32 vcc, s33, v99
	s_and_b64 s[4:5], s[44:45], vcc
	v_cndmask_b32_e64 v99, 0, 1.0, s[4:5]
	v_add_f32_e32 v99, v100, v99
	v_add_u32_e32 v100, -8, v128
	v_cmp_gt_i32_e32 vcc, s3, v100
	v_add_f32_e32 v99, v210, v99
	v_log_f32_e32 v99, v99
	v_cndmask_b32_e64 v101, 0, 1.0, vcc
	v_cmp_gt_i32_e32 vcc, s33, v100
	s_and_b64 s[4:5], s[38:39], vcc
	v_cndmask_b32_e64 v100, 0, 1.0, s[4:5]
	v_add_f32_e32 v100, v101, v100
	v_add_u32_e32 v101, -9, v128
	v_cmp_gt_i32_e32 vcc, s3, v101
	v_add_f32_e32 v100, v211, v100
	v_log_f32_e32 v100, v100
	v_cndmask_b32_e64 v102, 0, 1.0, vcc
	v_cmp_gt_i32_e32 vcc, s33, v101
	s_and_b64 s[4:5], s[40:41], vcc
	v_cndmask_b32_e64 v101, 0, 1.0, s[4:5]
	v_add_f32_e32 v101, v102, v101
	v_add_u32_e32 v102, -10, v128
	v_cmp_gt_i32_e32 vcc, s3, v102
	v_add_f32_e32 v101, v212, v101
	v_log_f32_e32 v101, v101
	v_cndmask_b32_e64 v103, 0, 1.0, vcc
	v_cmp_gt_i32_e32 vcc, s33, v102
	s_and_b64 s[4:5], s[42:43], vcc
	v_cndmask_b32_e64 v102, 0, 1.0, s[4:5]
	v_add_f32_e32 v102, v103, v102
	v_add_u32_e32 v103, -11, v128
	v_cmp_gt_i32_e32 vcc, s3, v103
	v_add_f32_e32 v102, v213, v102
	v_log_f32_e32 v102, v102
	v_cndmask_b32_e64 v104, 0, 1.0, vcc
	v_cmp_gt_i32_e32 vcc, s33, v103
	s_and_b64 s[4:5], s[44:45], vcc
	v_cndmask_b32_e64 v103, 0, 1.0, s[4:5]
	v_add_f32_e32 v103, v104, v103
	v_add_u32_e32 v104, -16, v128
	v_cmp_gt_i32_e32 vcc, s3, v104
	v_add_f32_e32 v103, v214, v103
	v_log_f32_e32 v103, v103
	v_cndmask_b32_e64 v105, 0, 1.0, vcc
	v_cmp_gt_i32_e32 vcc, s33, v104
	s_and_b64 s[4:5], s[38:39], vcc
	v_cndmask_b32_e64 v104, 0, 1.0, s[4:5]
	v_add_f32_e32 v104, v105, v104
	v_subrev_u32_e32 v105, 17, v128
	v_cmp_gt_i32_e32 vcc, s3, v105
	v_add_f32_e32 v104, v207, v104
	v_log_f32_e32 v104, v104
	v_cndmask_b32_e64 v106, 0, 1.0, vcc
	v_cmp_gt_i32_e32 vcc, s33, v105
	s_and_b64 s[4:5], s[40:41], vcc
	v_cndmask_b32_e64 v105, 0, 1.0, s[4:5]
	v_add_f32_e32 v105, v106, v105
	v_subrev_u32_e32 v106, 18, v128
	v_cmp_gt_i32_e32 vcc, s3, v106
	v_add_f32_e32 v105, v208, v105
	v_log_f32_e32 v105, v105
	v_cndmask_b32_e64 v107, 0, 1.0, vcc
	v_cmp_gt_i32_e32 vcc, s33, v106
	s_and_b64 s[4:5], s[42:43], vcc
	v_cndmask_b32_e64 v106, 0, 1.0, s[4:5]
	v_add_f32_e32 v106, v107, v106
	v_subrev_u32_e32 v107, 19, v128
	v_cmp_gt_i32_e32 vcc, s3, v107
	v_add_f32_e32 v106, v209, v106
	v_log_f32_e32 v106, v106
	v_cndmask_b32_e64 v108, 0, 1.0, vcc
	v_cmp_gt_i32_e32 vcc, s33, v107
	s_and_b64 s[4:5], s[44:45], vcc
	v_cndmask_b32_e64 v107, 0, 1.0, s[4:5]
	v_add_f32_e32 v107, v108, v107
	v_subrev_u32_e32 v108, 24, v128
	v_cmp_gt_i32_e32 vcc, s3, v108
	v_add_f32_e32 v107, v210, v107
	v_log_f32_e32 v107, v107
	v_cndmask_b32_e64 v109, 0, 1.0, vcc
	v_cmp_gt_i32_e32 vcc, s33, v108
	s_and_b64 s[4:5], s[38:39], vcc
	v_cndmask_b32_e64 v108, 0, 1.0, s[4:5]
	v_add_f32_e32 v108, v109, v108
	v_subrev_u32_e32 v109, 25, v128
	v_cmp_gt_i32_e32 vcc, s3, v109
	v_add_f32_e32 v108, v211, v108
	v_log_f32_e32 v108, v108
	v_cndmask_b32_e64 v110, 0, 1.0, vcc
	v_cmp_gt_i32_e32 vcc, s33, v109
	s_and_b64 s[4:5], s[40:41], vcc
	v_cndmask_b32_e64 v109, 0, 1.0, s[4:5]
	v_add_f32_e32 v109, v110, v109
	v_subrev_u32_e32 v110, 26, v128
	v_cmp_gt_i32_e32 vcc, s3, v110
	v_add_f32_e32 v109, v212, v109
	v_log_f32_e32 v109, v109
	v_cndmask_b32_e64 v111, 0, 1.0, vcc
	v_cmp_gt_i32_e32 vcc, s33, v110
	s_and_b64 s[4:5], s[42:43], vcc
	v_cndmask_b32_e64 v110, 0, 1.0, s[4:5]
	v_add_f32_e32 v110, v111, v110
	v_subrev_u32_e32 v111, 27, v128
	v_cmp_gt_i32_e32 vcc, s3, v111
	v_add_f32_e32 v110, v213, v110
	v_log_f32_e32 v110, v110
	v_cndmask_b32_e64 v112, 0, 1.0, vcc
	v_cmp_gt_i32_e32 vcc, s33, v111
	s_and_b64 s[4:5], s[44:45], vcc
	v_cndmask_b32_e64 v111, 0, 1.0, s[4:5]
	v_add_f32_e32 v111, v112, v111
	v_subrev_u32_e32 v112, 32, v128
	v_cmp_gt_i32_e32 vcc, s3, v112
	v_add_f32_e32 v111, v214, v111
	v_log_f32_e32 v111, v111
	v_cndmask_b32_e64 v113, 0, 1.0, vcc
	v_cmp_gt_i32_e32 vcc, s33, v112
	s_and_b64 s[4:5], s[38:39], vcc
	v_cndmask_b32_e64 v112, 0, 1.0, s[4:5]
	v_add_f32_e32 v112, v113, v112
	v_subrev_u32_e32 v113, 33, v128
	v_cmp_gt_i32_e32 vcc, s3, v113
	v_add_f32_e32 v112, v207, v112
	v_log_f32_e32 v112, v112
	v_cndmask_b32_e64 v114, 0, 1.0, vcc
	v_cmp_gt_i32_e32 vcc, s33, v113
	s_and_b64 s[4:5], s[40:41], vcc
	v_cndmask_b32_e64 v113, 0, 1.0, s[4:5]
	v_add_f32_e32 v113, v114, v113
	v_subrev_u32_e32 v114, 34, v128
	v_cmp_gt_i32_e32 vcc, s3, v114
	v_add_f32_e32 v113, v208, v113
	v_log_f32_e32 v113, v113
	v_cndmask_b32_e64 v115, 0, 1.0, vcc
	v_cmp_gt_i32_e32 vcc, s33, v114
	s_and_b64 s[4:5], s[42:43], vcc
	v_cndmask_b32_e64 v114, 0, 1.0, s[4:5]
	v_add_f32_e32 v114, v115, v114
	v_subrev_u32_e32 v115, 35, v128
	v_cmp_gt_i32_e32 vcc, s3, v115
	v_add_f32_e32 v114, v209, v114
	v_log_f32_e32 v114, v114
	v_cndmask_b32_e64 v116, 0, 1.0, vcc
	v_cmp_gt_i32_e32 vcc, s33, v115
	s_and_b64 s[4:5], s[44:45], vcc
	v_cndmask_b32_e64 v115, 0, 1.0, s[4:5]
	v_add_f32_e32 v115, v116, v115
	v_subrev_u32_e32 v116, 40, v128
	v_cmp_gt_i32_e32 vcc, s3, v116
	v_add_f32_e32 v115, v210, v115
	v_log_f32_e32 v115, v115
	v_cndmask_b32_e64 v117, 0, 1.0, vcc
	v_cmp_gt_i32_e32 vcc, s33, v116
	s_and_b64 s[4:5], s[38:39], vcc
	v_cndmask_b32_e64 v116, 0, 1.0, s[4:5]
	v_add_f32_e32 v116, v117, v116
	v_subrev_u32_e32 v117, 41, v128
	v_cmp_gt_i32_e32 vcc, s3, v117
	v_add_f32_e32 v116, v211, v116
	v_log_f32_e32 v116, v116
	v_cndmask_b32_e64 v118, 0, 1.0, vcc
	v_cmp_gt_i32_e32 vcc, s33, v117
	s_and_b64 s[4:5], s[40:41], vcc
	v_cndmask_b32_e64 v117, 0, 1.0, s[4:5]
	v_add_f32_e32 v117, v118, v117
	v_subrev_u32_e32 v118, 42, v128
	v_cmp_gt_i32_e32 vcc, s3, v118
	v_add_f32_e32 v117, v212, v117
	v_log_f32_e32 v117, v117
	v_cndmask_b32_e64 v119, 0, 1.0, vcc
	v_cmp_gt_i32_e32 vcc, s33, v118
	s_and_b64 s[4:5], s[42:43], vcc
	v_cndmask_b32_e64 v118, 0, 1.0, s[4:5]
	v_add_f32_e32 v118, v119, v118
	v_subrev_u32_e32 v119, 43, v128
	v_cmp_gt_i32_e32 vcc, s3, v119
	v_add_f32_e32 v118, v213, v118
	v_log_f32_e32 v118, v118
	v_cndmask_b32_e64 v120, 0, 1.0, vcc
	v_cmp_gt_i32_e32 vcc, s33, v119
	s_and_b64 s[4:5], s[44:45], vcc
	v_cndmask_b32_e64 v119, 0, 1.0, s[4:5]
	v_add_f32_e32 v119, v120, v119
	v_subrev_u32_e32 v120, 48, v128
	v_cmp_gt_i32_e32 vcc, s3, v120
	v_add_f32_e32 v119, v214, v119
	v_log_f32_e32 v119, v119
	v_cndmask_b32_e64 v121, 0, 1.0, vcc
	v_cmp_gt_i32_e32 vcc, s33, v120
	s_and_b64 s[4:5], s[38:39], vcc
	v_cndmask_b32_e64 v120, 0, 1.0, s[4:5]
	v_add_f32_e32 v120, v121, v120
	v_subrev_u32_e32 v121, 49, v128
	v_cmp_gt_i32_e32 vcc, s3, v121
	v_add_f32_e32 v120, v207, v120
	v_log_f32_e32 v120, v120
	v_cndmask_b32_e64 v122, 0, 1.0, vcc
	v_cmp_gt_i32_e32 vcc, s33, v121
	s_and_b64 s[4:5], s[40:41], vcc
	v_cndmask_b32_e64 v121, 0, 1.0, s[4:5]
	v_add_f32_e32 v121, v122, v121
	v_subrev_u32_e32 v122, 50, v128
	v_cmp_gt_i32_e32 vcc, s3, v122
	v_add_f32_e32 v121, v208, v121
	v_log_f32_e32 v121, v121
	v_cndmask_b32_e64 v123, 0, 1.0, vcc
	v_cmp_gt_i32_e32 vcc, s33, v122
	s_and_b64 s[4:5], s[42:43], vcc
	v_cndmask_b32_e64 v122, 0, 1.0, s[4:5]
	v_add_f32_e32 v122, v123, v122
	v_subrev_u32_e32 v123, 51, v128
	v_cmp_gt_i32_e32 vcc, s3, v123
	v_add_f32_e32 v122, v209, v122
	v_log_f32_e32 v122, v122
	v_cndmask_b32_e64 v124, 0, 1.0, vcc
	v_cmp_gt_i32_e32 vcc, s33, v123
	s_and_b64 s[4:5], s[44:45], vcc
	v_cndmask_b32_e64 v123, 0, 1.0, s[4:5]
	v_add_f32_e32 v123, v124, v123
	v_subrev_u32_e32 v124, 56, v128
	v_cmp_gt_i32_e32 vcc, s3, v124
	v_add_f32_e32 v123, v210, v123
	v_log_f32_e32 v123, v123
	v_cndmask_b32_e64 v125, 0, 1.0, vcc
	v_cmp_gt_i32_e32 vcc, s33, v124
	s_and_b64 s[4:5], s[38:39], vcc
	v_cndmask_b32_e64 v124, 0, 1.0, s[4:5]
	v_add_f32_e32 v124, v125, v124
	v_subrev_u32_e32 v125, 57, v128
	v_cmp_gt_i32_e32 vcc, s3, v125
	v_add_f32_e32 v124, v211, v124
	v_log_f32_e32 v124, v124
	v_cndmask_b32_e64 v126, 0, 1.0, vcc
	v_cmp_gt_i32_e32 vcc, s33, v125
	s_and_b64 s[4:5], s[40:41], vcc
	v_cndmask_b32_e64 v125, 0, 1.0, s[4:5]
	v_add_f32_e32 v125, v126, v125
	v_subrev_u32_e32 v126, 58, v128
	v_cmp_gt_i32_e32 vcc, s3, v126
	v_add_f32_e32 v125, v212, v125
	v_log_f32_e32 v125, v125
	v_cndmask_b32_e64 v127, 0, 1.0, vcc
	v_cmp_gt_i32_e32 vcc, s33, v126
	s_and_b64 s[4:5], s[42:43], vcc
	v_cndmask_b32_e64 v126, 0, 1.0, s[4:5]
	v_add_f32_e32 v126, v127, v126
	v_subrev_u32_e32 v127, 59, v128
	v_cmp_gt_i32_e32 vcc, s3, v127
	v_add_f32_e32 v126, v213, v126
	v_log_f32_e32 v126, v126
	v_cndmask_b32_e64 v130, 0, 1.0, vcc
	v_cmp_gt_i32_e32 vcc, s33, v127
	s_and_b64 s[4:5], s[44:45], vcc
	v_cndmask_b32_e64 v127, 0, 1.0, s[4:5]
	v_add_f32_e32 v127, v130, v127
	v_add_f32_e32 v127, v214, v127
	v_log_f32_e32 v127, v127
	v_add_f32_e32 v110, v46, v110
	v_add_f32_e32 v111, v47, v111
	v_add_f32_e32 v108, v44, v108
	v_add_f32_e32 v109, v45, v109
	v_add_f32_e32 v106, v42, v106
	v_add_f32_e32 v107, v43, v107
	v_add_f32_e32 v104, v40, v104
	v_add_f32_e32 v105, v41, v105
	v_add_f32_e32 v102, v38, v102
	v_add_f32_e32 v103, v39, v103
	v_add_f32_e32 v100, v36, v100
	v_add_f32_e32 v101, v37, v101
	v_add_f32_e32 v98, v34, v98
	v_add_f32_e32 v99, v35, v99
	v_add_f32_e32 v96, v32, v96
	v_add_f32_e32 v97, v33, v97
	v_add_f32_e32 v126, v62, v126
	v_add_f32_e32 v127, v63, v127
	v_add_f32_e32 v124, v60, v124
	v_add_f32_e32 v125, v61, v125
	v_add_f32_e32 v122, v58, v122
	v_add_f32_e32 v123, v59, v123
	v_add_f32_e32 v120, v56, v120
	v_add_f32_e32 v121, v57, v121
	v_add_f32_e32 v118, v54, v118
	v_add_f32_e32 v119, v55, v119
	v_add_f32_e32 v116, v52, v116
	v_add_f32_e32 v117, v53, v117
	v_add_f32_e32 v114, v50, v114
	v_add_f32_e32 v115, v51, v115
	v_add_f32_e32 v112, v48, v112
	v_add_f32_e32 v113, v49, v113
	s_mov_b64 s[4:5], 0

.LBB0_224:
	v_max_f32_e32 v32, v97, v97
	v_max_f32_e32 v33, v96, v96
	v_max_f32_e32 v32, v33, v32
	v_max3_f32 v32, v32, v98, v99
	v_max3_f32 v32, v32, v100, v101
	v_max3_f32 v32, v32, v102, v103
	v_max3_f32 v32, v32, v104, v105
	v_max3_f32 v32, v32, v106, v107
	v_max3_f32 v32, v32, v108, v109
	v_max3_f32 v32, v32, v110, v111
	v_max3_f32 v32, v32, v112, v113
	v_max3_f32 v32, v32, v114, v115
	v_max3_f32 v32, v32, v116, v117
	v_max3_f32 v32, v32, v118, v119
	v_max3_f32 v32, v32, v120, v121
	v_max3_f32 v32, v32, v122, v123
	v_max3_f32 v32, v32, v124, v125
	v_max3_f32 v32, v32, v126, v127
	v_mov_b32_e32 v33, v32
	v_mov_b32_e32 v34, v32
	s_nop 1
	v_permlane32_swap_b32_e32 v33, v34
	v_cndmask_b32_e64 v33, v33, v34, s[58:59]
	v_max3_f32 v130, v216, v32, v33
	v_cmp_neq_f32_e32 vcc, s2, v130
	s_nop 1
	v_cndmask_b32_e32 v63, 0, v130, vcc
	v_sub_f32_e32 v32, v216, v63
	v_exp_f32_e32 v128, v32
	s_nop 0
	v_cmp_eq_f32_e32 vcc, 1.0, v128
	s_cmp_eq_u64 vcc, exec
	s_cbranch_scc1 .LBB0_226
	v_mul_f32_e32 v30, v30, v128
	v_mul_f32_e32 v31, v31, v128
	v_mul_f32_e32 v28, v28, v128
	v_mul_f32_e32 v29, v29, v128
	v_mul_f32_e32 v26, v26, v128
	v_mul_f32_e32 v27, v27, v128
	v_mul_f32_e32 v24, v24, v128
	v_mul_f32_e32 v25, v25, v128
	v_mul_f32_e32 v22, v22, v128
	v_mul_f32_e32 v23, v23, v128
	v_mul_f32_e32 v20, v20, v128
	v_mul_f32_e32 v21, v21, v128
	v_mul_f32_e32 v18, v18, v128
	v_mul_f32_e32 v19, v19, v128
	v_mul_f32_e32 v16, v16, v128
	v_mul_f32_e32 v17, v17, v128
	v_mul_f32_e32 v14, v14, v128
	v_mul_f32_e32 v15, v15, v128
	v_mul_f32_e32 v12, v12, v128
	v_mul_f32_e32 v13, v13, v128
	v_mul_f32_e32 v10, v10, v128
	v_mul_f32_e32 v11, v11, v128
	v_mul_f32_e32 v8, v8, v128
	v_mul_f32_e32 v9, v9, v128
	v_mul_f32_e32 v6, v6, v128
	v_mul_f32_e32 v7, v7, v128
	v_mul_f32_e32 v4, v4, v128
	v_mul_f32_e32 v5, v5, v128
	v_mul_f32_e32 v2, v2, v128
	v_mul_f32_e32 v3, v3, v128
	v_mul_f32_e32 v0, v0, v128
	v_mul_f32_e32 v1, v1, v128

.LBB0_236:
	s_add_i32 s5, s4, -1
	s_cmp_gt_i32 s5, s26
	s_cbranch_scc1 .LBB0_238
	v_lshl_or_b32 v32, s5, 6, v200
	v_sub_u32_e32 v32, v199, v32
	v_cvt_f32_i32_e32 v32, v32
	s_mov_b32 s6, 2.0
	s_mov_b32 s7, 0x40400000
	v_mov_b32_e32 v193, v192
	v_mul_f32_e32 v48, v203, v32
	v_fma_f32 v34, v194, s6, v48
	v_fma_f32 v35, v195, s7, v48
	s_mov_b32 s6, 0x41000000
	s_mov_b32 s7, 0x41100000
	v_fma_f32 v36, v194, s6, v48
	v_fma_f32 v37, v195, s7, v48
	s_mov_b32 s6, 0x41200000
	s_mov_b32 s7, 0x41300000
	v_fma_f32 v38, v194, s6, v48
	v_fma_f32 v39, v195, s7, v48
	s_mov_b32 s6, 0x41800000
	s_mov_b32 s7, 0x41880000
	v_fma_f32 v40, v194, s6, v48
	v_fma_f32 v41, v195, s7, v48
	s_mov_b32 s6, 0x41900000
	s_mov_b32 s7, 0x41980000
	v_fma_f32 v42, v194, s6, v48
	v_fma_f32 v43, v195, s7, v48
	s_mov_b32 s6, 0x41c00000
	s_mov_b32 s7, 0x41c80000
	v_fma_f32 v44, v194, s6, v48
	v_fma_f32 v45, v195, s7, v48
	s_mov_b32 s6, 0x41d00000
	s_mov_b32 s7, 0x41d80000
	v_fma_f32 v46, v194, s6, v48
	v_fma_f32 v47, v195, s7, v48
	s_mov_b32 s6, 0x42680000
	s_mov_b32 s7, 0x426c0000
	v_fma_f32 v62, v192, s6, v48
	v_fma_f32 v63, v193, s7, v48
	s_mov_b32 s6, 0x42600000
	s_mov_b32 s7, 0x42640000
	v_fma_f32 v60, v192, s6, v48
	v_fma_f32 v61, v193, s7, v48
	s_mov_b32 s6, 0x42480000
	ds_read_b128 v[96:99], v204
	ds_read_b128 v[100:103], v204 offset:32
	s_mov_b32 s7, 0x424c0000
	v_fma_f32 v33, v203, v32, v192
	v_mov_b32_e32 v32, v48
	v_fma_f32 v58, v192, s6, v48
	v_fma_f32 v59, v193, s7, v48
	s_mov_b32 s6, 0x42400000
	v_fmac_f32_e32 v32, 0, v192
	s_mov_b32 s7, 0x42440000
	v_fma_f32 v56, v192, s6, v48
	v_fma_f32 v57, v193, s7, v48
	s_mov_b32 s6, 0x42280000
	s_waitcnt lgkmcnt(1)
	v_mfma_f32_32x32x16_bf16 v[32:47], v[96:99], v[144:147], v[32:47]
	ds_read_b128 v[96:99], v204 offset:4608
	s_mov_b32 s7, 0x422c0000
	v_fma_f32 v54, v192, s6, v48
	v_fma_f32 v55, v193, s7, v48
	s_mov_b32 s6, 0x42200000
	s_mov_b32 s7, 0x42240000
	v_fma_f32 v52, v192, s6, v48
	v_fma_f32 v53, v193, s7, v48
	s_mov_b32 s6, 0x42080000
	s_mov_b32 s7, 0x420c0000
	v_fma_f32 v50, v192, s6, v48
	v_fma_f32 v51, v193, s7, v48
	s_mov_b32 s6, 0x42000000
	s_mov_b32 s7, 0x42040000
	v_fma_f32 v49, v197, s7, v48
	v_fma_f32 v48, v196, s6, v48
	s_waitcnt lgkmcnt(1)
	v_mfma_f32_32x32x16_bf16 v[32:47], v[100:103], v[148:151], v[32:47]
	s_waitcnt lgkmcnt(0)
	v_mfma_f32_32x32x16_bf16 v[48:63], v[96:99], v[144:147], v[48:63]
	ds_read_b128 v[96:99], v204 offset:4640
	ds_read_b128 v[136:139], v204 offset:64
	ds_read_b128 v[140:143], v204 offset:4672
	ds_read_b128 v[244:247], v204 offset:96
	s_waitcnt lgkmcnt(3)
	v_mfma_f32_32x32x16_bf16 v[48:63], v[96:99], v[148:151], v[48:63]
	ds_read_b128 v[96:99], v204 offset:4704
	s_waitcnt lgkmcnt(3)
	v_mfma_f32_32x32x16_bf16 v[32:47], v[136:139], v[152:155], v[32:47]
	s_waitcnt lgkmcnt(2)
	v_mfma_f32_32x32x16_bf16 v[48:63], v[140:143], v[152:155], v[48:63]
	s_waitcnt lgkmcnt(1)
	v_mfma_f32_32x32x16_bf16 v[32:47], v[244:247], v[156:159], v[32:47]
	s_waitcnt lgkmcnt(0)
	v_mfma_f32_32x32x16_bf16 v[48:63], v[96:99], v[156:159], v[48:63]
.LBB0_238:
	s_cmp_gt_i32 s4, s26
	s_cbranch_scc1 .LBB0_252
	s_lshl_b32 s7, s4, 6
	s_or_b32 s6, s7, 63
	v_or_b32_e32 v96, s7, v200
	s_sub_i32 s8, s31, s6
	v_sub_u32_e32 v128, v199, v96
	s_cmpk_lt_i32 s8, 0x201
	s_mov_b64 s[4:5], -1
	s_cbranch_scc0 .LBB0_275
	s_sub_i32 s7, s31, s7
	s_cmpk_gt_i32 s8, 0x80
	s_cselect_b64 s[4:5], -1, 0
	s_cmpk_lt_i32 s7, 0x1e2
	s_cselect_b64 s[8:9], -1, 0
	s_and_b64 s[8:9], s[8:9], s[4:5]
	s_mov_b64 s[4:5], -1
	s_and_b64 vcc, exec, s[8:9]
	s_cbranch_vccnz .LBB0_242
	v_cmp_gt_i32_e32 vcc, s3, v128
	s_nop 1
	v_cndmask_b32_e64 v96, 0, 1.0, vcc
	v_cmp_gt_i32_e32 vcc, s33, v128
	s_and_b64 s[4:5], s[38:39], vcc
	v_cndmask_b32_e64 v97, 0, 1.0, s[4:5]
	v_add_f32_e32 v96, v96, v97
	v_add_u32_e32 v97, -1, v128
	v_cmp_gt_i32_e32 vcc, s3, v97
	v_add_f32_e32 v96, v207, v96
	v_log_f32_e32 v96, v96
	v_cndmask_b32_e64 v98, 0, 1.0, vcc
	v_cmp_gt_i32_e32 vcc, s33, v97
	s_and_b64 s[4:5], s[40:41], vcc
	v_cndmask_b32_e64 v97, 0, 1.0, s[4:5]
	v_add_f32_e32 v97, v98, v97
	v_add_u32_e32 v98, -2, v128
	v_cmp_gt_i32_e32 vcc, s3, v98
	v_add_f32_e32 v97, v208, v97
	v_log_f32_e32 v97, v97
	v_cndmask_b32_e64 v99, 0, 1.0, vcc
	v_cmp_gt_i32_e32 vcc, s33, v98
	s_and_b64 s[4:5], s[42:43], vcc
	v_cndmask_b32_e64 v98, 0, 1.0, s[4:5]
	v_add_f32_e32 v98, v99, v98
	v_add_u32_e32 v99, -3, v128
	v_cmp_gt_i32_e32 vcc, s3, v99
	v_add_f32_e32 v98, v209, v98
	v_log_f32_e32 v98, v98
	v_cndmask_b32_e64 v100, 0, 1.0, vcc
	v_cmp_gt_i32_e32 vcc, s33, v99
	s_and_b64 s[4:5], s[44:45], vcc
	v_cndmask_b32_e64 v99, 0, 1.0, s[4:5]
	v_add_f32_e32 v99, v100, v99
	v_add_u32_e32 v100, -8, v128
	v_cmp_gt_i32_e32 vcc, s3, v100
	v_add_f32_e32 v99, v210, v99
	v_log_f32_e32 v99, v99
	v_cndmask_b32_e64 v101, 0, 1.0, vcc
	v_cmp_gt_i32_e32 vcc, s33, v100
	s_and_b64 s[4:5], s[38:39], vcc
	v_cndmask_b32_e64 v100, 0, 1.0, s[4:5]
	v_add_f32_e32 v100, v101, v100
	v_add_u32_e32 v101, -9, v128
	v_cmp_gt_i32_e32 vcc, s3, v101
	v_add_f32_e32 v100, v211, v100
	v_log_f32_e32 v100, v100
	v_cndmask_b32_e64 v102, 0, 1.0, vcc
	v_cmp_gt_i32_e32 vcc, s33, v101
	s_and_b64 s[4:5], s[40:41], vcc
	v_cndmask_b32_e64 v101, 0, 1.0, s[4:5]
	v_add_f32_e32 v101, v102, v101
	v_add_u32_e32 v102, -10, v128
	v_cmp_gt_i32_e32 vcc, s3, v102
	v_add_f32_e32 v101, v212, v101
	v_log_f32_e32 v101, v101
	v_cndmask_b32_e64 v103, 0, 1.0, vcc
	v_cmp_gt_i32_e32 vcc, s33, v102
	s_and_b64 s[4:5], s[42:43], vcc
	v_cndmask_b32_e64 v102, 0, 1.0, s[4:5]
	v_add_f32_e32 v102, v103, v102
	v_add_u32_e32 v103, -11, v128
	v_cmp_gt_i32_e32 vcc, s3, v103
	v_add_f32_e32 v102, v213, v102
	v_log_f32_e32 v102, v102
	v_cndmask_b32_e64 v104, 0, 1.0, vcc
	v_cmp_gt_i32_e32 vcc, s33, v103
	s_and_b64 s[4:5], s[44:45], vcc
	v_cndmask_b32_e64 v103, 0, 1.0, s[4:5]
	v_add_f32_e32 v103, v104, v103
	v_add_u32_e32 v104, -16, v128
	v_cmp_gt_i32_e32 vcc, s3, v104
	v_add_f32_e32 v103, v214, v103
	v_log_f32_e32 v103, v103
	v_cndmask_b32_e64 v105, 0, 1.0, vcc
	v_cmp_gt_i32_e32 vcc, s33, v104
	s_and_b64 s[4:5], s[38:39], vcc
	v_cndmask_b32_e64 v104, 0, 1.0, s[4:5]
	v_add_f32_e32 v104, v105, v104
	v_subrev_u32_e32 v105, 17, v128
	v_cmp_gt_i32_e32 vcc, s3, v105
	v_add_f32_e32 v104, v207, v104
	v_log_f32_e32 v104, v104
	v_cndmask_b32_e64 v106, 0, 1.0, vcc
	v_cmp_gt_i32_e32 vcc, s33, v105
	s_and_b64 s[4:5], s[40:41], vcc
	v_cndmask_b32_e64 v105, 0, 1.0, s[4:5]
	v_add_f32_e32 v105, v106, v105
	v_subrev_u32_e32 v106, 18, v128
	v_cmp_gt_i32_e32 vcc, s3, v106
	v_add_f32_e32 v105, v208, v105
	v_log_f32_e32 v105, v105
	v_cndmask_b32_e64 v107, 0, 1.0, vcc
	v_cmp_gt_i32_e32 vcc, s33, v106
	s_and_b64 s[4:5], s[42:43], vcc
	v_cndmask_b32_e64 v106, 0, 1.0, s[4:5]
	v_add_f32_e32 v106, v107, v106
	v_subrev_u32_e32 v107, 19, v128
	v_cmp_gt_i32_e32 vcc, s3, v107
	v_add_f32_e32 v106, v209, v106
	v_log_f32_e32 v106, v106
	v_cndmask_b32_e64 v108, 0, 1.0, vcc
	v_cmp_gt_i32_e32 vcc, s33, v107
	s_and_b64 s[4:5], s[44:45], vcc
	v_cndmask_b32_e64 v107, 0, 1.0, s[4:5]
	v_add_f32_e32 v107, v108, v107
	v_subrev_u32_e32 v108, 24, v128
	v_cmp_gt_i32_e32 vcc, s3, v108
	v_add_f32_e32 v107, v210, v107
	v_log_f32_e32 v107, v107
	v_cndmask_b32_e64 v109, 0, 1.0, vcc
	v_cmp_gt_i32_e32 vcc, s33, v108
	s_and_b64 s[4:5], s[38:39], vcc
	v_cndmask_b32_e64 v108, 0, 1.0, s[4:5]
	v_add_f32_e32 v108, v109, v108
	v_subrev_u32_e32 v109, 25, v128
	v_cmp_gt_i32_e32 vcc, s3, v109
	v_add_f32_e32 v108, v211, v108
	v_log_f32_e32 v108, v108
	v_cndmask_b32_e64 v110, 0, 1.0, vcc
	v_cmp_gt_i32_e32 vcc, s33, v109
	s_and_b64 s[4:5], s[40:41], vcc
	v_cndmask_b32_e64 v109, 0, 1.0, s[4:5]
	v_add_f32_e32 v109, v110, v109
	v_subrev_u32_e32 v110, 26, v128
	v_cmp_gt_i32_e32 vcc, s3, v110
	v_add_f32_e32 v109, v212, v109
	v_log_f32_e32 v109, v109
	v_cndmask_b32_e64 v111, 0, 1.0, vcc
	v_cmp_gt_i32_e32 vcc, s33, v110
	s_and_b64 s[4:5], s[42:43], vcc
	v_cndmask_b32_e64 v110, 0, 1.0, s[4:5]
	v_add_f32_e32 v110, v111, v110
	v_subrev_u32_e32 v111, 27, v128
	v_cmp_gt_i32_e32 vcc, s3, v111
	v_add_f32_e32 v110, v213, v110
	v_log_f32_e32 v110, v110
	v_cndmask_b32_e64 v112, 0, 1.0, vcc
	v_cmp_gt_i32_e32 vcc, s33, v111
	s_and_b64 s[4:5], s[44:45], vcc
	v_cndmask_b32_e64 v111, 0, 1.0, s[4:5]
	v_add_f32_e32 v111, v112, v111
	v_subrev_u32_e32 v112, 32, v128
	v_cmp_gt_i32_e32 vcc, s3, v112
	v_add_f32_e32 v111, v214, v111
	v_log_f32_e32 v111, v111
	v_cndmask_b32_e64 v113, 0, 1.0, vcc
	v_cmp_gt_i32_e32 vcc, s33, v112
	s_and_b64 s[4:5], s[38:39], vcc
	v_cndmask_b32_e64 v112, 0, 1.0, s[4:5]
	v_add_f32_e32 v112, v113, v112
	v_subrev_u32_e32 v113, 33, v128
	v_cmp_gt_i32_e32 vcc, s3, v113
	v_add_f32_e32 v112, v207, v112
	v_log_f32_e32 v112, v112
	v_cndmask_b32_e64 v114, 0, 1.0, vcc
	v_cmp_gt_i32_e32 vcc, s33, v113
	s_and_b64 s[4:5], s[40:41], vcc
	v_cndmask_b32_e64 v113, 0, 1.0, s[4:5]
	v_add_f32_e32 v113, v114, v113
	v_subrev_u32_e32 v114, 34, v128
	v_cmp_gt_i32_e32 vcc, s3, v114
	v_add_f32_e32 v113, v208, v113
	v_log_f32_e32 v113, v113
	v_cndmask_b32_e64 v115, 0, 1.0, vcc
	v_cmp_gt_i32_e32 vcc, s33, v114
	s_and_b64 s[4:5], s[42:43], vcc
	v_cndmask_b32_e64 v114, 0, 1.0, s[4:5]
	v_add_f32_e32 v114, v115, v114
	v_subrev_u32_e32 v115, 35, v128
	v_cmp_gt_i32_e32 vcc, s3, v115
	v_add_f32_e32 v114, v209, v114
	v_log_f32_e32 v114, v114
	v_cndmask_b32_e64 v116, 0, 1.0, vcc
	v_cmp_gt_i32_e32 vcc, s33, v115
	s_and_b64 s[4:5], s[44:45], vcc
	v_cndmask_b32_e64 v115, 0, 1.0, s[4:5]
	v_add_f32_e32 v115, v116, v115
	v_subrev_u32_e32 v116, 40, v128
	v_cmp_gt_i32_e32 vcc, s3, v116
	v_add_f32_e32 v115, v210, v115
	v_log_f32_e32 v115, v115
	v_cndmask_b32_e64 v117, 0, 1.0, vcc
	v_cmp_gt_i32_e32 vcc, s33, v116
	s_and_b64 s[4:5], s[38:39], vcc
	v_cndmask_b32_e64 v116, 0, 1.0, s[4:5]
	v_add_f32_e32 v116, v117, v116
	v_subrev_u32_e32 v117, 41, v128
	v_cmp_gt_i32_e32 vcc, s3, v117
	v_add_f32_e32 v116, v211, v116
	v_log_f32_e32 v116, v116
	v_cndmask_b32_e64 v118, 0, 1.0, vcc
	v_cmp_gt_i32_e32 vcc, s33, v117
	s_and_b64 s[4:5], s[40:41], vcc
	v_cndmask_b32_e64 v117, 0, 1.0, s[4:5]
	v_add_f32_e32 v117, v118, v117
	v_subrev_u32_e32 v118, 42, v128
	v_cmp_gt_i32_e32 vcc, s3, v118
	v_add_f32_e32 v117, v212, v117
	v_log_f32_e32 v117, v117
	v_cndmask_b32_e64 v119, 0, 1.0, vcc
	v_cmp_gt_i32_e32 vcc, s33, v118
	s_and_b64 s[4:5], s[42:43], vcc
	v_cndmask_b32_e64 v118, 0, 1.0, s[4:5]
	v_add_f32_e32 v118, v119, v118
	v_subrev_u32_e32 v119, 43, v128
	v_cmp_gt_i32_e32 vcc, s3, v119
	v_add_f32_e32 v118, v213, v118
	v_log_f32_e32 v118, v118
	v_cndmask_b32_e64 v120, 0, 1.0, vcc
	v_cmp_gt_i32_e32 vcc, s33, v119
	s_and_b64 s[4:5], s[44:45], vcc
	v_cndmask_b32_e64 v119, 0, 1.0, s[4:5]
	v_add_f32_e32 v119, v120, v119
	v_subrev_u32_e32 v120, 48, v128
	v_cmp_gt_i32_e32 vcc, s3, v120
	v_add_f32_e32 v119, v214, v119
	v_log_f32_e32 v119, v119
	v_cndmask_b32_e64 v121, 0, 1.0, vcc
	v_cmp_gt_i32_e32 vcc, s33, v120
	s_and_b64 s[4:5], s[38:39], vcc
	v_cndmask_b32_e64 v120, 0, 1.0, s[4:5]
	v_add_f32_e32 v120, v121, v120
	v_subrev_u32_e32 v121, 49, v128
	v_cmp_gt_i32_e32 vcc, s3, v121
	v_add_f32_e32 v120, v207, v120
	v_log_f32_e32 v120, v120
	v_cndmask_b32_e64 v122, 0, 1.0, vcc
	v_cmp_gt_i32_e32 vcc, s33, v121
	s_and_b64 s[4:5], s[40:41], vcc
	v_cndmask_b32_e64 v121, 0, 1.0, s[4:5]
	v_add_f32_e32 v121, v122, v121
	v_subrev_u32_e32 v122, 50, v128
	v_cmp_gt_i32_e32 vcc, s3, v122
	v_add_f32_e32 v121, v208, v121
	v_log_f32_e32 v121, v121
	v_cndmask_b32_e64 v123, 0, 1.0, vcc
	v_cmp_gt_i32_e32 vcc, s33, v122
	s_and_b64 s[4:5], s[42:43], vcc
	v_cndmask_b32_e64 v122, 0, 1.0, s[4:5]
	v_add_f32_e32 v122, v123, v122
	v_subrev_u32_e32 v123, 51, v128
	v_cmp_gt_i32_e32 vcc, s3, v123
	v_add_f32_e32 v122, v209, v122
	v_log_f32_e32 v122, v122
	v_cndmask_b32_e64 v124, 0, 1.0, vcc
	v_cmp_gt_i32_e32 vcc, s33, v123
	s_and_b64 s[4:5], s[44:45], vcc
	v_cndmask_b32_e64 v123, 0, 1.0, s[4:5]
	v_add_f32_e32 v123, v124, v123
	v_subrev_u32_e32 v124, 56, v128
	v_cmp_gt_i32_e32 vcc, s3, v124
	v_add_f32_e32 v123, v210, v123
	v_log_f32_e32 v123, v123
	v_cndmask_b32_e64 v125, 0, 1.0, vcc
	v_cmp_gt_i32_e32 vcc, s33, v124
	s_and_b64 s[4:5], s[38:39], vcc
	v_cndmask_b32_e64 v124, 0, 1.0, s[4:5]
	v_add_f32_e32 v124, v125, v124
	v_subrev_u32_e32 v125, 57, v128
	v_cmp_gt_i32_e32 vcc, s3, v125
	v_add_f32_e32 v124, v211, v124
	v_log_f32_e32 v124, v124
	v_cndmask_b32_e64 v126, 0, 1.0, vcc
	v_cmp_gt_i32_e32 vcc, s33, v125
	s_and_b64 s[4:5], s[40:41], vcc
	v_cndmask_b32_e64 v125, 0, 1.0, s[4:5]
	v_add_f32_e32 v125, v126, v125
	v_subrev_u32_e32 v126, 58, v128
	v_cmp_gt_i32_e32 vcc, s3, v126
	v_add_f32_e32 v125, v212, v125
	v_log_f32_e32 v125, v125
	v_cndmask_b32_e64 v127, 0, 1.0, vcc
	v_cmp_gt_i32_e32 vcc, s33, v126
	s_and_b64 s[4:5], s[42:43], vcc
	v_cndmask_b32_e64 v126, 0, 1.0, s[4:5]
	v_add_f32_e32 v126, v127, v126
	v_subrev_u32_e32 v127, 59, v128
	v_cmp_gt_i32_e32 vcc, s3, v127
	v_add_f32_e32 v126, v213, v126
	v_log_f32_e32 v126, v126
	v_cndmask_b32_e64 v131, 0, 1.0, vcc
	v_cmp_gt_i32_e32 vcc, s33, v127
	s_and_b64 s[4:5], s[44:45], vcc
	v_cndmask_b32_e64 v127, 0, 1.0, s[4:5]
	v_add_f32_e32 v127, v131, v127
	v_add_f32_e32 v127, v214, v127
	v_log_f32_e32 v127, v127
	v_add_f32_e32 v110, v110, v78
	v_add_f32_e32 v111, v111, v79
	v_add_f32_e32 v108, v108, v76
	v_add_f32_e32 v109, v109, v77
	v_add_f32_e32 v106, v106, v74
	v_add_f32_e32 v107, v107, v75
	v_add_f32_e32 v104, v104, v72
	v_add_f32_e32 v105, v105, v73
	v_add_f32_e32 v102, v102, v70
	v_add_f32_e32 v103, v103, v71
	v_add_f32_e32 v100, v100, v68
	v_add_f32_e32 v101, v101, v69
	v_add_f32_e32 v98, v98, v66
	v_add_f32_e32 v99, v99, v67
	v_add_f32_e32 v96, v96, v64
	v_add_f32_e32 v97, v97, v65
	v_add_f32_e32 v126, v126, v94
	v_add_f32_e32 v127, v127, v95
	v_add_f32_e32 v124, v124, v92
	v_add_f32_e32 v125, v125, v93
	v_add_f32_e32 v122, v122, v90
	v_add_f32_e32 v123, v123, v91
	v_add_f32_e32 v120, v120, v88
	v_add_f32_e32 v121, v121, v89
	v_add_f32_e32 v118, v118, v86
	v_add_f32_e32 v119, v119, v87
	v_add_f32_e32 v116, v116, v84
	v_add_f32_e32 v117, v117, v85
	v_add_f32_e32 v114, v114, v82
	v_add_f32_e32 v115, v115, v83
	v_add_f32_e32 v112, v112, v80
	v_add_f32_e32 v113, v113, v81
	s_mov_b64 s[4:5], 0

.LBB0_247:
	v_max_f32_e32 v64, v97, v97
	v_max_f32_e32 v65, v96, v96
	v_max_f32_e32 v64, v65, v64
	v_max3_f32 v64, v64, v98, v99
	v_max3_f32 v64, v64, v100, v101
	v_max3_f32 v64, v64, v102, v103
	v_max3_f32 v64, v64, v104, v105
	v_max3_f32 v64, v64, v106, v107
	v_max3_f32 v64, v64, v108, v109
	v_max3_f32 v64, v64, v110, v111
	v_max3_f32 v64, v64, v112, v113
	v_max3_f32 v64, v64, v114, v115
	v_max3_f32 v64, v64, v116, v117
	v_max3_f32 v64, v64, v118, v119
	v_max3_f32 v64, v64, v120, v121
	v_max3_f32 v64, v64, v122, v123
	v_max3_f32 v64, v64, v124, v125
	v_max3_f32 v64, v64, v126, v127
	v_mov_b32_e32 v65, v64
	v_mov_b32_e32 v66, v64
	s_nop 1
	v_permlane32_swap_b32_e32 v65, v66
	v_cndmask_b32_e64 v65, v65, v66, s[58:59]
	v_max3_f32 v131, v130, v64, v65
	v_cmp_neq_f32_e32 vcc, s2, v131
	s_nop 1
	v_cndmask_b32_e32 v95, 0, v131, vcc
	v_sub_f32_e32 v64, v130, v95
	v_exp_f32_e32 v128, v64
	s_nop 0
	v_cmp_eq_f32_e32 vcc, 1.0, v128
	s_cmp_eq_u64 vcc, exec
	s_cbranch_scc1 .LBB0_249
	v_mul_f32_e32 v30, v30, v128
	v_mul_f32_e32 v31, v31, v128
	v_mul_f32_e32 v28, v28, v128
	v_mul_f32_e32 v29, v29, v128
	v_mul_f32_e32 v26, v26, v128
	v_mul_f32_e32 v27, v27, v128
	v_mul_f32_e32 v24, v24, v128
	v_mul_f32_e32 v25, v25, v128
	v_mul_f32_e32 v22, v22, v128
	v_mul_f32_e32 v23, v23, v128
	v_mul_f32_e32 v20, v20, v128
	v_mul_f32_e32 v21, v21, v128
	v_mul_f32_e32 v18, v18, v128
	v_mul_f32_e32 v19, v19, v128
	v_mul_f32_e32 v16, v16, v128
	v_mul_f32_e32 v17, v17, v128
	v_mul_f32_e32 v14, v14, v128
	v_mul_f32_e32 v15, v15, v128
	v_mul_f32_e32 v12, v12, v128
	v_mul_f32_e32 v13, v13, v128
	v_mul_f32_e32 v10, v10, v128
	v_mul_f32_e32 v11, v11, v128
	v_mul_f32_e32 v8, v8, v128
	v_mul_f32_e32 v9, v9, v128
	v_mul_f32_e32 v6, v6, v128
	v_mul_f32_e32 v7, v7, v128
	v_mul_f32_e32 v4, v4, v128
	v_mul_f32_e32 v5, v5, v128
	v_mul_f32_e32 v2, v2, v128
	v_mul_f32_e32 v3, v3, v128
	v_mul_f32_e32 v0, v0, v128
	v_mul_f32_e32 v1, v1, v128

.LBB0_261:
	s_add_i32 s5, s4, -1
	s_cmp_gt_i32 s5, s26
	s_cbranch_scc1 .LBB0_263
	v_lshl_or_b32 v64, s5, 6, v200
	v_sub_u32_e32 v64, v199, v64
	v_cvt_f32_i32_e32 v64, v64
	s_mov_b32 s6, 2.0
	s_mov_b32 s7, 0x40400000
	v_mov_b32_e32 v193, v192
	v_mul_f32_e32 v80, v203, v64
	v_fma_f32 v66, v194, s6, v80
	v_fma_f32 v67, v195, s7, v80
	s_mov_b32 s6, 0x41000000
	s_mov_b32 s7, 0x41100000
	v_fma_f32 v68, v194, s6, v80
	v_fma_f32 v69, v195, s7, v80
	s_mov_b32 s6, 0x41200000
	s_mov_b32 s7, 0x41300000
	v_fma_f32 v70, v194, s6, v80
	v_fma_f32 v71, v195, s7, v80
	s_mov_b32 s6, 0x41800000
	s_mov_b32 s7, 0x41880000
	v_fma_f32 v72, v194, s6, v80
	v_fma_f32 v73, v195, s7, v80
	s_mov_b32 s6, 0x41900000
	s_mov_b32 s7, 0x41980000
	v_fma_f32 v74, v194, s6, v80
	v_fma_f32 v75, v195, s7, v80
	s_mov_b32 s6, 0x41c00000
	s_mov_b32 s7, 0x41c80000
	v_fma_f32 v76, v194, s6, v80
	v_fma_f32 v77, v195, s7, v80
	s_mov_b32 s6, 0x41d00000
	s_mov_b32 s7, 0x41d80000
	v_fma_f32 v78, v194, s6, v80
	v_fma_f32 v79, v195, s7, v80
	s_mov_b32 s6, 0x42680000
	s_mov_b32 s7, 0x426c0000
	v_fma_f32 v94, v192, s6, v80
	v_fma_f32 v95, v193, s7, v80
	s_mov_b32 s6, 0x42600000
	s_mov_b32 s7, 0x42640000
	v_fma_f32 v92, v192, s6, v80
	v_fma_f32 v93, v193, s7, v80
	s_mov_b32 s6, 0x42480000
	ds_read_b128 v[96:99], v204 offset:9216
	ds_read_b128 v[100:103], v204 offset:9248
	s_mov_b32 s7, 0x424c0000
	v_fma_f32 v65, v203, v64, v192
	v_mov_b32_e32 v64, v80
	v_fma_f32 v90, v192, s6, v80
	v_fma_f32 v91, v193, s7, v80
	s_mov_b32 s6, 0x42400000
	v_fmac_f32_e32 v64, 0, v192
	s_mov_b32 s7, 0x42440000
	v_fma_f32 v88, v192, s6, v80
	v_fma_f32 v89, v193, s7, v80
	s_mov_b32 s6, 0x42280000
	s_waitcnt lgkmcnt(1)
	v_mfma_f32_32x32x16_bf16 v[64:79], v[96:99], v[144:147], v[64:79]
	ds_read_b128 v[96:99], v204 offset:13824
	s_mov_b32 s7, 0x422c0000
	v_fma_f32 v86, v192, s6, v80
	v_fma_f32 v87, v193, s7, v80
	s_mov_b32 s6, 0x42200000
	s_mov_b32 s7, 0x42240000
	v_fma_f32 v84, v192, s6, v80
	v_fma_f32 v85, v193, s7, v80
	s_mov_b32 s6, 0x42080000
	s_mov_b32 s7, 0x420c0000
	v_fma_f32 v82, v192, s6, v80
	v_fma_f32 v83, v193, s7, v80
	s_mov_b32 s6, 0x42000000
	s_mov_b32 s7, 0x42040000
	v_fma_f32 v81, v197, s7, v80
	v_fma_f32 v80, v196, s6, v80
	s_waitcnt lgkmcnt(1)
	v_mfma_f32_32x32x16_bf16 v[64:79], v[100:103], v[148:151], v[64:79]
	s_waitcnt lgkmcnt(0)
	v_mfma_f32_32x32x16_bf16 v[80:95], v[96:99], v[144:147], v[80:95]
	ds_read_b128 v[96:99], v204 offset:13856
	ds_read_b128 v[136:139], v204 offset:9280
	ds_read_b128 v[140:143], v204 offset:13888
	ds_read_b128 v[244:247], v204 offset:9312
	s_waitcnt lgkmcnt(3)
	v_mfma_f32_32x32x16_bf16 v[80:95], v[96:99], v[148:151], v[80:95]
	ds_read_b128 v[96:99], v204 offset:13920
	s_waitcnt lgkmcnt(3)
	v_mfma_f32_32x32x16_bf16 v[64:79], v[136:139], v[152:155], v[64:79]
	s_waitcnt lgkmcnt(2)
	v_mfma_f32_32x32x16_bf16 v[80:95], v[140:143], v[152:155], v[80:95]
	s_waitcnt lgkmcnt(1)
	v_mfma_f32_32x32x16_bf16 v[64:79], v[244:247], v[156:159], v[64:79]
	s_waitcnt lgkmcnt(0)
	v_mfma_f32_32x32x16_bf16 v[80:95], v[96:99], v[156:159], v[80:95]
.LBB0_263:
	s_cmp_gt_i32 s4, s26
	s_cbranch_scc1 .LBB0_277
	s_lshl_b32 s7, s4, 6
	s_or_b32 s6, s7, 63
	v_or_b32_e32 v96, s7, v200
	s_sub_i32 s8, s31, s6
	v_sub_u32_e32 v128, v199, v96
	s_cmpk_lt_i32 s8, 0x201
	s_mov_b64 s[4:5], -1
	s_cbranch_scc0 .LBB0_300
	s_sub_i32 s7, s31, s7
	s_cmpk_gt_i32 s8, 0x80
	s_cselect_b64 s[4:5], -1, 0
	s_cmpk_lt_i32 s7, 0x1e2
	s_cselect_b64 s[8:9], -1, 0
	s_and_b64 s[8:9], s[8:9], s[4:5]
	s_mov_b64 s[4:5], -1
	s_and_b64 vcc, exec, s[8:9]
	s_cbranch_vccnz .LBB0_267
	v_cmp_gt_i32_e32 vcc, s3, v128
	s_nop 1
	v_cndmask_b32_e64 v96, 0, 1.0, vcc
	v_cmp_gt_i32_e32 vcc, s33, v128
	s_and_b64 s[4:5], s[38:39], vcc
	v_cndmask_b32_e64 v97, 0, 1.0, s[4:5]
	v_add_f32_e32 v96, v96, v97
	v_add_u32_e32 v97, -1, v128
	v_cmp_gt_i32_e32 vcc, s3, v97
	v_add_f32_e32 v96, v207, v96
	v_log_f32_e32 v96, v96
	v_cndmask_b32_e64 v98, 0, 1.0, vcc
	v_cmp_gt_i32_e32 vcc, s33, v97
	s_and_b64 s[4:5], s[40:41], vcc
	v_cndmask_b32_e64 v97, 0, 1.0, s[4:5]
	v_add_f32_e32 v97, v98, v97
	v_add_u32_e32 v98, -2, v128
	v_cmp_gt_i32_e32 vcc, s3, v98
	v_add_f32_e32 v97, v208, v97
	v_log_f32_e32 v97, v97
	v_cndmask_b32_e64 v99, 0, 1.0, vcc
	v_cmp_gt_i32_e32 vcc, s33, v98
	s_and_b64 s[4:5], s[42:43], vcc
	v_cndmask_b32_e64 v98, 0, 1.0, s[4:5]
	v_add_f32_e32 v98, v99, v98
	v_add_u32_e32 v99, -3, v128
	v_cmp_gt_i32_e32 vcc, s3, v99
	v_add_f32_e32 v98, v209, v98
	v_log_f32_e32 v98, v98
	v_cndmask_b32_e64 v100, 0, 1.0, vcc
	v_cmp_gt_i32_e32 vcc, s33, v99
	s_and_b64 s[4:5], s[44:45], vcc
	v_cndmask_b32_e64 v99, 0, 1.0, s[4:5]
	v_add_f32_e32 v99, v100, v99
	v_add_u32_e32 v100, -8, v128
	v_cmp_gt_i32_e32 vcc, s3, v100
	v_add_f32_e32 v99, v210, v99
	v_log_f32_e32 v99, v99
	v_cndmask_b32_e64 v101, 0, 1.0, vcc
	v_cmp_gt_i32_e32 vcc, s33, v100
	s_and_b64 s[4:5], s[38:39], vcc
	v_cndmask_b32_e64 v100, 0, 1.0, s[4:5]
	v_add_f32_e32 v100, v101, v100
	v_add_u32_e32 v101, -9, v128
	v_cmp_gt_i32_e32 vcc, s3, v101
	v_add_f32_e32 v100, v211, v100
	v_log_f32_e32 v100, v100
	v_cndmask_b32_e64 v102, 0, 1.0, vcc
	v_cmp_gt_i32_e32 vcc, s33, v101
	s_and_b64 s[4:5], s[40:41], vcc
	v_cndmask_b32_e64 v101, 0, 1.0, s[4:5]
	v_add_f32_e32 v101, v102, v101
	v_add_u32_e32 v102, -10, v128
	v_cmp_gt_i32_e32 vcc, s3, v102
	v_add_f32_e32 v101, v212, v101
	v_log_f32_e32 v101, v101
	v_cndmask_b32_e64 v103, 0, 1.0, vcc
	v_cmp_gt_i32_e32 vcc, s33, v102
	s_and_b64 s[4:5], s[42:43], vcc
	v_cndmask_b32_e64 v102, 0, 1.0, s[4:5]
	v_add_f32_e32 v102, v103, v102
	v_add_u32_e32 v103, -11, v128
	v_cmp_gt_i32_e32 vcc, s3, v103
	v_add_f32_e32 v102, v213, v102
	v_log_f32_e32 v102, v102
	v_cndmask_b32_e64 v104, 0, 1.0, vcc
	v_cmp_gt_i32_e32 vcc, s33, v103
	s_and_b64 s[4:5], s[44:45], vcc
	v_cndmask_b32_e64 v103, 0, 1.0, s[4:5]
	v_add_f32_e32 v103, v104, v103
	v_add_u32_e32 v104, -16, v128
	v_cmp_gt_i32_e32 vcc, s3, v104
	v_add_f32_e32 v103, v214, v103
	v_log_f32_e32 v103, v103
	v_cndmask_b32_e64 v105, 0, 1.0, vcc
	v_cmp_gt_i32_e32 vcc, s33, v104
	s_and_b64 s[4:5], s[38:39], vcc
	v_cndmask_b32_e64 v104, 0, 1.0, s[4:5]
	v_add_f32_e32 v104, v105, v104
	v_subrev_u32_e32 v105, 17, v128
	v_cmp_gt_i32_e32 vcc, s3, v105
	v_add_f32_e32 v104, v207, v104
	v_log_f32_e32 v104, v104
	v_cndmask_b32_e64 v106, 0, 1.0, vcc
	v_cmp_gt_i32_e32 vcc, s33, v105
	s_and_b64 s[4:5], s[40:41], vcc
	v_cndmask_b32_e64 v105, 0, 1.0, s[4:5]
	v_add_f32_e32 v105, v106, v105
	v_subrev_u32_e32 v106, 18, v128
	v_cmp_gt_i32_e32 vcc, s3, v106
	v_add_f32_e32 v105, v208, v105
	v_log_f32_e32 v105, v105
	v_cndmask_b32_e64 v107, 0, 1.0, vcc
	v_cmp_gt_i32_e32 vcc, s33, v106
	s_and_b64 s[4:5], s[42:43], vcc
	v_cndmask_b32_e64 v106, 0, 1.0, s[4:5]
	v_add_f32_e32 v106, v107, v106
	v_subrev_u32_e32 v107, 19, v128
	v_cmp_gt_i32_e32 vcc, s3, v107
	v_add_f32_e32 v106, v209, v106
	v_log_f32_e32 v106, v106
	v_cndmask_b32_e64 v108, 0, 1.0, vcc
	v_cmp_gt_i32_e32 vcc, s33, v107
	s_and_b64 s[4:5], s[44:45], vcc
	v_cndmask_b32_e64 v107, 0, 1.0, s[4:5]
	v_add_f32_e32 v107, v108, v107
	v_subrev_u32_e32 v108, 24, v128
	v_cmp_gt_i32_e32 vcc, s3, v108
	v_add_f32_e32 v107, v210, v107
	v_log_f32_e32 v107, v107
	v_cndmask_b32_e64 v109, 0, 1.0, vcc
	v_cmp_gt_i32_e32 vcc, s33, v108
	s_and_b64 s[4:5], s[38:39], vcc
	v_cndmask_b32_e64 v108, 0, 1.0, s[4:5]
	v_add_f32_e32 v108, v109, v108
	v_subrev_u32_e32 v109, 25, v128
	v_cmp_gt_i32_e32 vcc, s3, v109
	v_add_f32_e32 v108, v211, v108
	v_log_f32_e32 v108, v108
	v_cndmask_b32_e64 v110, 0, 1.0, vcc
	v_cmp_gt_i32_e32 vcc, s33, v109
	s_and_b64 s[4:5], s[40:41], vcc
	v_cndmask_b32_e64 v109, 0, 1.0, s[4:5]
	v_add_f32_e32 v109, v110, v109
	v_subrev_u32_e32 v110, 26, v128
	v_cmp_gt_i32_e32 vcc, s3, v110
	v_add_f32_e32 v109, v212, v109
	v_log_f32_e32 v109, v109
	v_cndmask_b32_e64 v111, 0, 1.0, vcc
	v_cmp_gt_i32_e32 vcc, s33, v110
	s_and_b64 s[4:5], s[42:43], vcc
	v_cndmask_b32_e64 v110, 0, 1.0, s[4:5]
	v_add_f32_e32 v110, v111, v110
	v_subrev_u32_e32 v111, 27, v128
	v_cmp_gt_i32_e32 vcc, s3, v111
	v_add_f32_e32 v110, v213, v110
	v_log_f32_e32 v110, v110
	v_cndmask_b32_e64 v112, 0, 1.0, vcc
	v_cmp_gt_i32_e32 vcc, s33, v111
	s_and_b64 s[4:5], s[44:45], vcc
	v_cndmask_b32_e64 v111, 0, 1.0, s[4:5]
	v_add_f32_e32 v111, v112, v111
	v_subrev_u32_e32 v112, 32, v128
	v_cmp_gt_i32_e32 vcc, s3, v112
	v_add_f32_e32 v111, v214, v111
	v_log_f32_e32 v111, v111
	v_cndmask_b32_e64 v113, 0, 1.0, vcc
	v_cmp_gt_i32_e32 vcc, s33, v112
	s_and_b64 s[4:5], s[38:39], vcc
	v_cndmask_b32_e64 v112, 0, 1.0, s[4:5]
	v_add_f32_e32 v112, v113, v112
	v_subrev_u32_e32 v113, 33, v128
	v_cmp_gt_i32_e32 vcc, s3, v113
	v_add_f32_e32 v112, v207, v112
	v_log_f32_e32 v112, v112
	v_cndmask_b32_e64 v114, 0, 1.0, vcc
	v_cmp_gt_i32_e32 vcc, s33, v113
	s_and_b64 s[4:5], s[40:41], vcc
	v_cndmask_b32_e64 v113, 0, 1.0, s[4:5]
	v_add_f32_e32 v113, v114, v113
	v_subrev_u32_e32 v114, 34, v128
	v_cmp_gt_i32_e32 vcc, s3, v114
	v_add_f32_e32 v113, v208, v113
	v_log_f32_e32 v113, v113
	v_cndmask_b32_e64 v115, 0, 1.0, vcc
	v_cmp_gt_i32_e32 vcc, s33, v114
	s_and_b64 s[4:5], s[42:43], vcc
	v_cndmask_b32_e64 v114, 0, 1.0, s[4:5]
	v_add_f32_e32 v114, v115, v114
	v_subrev_u32_e32 v115, 35, v128
	v_cmp_gt_i32_e32 vcc, s3, v115
	v_add_f32_e32 v114, v209, v114
	v_log_f32_e32 v114, v114
	v_cndmask_b32_e64 v116, 0, 1.0, vcc
	v_cmp_gt_i32_e32 vcc, s33, v115
	s_and_b64 s[4:5], s[44:45], vcc
	v_cndmask_b32_e64 v115, 0, 1.0, s[4:5]
	v_add_f32_e32 v115, v116, v115
	v_subrev_u32_e32 v116, 40, v128
	v_cmp_gt_i32_e32 vcc, s3, v116
	v_add_f32_e32 v115, v210, v115
	v_log_f32_e32 v115, v115
	v_cndmask_b32_e64 v117, 0, 1.0, vcc
	v_cmp_gt_i32_e32 vcc, s33, v116
	s_and_b64 s[4:5], s[38:39], vcc
	v_cndmask_b32_e64 v116, 0, 1.0, s[4:5]
	v_add_f32_e32 v116, v117, v116
	v_subrev_u32_e32 v117, 41, v128
	v_cmp_gt_i32_e32 vcc, s3, v117
	v_add_f32_e32 v116, v211, v116
	v_log_f32_e32 v116, v116
	v_cndmask_b32_e64 v118, 0, 1.0, vcc
	v_cmp_gt_i32_e32 vcc, s33, v117
	s_and_b64 s[4:5], s[40:41], vcc
	v_cndmask_b32_e64 v117, 0, 1.0, s[4:5]
	v_add_f32_e32 v117, v118, v117
	v_subrev_u32_e32 v118, 42, v128
	v_cmp_gt_i32_e32 vcc, s3, v118
	v_add_f32_e32 v117, v212, v117
	v_log_f32_e32 v117, v117
	v_cndmask_b32_e64 v119, 0, 1.0, vcc
	v_cmp_gt_i32_e32 vcc, s33, v118
	s_and_b64 s[4:5], s[42:43], vcc
	v_cndmask_b32_e64 v118, 0, 1.0, s[4:5]
	v_add_f32_e32 v118, v119, v118
	v_subrev_u32_e32 v119, 43, v128
	v_cmp_gt_i32_e32 vcc, s3, v119
	v_add_f32_e32 v118, v213, v118
	v_log_f32_e32 v118, v118
	v_cndmask_b32_e64 v120, 0, 1.0, vcc
	v_cmp_gt_i32_e32 vcc, s33, v119
	s_and_b64 s[4:5], s[44:45], vcc
	v_cndmask_b32_e64 v119, 0, 1.0, s[4:5]
	v_add_f32_e32 v119, v120, v119
	v_subrev_u32_e32 v120, 48, v128
	v_cmp_gt_i32_e32 vcc, s3, v120
	v_add_f32_e32 v119, v214, v119
	v_log_f32_e32 v119, v119
	v_cndmask_b32_e64 v121, 0, 1.0, vcc
	v_cmp_gt_i32_e32 vcc, s33, v120
	s_and_b64 s[4:5], s[38:39], vcc
	v_cndmask_b32_e64 v120, 0, 1.0, s[4:5]
	v_add_f32_e32 v120, v121, v120
	v_subrev_u32_e32 v121, 49, v128
	v_cmp_gt_i32_e32 vcc, s3, v121
	v_add_f32_e32 v120, v207, v120
	v_log_f32_e32 v120, v120
	v_cndmask_b32_e64 v122, 0, 1.0, vcc
	v_cmp_gt_i32_e32 vcc, s33, v121
	s_and_b64 s[4:5], s[40:41], vcc
	v_cndmask_b32_e64 v121, 0, 1.0, s[4:5]
	v_add_f32_e32 v121, v122, v121
	v_subrev_u32_e32 v122, 50, v128
	v_cmp_gt_i32_e32 vcc, s3, v122
	v_add_f32_e32 v121, v208, v121
	v_log_f32_e32 v121, v121
	v_cndmask_b32_e64 v123, 0, 1.0, vcc
	v_cmp_gt_i32_e32 vcc, s33, v122
	s_and_b64 s[4:5], s[42:43], vcc
	v_cndmask_b32_e64 v122, 0, 1.0, s[4:5]
	v_add_f32_e32 v122, v123, v122
	v_subrev_u32_e32 v123, 51, v128
	v_cmp_gt_i32_e32 vcc, s3, v123
	v_add_f32_e32 v122, v209, v122
	v_log_f32_e32 v122, v122
	v_cndmask_b32_e64 v124, 0, 1.0, vcc
	v_cmp_gt_i32_e32 vcc, s33, v123
	s_and_b64 s[4:5], s[44:45], vcc
	v_cndmask_b32_e64 v123, 0, 1.0, s[4:5]
	v_add_f32_e32 v123, v124, v123
	v_subrev_u32_e32 v124, 56, v128
	v_cmp_gt_i32_e32 vcc, s3, v124
	v_add_f32_e32 v123, v210, v123
	v_log_f32_e32 v123, v123
	v_cndmask_b32_e64 v125, 0, 1.0, vcc
	v_cmp_gt_i32_e32 vcc, s33, v124
	s_and_b64 s[4:5], s[38:39], vcc
	v_cndmask_b32_e64 v124, 0, 1.0, s[4:5]
	v_add_f32_e32 v124, v125, v124
	v_subrev_u32_e32 v125, 57, v128
	v_cmp_gt_i32_e32 vcc, s3, v125
	v_add_f32_e32 v124, v211, v124
	v_log_f32_e32 v124, v124
	v_cndmask_b32_e64 v126, 0, 1.0, vcc
	v_cmp_gt_i32_e32 vcc, s33, v125
	s_and_b64 s[4:5], s[40:41], vcc
	v_cndmask_b32_e64 v125, 0, 1.0, s[4:5]
	v_add_f32_e32 v125, v126, v125
	v_subrev_u32_e32 v126, 58, v128
	v_cmp_gt_i32_e32 vcc, s3, v126
	v_add_f32_e32 v125, v212, v125
	v_log_f32_e32 v125, v125
	v_cndmask_b32_e64 v127, 0, 1.0, vcc
	v_cmp_gt_i32_e32 vcc, s33, v126
	s_and_b64 s[4:5], s[42:43], vcc
	v_cndmask_b32_e64 v126, 0, 1.0, s[4:5]
	v_add_f32_e32 v126, v127, v126
	v_subrev_u32_e32 v127, 59, v128
	v_cmp_gt_i32_e32 vcc, s3, v127
	v_add_f32_e32 v126, v213, v126
	v_log_f32_e32 v126, v126
	v_cndmask_b32_e64 v130, 0, 1.0, vcc
	v_cmp_gt_i32_e32 vcc, s33, v127
	s_and_b64 s[4:5], s[44:45], vcc
	v_cndmask_b32_e64 v127, 0, 1.0, s[4:5]
	v_add_f32_e32 v127, v130, v127
	v_add_f32_e32 v127, v214, v127
	v_log_f32_e32 v127, v127
	v_add_f32_e32 v110, v110, v46
	v_add_f32_e32 v111, v111, v47
	v_add_f32_e32 v108, v108, v44
	v_add_f32_e32 v109, v109, v45
	v_add_f32_e32 v106, v106, v42
	v_add_f32_e32 v107, v107, v43
	v_add_f32_e32 v104, v104, v40
	v_add_f32_e32 v105, v105, v41
	v_add_f32_e32 v102, v102, v38
	v_add_f32_e32 v103, v103, v39
	v_add_f32_e32 v100, v100, v36
	v_add_f32_e32 v101, v101, v37
	v_add_f32_e32 v98, v98, v34
	v_add_f32_e32 v99, v99, v35
	v_add_f32_e32 v96, v96, v32
	v_add_f32_e32 v97, v97, v33
	v_add_f32_e32 v126, v126, v62
	v_add_f32_e32 v127, v127, v63
	v_add_f32_e32 v124, v124, v60
	v_add_f32_e32 v125, v125, v61
	v_add_f32_e32 v122, v122, v58
	v_add_f32_e32 v123, v123, v59
	v_add_f32_e32 v120, v120, v56
	v_add_f32_e32 v121, v121, v57
	v_add_f32_e32 v118, v118, v54
	v_add_f32_e32 v119, v119, v55
	v_add_f32_e32 v116, v116, v52
	v_add_f32_e32 v117, v117, v53
	v_add_f32_e32 v114, v114, v50
	v_add_f32_e32 v115, v115, v51
	v_add_f32_e32 v112, v112, v48
	v_add_f32_e32 v113, v113, v49
	s_mov_b64 s[4:5], 0

.LBB0_272:
	v_max_f32_e32 v32, v97, v97
	v_max_f32_e32 v33, v96, v96
	v_max_f32_e32 v32, v33, v32
	v_max3_f32 v32, v32, v98, v99
	v_max3_f32 v32, v32, v100, v101
	v_max3_f32 v32, v32, v102, v103
	v_max3_f32 v32, v32, v104, v105
	v_max3_f32 v32, v32, v106, v107
	v_max3_f32 v32, v32, v108, v109
	v_max3_f32 v32, v32, v110, v111
	v_max3_f32 v32, v32, v112, v113
	v_max3_f32 v32, v32, v114, v115
	v_max3_f32 v32, v32, v116, v117
	v_max3_f32 v32, v32, v118, v119
	v_max3_f32 v32, v32, v120, v121
	v_max3_f32 v32, v32, v122, v123
	v_max3_f32 v32, v32, v124, v125
	v_max3_f32 v32, v32, v126, v127
	v_mov_b32_e32 v33, v32
	v_mov_b32_e32 v34, v32
	s_nop 1
	v_permlane32_swap_b32_e32 v33, v34
	v_cndmask_b32_e64 v33, v33, v34, s[58:59]
	v_max3_f32 v130, v131, v32, v33
	v_cmp_neq_f32_e32 vcc, s2, v130
	s_nop 1
	v_cndmask_b32_e32 v63, 0, v130, vcc
	v_sub_f32_e32 v32, v131, v63
	v_exp_f32_e32 v128, v32
	s_nop 0
	v_cmp_eq_f32_e32 vcc, 1.0, v128
	s_cmp_eq_u64 vcc, exec
	s_cbranch_scc1 .LBB0_274
	v_mul_f32_e32 v30, v30, v128
	v_mul_f32_e32 v31, v31, v128
	v_mul_f32_e32 v28, v28, v128
	v_mul_f32_e32 v29, v29, v128
	v_mul_f32_e32 v26, v26, v128
	v_mul_f32_e32 v27, v27, v128
	v_mul_f32_e32 v24, v24, v128
	v_mul_f32_e32 v25, v25, v128
	v_mul_f32_e32 v22, v22, v128
	v_mul_f32_e32 v23, v23, v128
	v_mul_f32_e32 v20, v20, v128
	v_mul_f32_e32 v21, v21, v128
	v_mul_f32_e32 v18, v18, v128
	v_mul_f32_e32 v19, v19, v128
	v_mul_f32_e32 v16, v16, v128
	v_mul_f32_e32 v17, v17, v128
	v_mul_f32_e32 v14, v14, v128
	v_mul_f32_e32 v15, v15, v128
	v_mul_f32_e32 v12, v12, v128
	v_mul_f32_e32 v13, v13, v128
	v_mul_f32_e32 v10, v10, v128
	v_mul_f32_e32 v11, v11, v128
	v_mul_f32_e32 v8, v8, v128
	v_mul_f32_e32 v9, v9, v128
	v_mul_f32_e32 v6, v6, v128
	v_mul_f32_e32 v7, v7, v128
	v_mul_f32_e32 v4, v4, v128
	v_mul_f32_e32 v5, v5, v128
	v_mul_f32_e32 v2, v2, v128
	v_mul_f32_e32 v3, v3, v128
	v_mul_f32_e32 v0, v0, v128
	v_mul_f32_e32 v1, v1, v128

.LBB0_297:
	v_max_f32_e32 v64, v97, v97
	v_max_f32_e32 v65, v96, v96
	v_max_f32_e32 v64, v65, v64
	v_max3_f32 v64, v64, v98, v99
	v_max3_f32 v64, v64, v100, v101
	v_max3_f32 v64, v64, v102, v103
	v_max3_f32 v64, v64, v104, v105
	v_max3_f32 v64, v64, v106, v107
	v_max3_f32 v64, v64, v108, v109
	v_max3_f32 v64, v64, v110, v111
	v_max3_f32 v64, v64, v112, v113
	v_max3_f32 v64, v64, v114, v115
	v_max3_f32 v64, v64, v116, v117
	v_max3_f32 v64, v64, v118, v119
	v_max3_f32 v64, v64, v120, v121
	v_max3_f32 v64, v64, v122, v123
	v_max3_f32 v64, v64, v124, v125
	v_max3_f32 v64, v64, v126, v127
	v_mov_b32_e32 v65, v64
	v_mov_b32_e32 v66, v64
	s_nop 1
	v_permlane32_swap_b32_e32 v65, v66
	v_cndmask_b32_e64 v65, v65, v66, s[58:59]
	v_max3_f32 v216, v130, v64, v65
	v_cmp_neq_f32_e32 vcc, s2, v216
	s_nop 1
	v_cndmask_b32_e32 v95, 0, v216, vcc
	v_sub_f32_e32 v64, v130, v95
	v_exp_f32_e32 v128, v64
	s_nop 0
	v_cmp_eq_f32_e32 vcc, 1.0, v128
	s_cmp_eq_u64 vcc, exec
	s_cbranch_scc1 .LBB0_299
	v_mul_f32_e32 v30, v30, v128
	v_mul_f32_e32 v31, v31, v128
	v_mul_f32_e32 v28, v28, v128
	v_mul_f32_e32 v29, v29, v128
	v_mul_f32_e32 v26, v26, v128
	v_mul_f32_e32 v27, v27, v128
	v_mul_f32_e32 v24, v24, v128
	v_mul_f32_e32 v25, v25, v128
	v_mul_f32_e32 v22, v22, v128
	v_mul_f32_e32 v23, v23, v128
	v_mul_f32_e32 v20, v20, v128
	v_mul_f32_e32 v21, v21, v128
	v_mul_f32_e32 v18, v18, v128
	v_mul_f32_e32 v19, v19, v128
	v_mul_f32_e32 v16, v16, v128
	v_mul_f32_e32 v17, v17, v128
	v_mul_f32_e32 v14, v14, v128
	v_mul_f32_e32 v15, v15, v128
	v_mul_f32_e32 v12, v12, v128
	v_mul_f32_e32 v13, v13, v128
	v_mul_f32_e32 v10, v10, v128
	v_mul_f32_e32 v11, v11, v128
	v_mul_f32_e32 v8, v8, v128
	v_mul_f32_e32 v9, v9, v128
	v_mul_f32_e32 v6, v6, v128
	v_mul_f32_e32 v7, v7, v128
	v_mul_f32_e32 v4, v4, v128
	v_mul_f32_e32 v5, v5, v128
	v_mul_f32_e32 v2, v2, v128
	v_mul_f32_e32 v3, v3, v128
	v_mul_f32_e32 v0, v0, v128
	v_mul_f32_e32 v1, v1, v128

.LBB0_308:
	v_mov_b32_e32 v32, v215
	v_mov_b32_e32 v33, v215
	s_nop 1
	v_permlane32_swap_b32_e32 v32, v33
	v_cndmask_b32_e64 v32, v32, v33, s[58:59]
	v_add_f32_e32 v32, v215, v32
	v_div_scale_f32 v33, s[4:5], v32, v32, 1.0
	v_rcp_f32_e32 v34, v33
	s_lshl_b32 s4, s27, 11
	s_add_i32 s14, s14, s4
	s_ashr_i32 s4, s15, 1
	v_fma_f32 v35, -v33, v34, 1.0
	v_fmac_f32_e32 v34, v35, v34
	v_div_scale_f32 v35, vcc, 1.0, v32, 1.0
	v_mul_f32_e32 v36, v35, v34
	v_fma_f32 v37, -v33, v36, v35
	v_fmac_f32_e32 v36, v37, v34
	v_fma_f32 v33, -v33, v36, v35
	v_div_fmas_f32 v33, v33, v34, v36
	v_div_fixup_f32 v32, v33, v32, 1.0
	v_mul_f32_e32 v30, v30, v32
	v_mul_f32_e32 v31, v31, v32
	v_mul_f32_e32 v28, v28, v32
	v_mul_f32_e32 v29, v29, v32
	v_mul_f32_e32 v26, v26, v32
	v_mul_f32_e32 v27, v27, v32
	v_mul_f32_e32 v24, v24, v32
	v_mul_f32_e32 v25, v25, v32
	v_mul_f32_e32 v22, v22, v32
	v_mul_f32_e32 v23, v23, v32
	v_mul_f32_e32 v20, v20, v32
	v_mul_f32_e32 v21, v21, v32
	v_mul_f32_e32 v18, v18, v32
	v_mul_f32_e32 v19, v19, v32
	v_mul_f32_e32 v16, v16, v32
	v_mul_f32_e32 v17, v17, v32
	v_mul_f32_e32 v14, v14, v32
	v_mul_f32_e32 v15, v15, v32
	v_mul_f32_e32 v12, v12, v32
	v_mul_f32_e32 v13, v13, v32
	v_mul_f32_e32 v10, v10, v32
	v_mul_f32_e32 v11, v11, v32
	v_mul_f32_e32 v8, v8, v32
	v_mul_f32_e32 v9, v9, v32
	v_mul_f32_e32 v6, v6, v32
	v_mul_f32_e32 v7, v7, v32
	v_mul_f32_e32 v4, v4, v32
	v_mul_f32_e32 v5, v5, v32
	v_mul_f32_e32 v2, v2, v32
	v_mul_f32_e32 v3, v3, v32
	v_mul_f32_e32 v0, v0, v32
	v_mul_f32_e32 v1, v1, v32
	s_andn2_b32 s4, s4, 31
	v_and_or_b32 v32, v198, 31, s14
	v_add_u32_e32 v32, s4, v32
	v_ashrrev_i32_e32 v33, 31, v32
	v_readlane_b32 s4, v255, 13
	v_lshlrev_b64 v[32:33], 12, v[32:33]
	v_readlane_b32 s5, v255, 14
	s_lshl_b32 s6, s22, 1
	v_lshrrev_b32_e32 v34, 2, v198
	v_lshl_add_u64 v[32:33], s[4:5], 0, v[32:33]
	v_readlane_b32 s4, v254, 19
	v_readlane_b32 s5, v254, 20
	s_mov_b32 s7, s5
	v_lshl_add_u64 v[32:33], v[32:33], 0, s[6:7]
	v_and_b32_e32 v128, 8, v34
	v_lshl_add_u64 v[32:33], v[32:33], 0, v[128:129]
	v_cvt_pk_bf16_f32 v16, v16, v17
	v_cvt_pk_bf16_f32 v17, v18, v19
	v_cvt_pk_bf16_f32 v0, v0, v1
	v_cvt_pk_bf16_f32 v1, v2, v3
	global_store_dwordx2 v[32:33], v[16:17], off offset:3072
	v_cvt_pk_bf16_f32 v16, v20, v21
	v_cvt_pk_bf16_f32 v17, v22, v23
	global_store_dwordx2 v[32:33], v[0:1], off offset:3136
	v_cvt_pk_bf16_f32 v0, v4, v5
	v_cvt_pk_bf16_f32 v1, v6, v7
	global_store_dwordx2 v[32:33], v[16:17], off offset:3088
	v_cvt_pk_bf16_f32 v16, v24, v25
	v_cvt_pk_bf16_f32 v17, v26, v27
	global_store_dwordx2 v[32:33], v[0:1], off offset:3152
	v_cvt_pk_bf16_f32 v0, v8, v9
	v_cvt_pk_bf16_f32 v1, v10, v11
	v_writelane_b32 v254, s4, 19
	global_store_dwordx2 v[32:33], v[16:17], off offset:3104
	v_cvt_pk_bf16_f32 v16, v28, v29
	v_cvt_pk_bf16_f32 v17, v30, v31
	global_store_dwordx2 v[32:33], v[0:1], off offset:3168
	v_cvt_pk_bf16_f32 v0, v12, v13
	v_cvt_pk_bf16_f32 v1, v14, v15
	v_readlane_b32 s30, v255, 3
	v_readlane_b32 s78, v255, 5
	v_readlane_b32 s22, v255, 16
	v_writelane_b32 v254, s5, 20
	global_store_dwordx2 v[32:33], v[16:17], off offset:3120
	global_store_dwordx2 v[32:33], v[0:1], off offset:3184
	s_mov_b64 s[4:5], 0
	v_readlane_b32 s31, v255, 4
	v_readlane_b32 s79, v255, 6
	s_movk_i32 s80, 0x6020
	s_mov_b64 s[82:83], 0x600000
	v_readlane_b32 s23, v255, 17
.LBB0_309:
	s_mov_b64 s[66:67], 0
	s_and_b64 vcc, exec, s[4:5]
	s_mov_b64 s[4:5], 0
	s_cbranch_vccz .LBB0_357
	s_mul_i32 s25, s27, 0x1800000
	v_readlane_b32 s4, v255, 11
	s_mul_hi_i32 s19, s27, 0x1800000
	v_readlane_b32 s5, v255, 12
	s_add_u32 s11, s4, s25
	s_addc_u32 s14, s5, s19
	s_lshl_b32 s26, s29, 8
	s_add_u32 s4, s11, s26
	v_mov_b32_e32 v202, v241
	s_addc_u32 s5, s14, 0
	v_mov_b32_e32 v4, v241
	s_add_u32 s64, s4, 0x1800
	s_addc_u32 s65, s5, 0
	v_readfirstlane_b32 s10, v4
	s_ashr_i32 s9, s10, 6
	s_lshl_b32 s30, s28, 8
	s_lshl_b32 s8, s9, 5
	v_and_b32_e32 v2, 31, v4
	s_add_i32 s21, s8, s30
	v_bfe_u32 v3, v4, 5, 1
	v_or_b32_e32 v5, s21, v2
	v_mov_b64_e32 v[0:1], s[64:65]
	s_movk_i32 s4, 0x3000
	v_mad_i64_i32 v[0:1], s[4:5], v5, s4, v[0:1]
	v_lshlrev_b32_e32 v128, 4, v3
	v_lshl_add_u64 v[0:1], v[0:1], 0, v[128:129]
	global_load_dwordx4 v[6:9], v[0:1], off
	global_load_dwordx4 v[16:19], v[0:1], off offset:32
	global_load_dwordx4 v[20:23], v[0:1], off offset:64
	global_load_dwordx4 v[24:27], v[0:1], off offset:96
	s_mov_b32 s4, 0x3e38aa3b
	s_add_i32 s15, s28, 1
	s_lshl_b32 s23, s15, 8
	v_readfirstlane_b32 s17, v202
	v_cmp_gt_i32_e32 vcc, s23, v4
	s_waitcnt vmcnt(3)
	v_and_b32_e32 v11, 0xffff0000, v6
	v_lshlrev_b32_e32 v10, 16, v6
	v_mul_f32_e32 v10, s4, v10
	v_mul_f32_e32 v11, s4, v11
	s_nop 0
	v_cvt_pk_bf16_f32 v96, v10, v11
	v_and_b32_e32 v11, 0xffff0000, v7
	v_lshlrev_b32_e32 v10, 16, v7
	v_mul_f32_e32 v6, s4, v10
	v_mul_f32_e32 v7, s4, v11
	s_nop 0
	v_cvt_pk_bf16_f32 v97, v6, v7
	v_and_b32_e32 v7, 0xffff0000, v8
	v_lshlrev_b32_e32 v6, 16, v8
	v_mul_f32_e32 v6, s4, v6
	v_mul_f32_e32 v7, s4, v7
	s_nop 0
	v_cvt_pk_bf16_f32 v98, v6, v7
	v_and_b32_e32 v7, 0xffff0000, v9
	v_lshlrev_b32_e32 v6, 16, v9
	v_mul_f32_e32 v6, s4, v6
	v_mul_f32_e32 v7, s4, v7
	s_nop 0
	v_cvt_pk_bf16_f32 v99, v6, v7
	s_waitcnt vmcnt(2)
	v_and_b32_e32 v11, 0xffff0000, v16
	v_lshlrev_b32_e32 v10, 16, v16
	v_mul_f32_e32 v10, s4, v10
	v_mul_f32_e32 v11, s4, v11
	s_nop 0
	v_cvt_pk_bf16_f32 v100, v10, v11
	v_and_b32_e32 v11, 0xffff0000, v17
	v_lshlrev_b32_e32 v10, 16, v17
	v_mul_f32_e32 v6, s4, v10
	v_mul_f32_e32 v7, s4, v11
	s_nop 0
	v_cvt_pk_bf16_f32 v101, v6, v7
	v_and_b32_e32 v7, 0xffff0000, v18
	v_lshlrev_b32_e32 v6, 16, v18
	v_mul_f32_e32 v6, s4, v6
	v_mul_f32_e32 v7, s4, v7
	s_nop 0
	v_cvt_pk_bf16_f32 v102, v6, v7
	v_and_b32_e32 v7, 0xffff0000, v19
	v_lshlrev_b32_e32 v6, 16, v19
	v_mul_f32_e32 v6, s4, v6
	v_mul_f32_e32 v7, s4, v7
	s_nop 0
	v_cvt_pk_bf16_f32 v103, v6, v7
	s_waitcnt vmcnt(1)
	v_and_b32_e32 v11, 0xffff0000, v20
	v_lshlrev_b32_e32 v10, 16, v20
	v_mul_f32_e32 v10, s4, v10
	v_mul_f32_e32 v11, s4, v11
	s_nop 0
	v_cvt_pk_bf16_f32 v104, v10, v11
	v_and_b32_e32 v11, 0xffff0000, v21
	v_lshlrev_b32_e32 v10, 16, v21
	v_mul_f32_e32 v6, s4, v10
	v_mul_f32_e32 v7, s4, v11
	s_nop 0
	v_cvt_pk_bf16_f32 v105, v6, v7
	v_and_b32_e32 v7, 0xffff0000, v22
	v_lshlrev_b32_e32 v6, 16, v22
	v_mul_f32_e32 v6, s4, v6
	v_mul_f32_e32 v7, s4, v7
	s_nop 0
	v_cvt_pk_bf16_f32 v106, v6, v7
	v_and_b32_e32 v7, 0xffff0000, v23
	v_lshlrev_b32_e32 v6, 16, v23
	v_mul_f32_e32 v6, s4, v6
	v_mul_f32_e32 v7, s4, v7
	s_nop 0
	v_cvt_pk_bf16_f32 v107, v6, v7
	s_waitcnt vmcnt(0)
	v_and_b32_e32 v1, 0xffff0000, v24
	v_lshlrev_b32_e32 v0, 16, v24
	v_mul_f32_e32 v0, s4, v0
	v_mul_f32_e32 v1, s4, v1
	s_nop 0
	v_cvt_pk_bf16_f32 v108, v0, v1
	v_and_b32_e32 v1, 0xffff0000, v25
	v_lshlrev_b32_e32 v0, 16, v25
	v_mul_f32_e32 v0, s4, v0
	v_mul_f32_e32 v1, s4, v1
	s_nop 0
	v_cvt_pk_bf16_f32 v109, v0, v1
	v_and_b32_e32 v1, 0xffff0000, v26
	v_lshlrev_b32_e32 v0, 16, v26
	v_mul_f32_e32 v0, s4, v0
	v_mul_f32_e32 v1, s4, v1
	v_mov_b32_e32 v8, 0
	v_cvt_pk_bf16_f32 v110, v0, v1
	v_and_b32_e32 v1, 0xffff0000, v27
	v_lshlrev_b32_e32 v0, 16, v27
	v_mul_f32_e32 v0, s4, v0
	v_mul_f32_e32 v1, s4, v1
	s_nop 0
	v_cvt_pk_bf16_f32 v111, v0, v1
	v_and_b32_e32 v1, 0xffff0000, v96
	v_lshlrev_b32_e32 v0, 16, v96
	v_mul_f32_e32 v5, v1, v1
	v_fmac_f32_e32 v5, v0, v0
	v_lshlrev_b32_e32 v0, 16, v97
	v_fmac_f32_e32 v5, v0, v0
	v_and_b32_e32 v0, 0xffff0000, v97
	v_fmac_f32_e32 v5, v0, v0
	v_lshlrev_b32_e32 v0, 16, v98
	v_fmac_f32_e32 v5, v0, v0
	v_and_b32_e32 v0, 0xffff0000, v98
	v_fmac_f32_e32 v5, v0, v0
	v_lshlrev_b32_e32 v0, 16, v99
	v_fmac_f32_e32 v5, v0, v0
	v_and_b32_e32 v0, 0xffff0000, v99
	v_fmac_f32_e32 v5, v0, v0
	v_lshlrev_b32_e32 v0, 16, v100
	v_fmac_f32_e32 v5, v0, v0
	v_and_b32_e32 v0, 0xffff0000, v100
	v_fmac_f32_e32 v5, v0, v0
	v_lshlrev_b32_e32 v0, 16, v101
	v_fmac_f32_e32 v5, v0, v0
	v_and_b32_e32 v0, 0xffff0000, v101
	v_fmac_f32_e32 v5, v0, v0
	v_lshlrev_b32_e32 v0, 16, v102
	v_fmac_f32_e32 v5, v0, v0
	v_and_b32_e32 v0, 0xffff0000, v102
	v_fmac_f32_e32 v5, v0, v0
	v_lshlrev_b32_e32 v0, 16, v103
	v_fmac_f32_e32 v5, v0, v0
	v_and_b32_e32 v0, 0xffff0000, v103
	v_fmac_f32_e32 v5, v0, v0
	v_lshlrev_b32_e32 v0, 16, v104
	v_fmac_f32_e32 v5, v0, v0
	v_and_b32_e32 v0, 0xffff0000, v104
	v_fmac_f32_e32 v5, v0, v0
	v_lshlrev_b32_e32 v0, 16, v105
	v_fmac_f32_e32 v5, v0, v0
	v_and_b32_e32 v0, 0xffff0000, v105
	v_fmac_f32_e32 v5, v0, v0
	v_lshlrev_b32_e32 v0, 16, v106
	v_fmac_f32_e32 v5, v0, v0
	v_and_b32_e32 v0, 0xffff0000, v106
	v_fmac_f32_e32 v5, v0, v0
	v_lshlrev_b32_e32 v0, 16, v107
	v_fmac_f32_e32 v5, v0, v0
	v_and_b32_e32 v0, 0xffff0000, v107
	v_fmac_f32_e32 v5, v0, v0
	v_lshlrev_b32_e32 v0, 16, v108
	v_fmac_f32_e32 v5, v0, v0
	v_and_b32_e32 v0, 0xffff0000, v108
	v_fmac_f32_e32 v5, v0, v0
	v_lshlrev_b32_e32 v0, 16, v109
	v_fmac_f32_e32 v5, v0, v0
	v_and_b32_e32 v0, 0xffff0000, v109
	v_fmac_f32_e32 v5, v0, v0
	v_lshlrev_b32_e32 v0, 16, v110
	v_fmac_f32_e32 v5, v0, v0
	v_and_b32_e32 v0, 0xffff0000, v110
	v_fmac_f32_e32 v5, v0, v0
	v_lshlrev_b32_e32 v0, 16, v111
	v_fmac_f32_e32 v5, v0, v0
	v_and_b32_e32 v0, 0xffff0000, v111
	v_fmac_f32_e32 v5, v0, v0
	v_mov_b32_e32 v6, v5
	v_mov_b32_e32 v7, v5
	s_nop 1
	v_permlane32_swap_b32_e32 v6, v7
	s_and_saveexec_b64 s[4:5], vcc
	s_cbranch_execz .LBB0_314
	v_readlane_b32 s6, v255, 34
	s_add_u32 s6, s6, s26
	v_readlane_b32 s7, v255, 35
	s_addc_u32 s7, s7, 0
	s_add_u32 s6, s6, s25
	s_addc_u32 s7, s7, s19
	v_mov_b64_e32 v[0:1], s[6:7]
	s_movk_i32 s6, 0x3000
	v_mad_i64_i32 v[0:1], s[6:7], v4, s6, v[0:1]
	v_mov_b32_e32 v8, 0
	s_mov_b64 s[6:7], 0
	v_mov_b32_e32 v9, v4
.LBB0_312:
	global_load_dwordx4 v[20:23], v[0:1], off offset:-112
	global_load_dwordx4 v[24:27], v[0:1], off offset:-96
	global_load_dwordx4 v[28:31], v[0:1], off offset:-80
	global_load_dwordx4 v[32:35], v[0:1], off offset:-64
	global_load_dwordx4 v[36:39], v[0:1], off offset:-48
	global_load_dwordx4 v[40:43], v[0:1], off offset:-32
	global_load_dwordx4 v[44:47], v[0:1], off offset:-16
	global_load_dwordx4 v[48:51], v[0:1], off
	v_lshl_add_u64 v[0:1], v[0:1], 0, s[82:83]
	v_add_u32_e32 v9, 0x200, v9
	v_max_f32_e32 v8, v8, v8
	v_cmp_le_i32_e32 vcc, s23, v9
	s_or_b64 s[6:7], vcc, s[6:7]
	s_waitcnt vmcnt(7)
	v_lshlrev_b32_e32 v14, 16, v20
	v_and_b32_e32 v10, 0xffff0000, v20
	v_mul_f32_e32 v10, v10, v10
	v_fmac_f32_e32 v10, v14, v14
	v_lshlrev_b32_e32 v11, 16, v21
	v_fmac_f32_e32 v10, v11, v11
	v_and_b32_e32 v11, 0xffff0000, v21
	v_fmac_f32_e32 v10, v11, v11
	v_lshlrev_b32_e32 v11, 16, v22
	v_fmac_f32_e32 v10, v11, v11
	v_and_b32_e32 v11, 0xffff0000, v22
	v_fmac_f32_e32 v10, v11, v11
	v_lshlrev_b32_e32 v11, 16, v23
	v_fmac_f32_e32 v10, v11, v11
	v_and_b32_e32 v11, 0xffff0000, v23
	v_fmac_f32_e32 v10, v11, v11
	s_waitcnt vmcnt(6)
	v_lshlrev_b32_e32 v11, 16, v24
	v_fmac_f32_e32 v10, v11, v11
	v_and_b32_e32 v11, 0xffff0000, v24
	v_fmac_f32_e32 v10, v11, v11
	v_lshlrev_b32_e32 v11, 16, v25
	v_fmac_f32_e32 v10, v11, v11
	v_and_b32_e32 v11, 0xffff0000, v25
	v_fmac_f32_e32 v10, v11, v11
	v_lshlrev_b32_e32 v11, 16, v26
	v_fmac_f32_e32 v10, v11, v11
	v_and_b32_e32 v11, 0xffff0000, v26
	v_fmac_f32_e32 v10, v11, v11
	v_lshlrev_b32_e32 v11, 16, v27
	v_fmac_f32_e32 v10, v11, v11
	v_and_b32_e32 v11, 0xffff0000, v27
	v_fmac_f32_e32 v10, v11, v11
	s_waitcnt vmcnt(5)
	v_lshlrev_b32_e32 v11, 16, v28
	v_fmac_f32_e32 v10, v11, v11
	v_and_b32_e32 v11, 0xffff0000, v28
	v_fmac_f32_e32 v10, v11, v11
	v_lshlrev_b32_e32 v11, 16, v29
	v_fmac_f32_e32 v10, v11, v11
	v_and_b32_e32 v11, 0xffff0000, v29
	v_fmac_f32_e32 v10, v11, v11
	v_lshlrev_b32_e32 v11, 16, v30
	v_fmac_f32_e32 v10, v11, v11
	v_and_b32_e32 v11, 0xffff0000, v30
	v_fmac_f32_e32 v10, v11, v11
	v_lshlrev_b32_e32 v11, 16, v31
	v_fmac_f32_e32 v10, v11, v11
	v_and_b32_e32 v11, 0xffff0000, v31
	v_fmac_f32_e32 v10, v11, v11
	s_waitcnt vmcnt(4)
	v_lshlrev_b32_e32 v11, 16, v32
	v_fmac_f32_e32 v10, v11, v11
	v_and_b32_e32 v11, 0xffff0000, v32
	v_fmac_f32_e32 v10, v11, v11
	v_lshlrev_b32_e32 v11, 16, v33
	v_fmac_f32_e32 v10, v11, v11
	v_and_b32_e32 v11, 0xffff0000, v33
	v_fmac_f32_e32 v10, v11, v11
	v_lshlrev_b32_e32 v11, 16, v34
	v_fmac_f32_e32 v10, v11, v11
	v_and_b32_e32 v11, 0xffff0000, v34
	v_fmac_f32_e32 v10, v11, v11
	v_lshlrev_b32_e32 v11, 16, v35
	v_fmac_f32_e32 v10, v11, v11
	v_and_b32_e32 v11, 0xffff0000, v35
	v_fmac_f32_e32 v10, v11, v11
	s_waitcnt vmcnt(3)
	v_lshlrev_b32_e32 v11, 16, v36
	v_fmac_f32_e32 v10, v11, v11
	v_and_b32_e32 v11, 0xffff0000, v36
	v_fmac_f32_e32 v10, v11, v11
	v_lshlrev_b32_e32 v11, 16, v37
	v_fmac_f32_e32 v10, v11, v11
	v_and_b32_e32 v11, 0xffff0000, v37
	v_fmac_f32_e32 v10, v11, v11
	v_lshlrev_b32_e32 v11, 16, v38
	v_fmac_f32_e32 v10, v11, v11
	v_and_b32_e32 v11, 0xffff0000, v38
	v_fmac_f32_e32 v10, v11, v11
	v_lshlrev_b32_e32 v11, 16, v39
	v_fmac_f32_e32 v10, v11, v11
	v_and_b32_e32 v11, 0xffff0000, v39
	v_fmac_f32_e32 v10, v11, v11
	s_waitcnt vmcnt(2)
	v_lshlrev_b32_e32 v11, 16, v40
	v_fmac_f32_e32 v10, v11, v11
	v_and_b32_e32 v11, 0xffff0000, v40
	v_fmac_f32_e32 v10, v11, v11
	v_lshlrev_b32_e32 v11, 16, v41
	v_fmac_f32_e32 v10, v11, v11
	v_and_b32_e32 v11, 0xffff0000, v41
	v_fmac_f32_e32 v10, v11, v11
	v_lshlrev_b32_e32 v11, 16, v42
	v_fmac_f32_e32 v10, v11, v11
	v_and_b32_e32 v11, 0xffff0000, v42
	v_fmac_f32_e32 v10, v11, v11
	v_lshlrev_b32_e32 v11, 16, v43
	v_fmac_f32_e32 v10, v11, v11
	v_and_b32_e32 v11, 0xffff0000, v43
	v_fmac_f32_e32 v10, v11, v11
	s_waitcnt vmcnt(1)
	v_lshlrev_b32_e32 v11, 16, v44
	v_fmac_f32_e32 v10, v11, v11
	v_and_b32_e32 v11, 0xffff0000, v44
	v_fmac_f32_e32 v10, v11, v11
	v_lshlrev_b32_e32 v11, 16, v45
	v_fmac_f32_e32 v10, v11, v11
	v_and_b32_e32 v11, 0xffff0000, v45
	v_fmac_f32_e32 v10, v11, v11
	v_and_b32_e32 v15, 0xffff0000, v46
	v_lshlrev_b32_e32 v14, 16, v46
	v_mul_f32_e32 v14, v14, v14
	v_mul_f32_e32 v15, v15, v15
	s_nop 0
	v_add_f32_e32 v10, v14, v10
	v_add_f32_e32 v10, v15, v10
	v_and_b32_e32 v15, 0xffff0000, v47
	v_lshlrev_b32_e32 v14, 16, v47
	v_mul_f32_e32 v14, v14, v14
	v_mul_f32_e32 v15, v15, v15
	s_nop 0
	v_add_f32_e32 v10, v14, v10
	v_add_f32_e32 v10, v15, v10
	s_waitcnt vmcnt(0)
	v_and_b32_e32 v15, 0xffff0000, v48
	v_lshlrev_b32_e32 v14, 16, v48
	v_mul_f32_e32 v14, v14, v14
	v_mul_f32_e32 v15, v15, v15
	s_nop 0
	v_add_f32_e32 v10, v14, v10
	v_add_f32_e32 v10, v15, v10
	v_and_b32_e32 v15, 0xffff0000, v49
	v_lshlrev_b32_e32 v14, 16, v49
	v_mul_f32_e32 v14, v14, v14
	v_mul_f32_e32 v15, v15, v15
	s_nop 0
	v_add_f32_e32 v10, v14, v10
	v_add_f32_e32 v10, v15, v10
	v_and_b32_e32 v15, 0xffff0000, v50
	v_lshlrev_b32_e32 v14, 16, v50
	v_mul_f32_e32 v14, v14, v14
	v_mul_f32_e32 v15, v15, v15
	s_nop 0
	v_add_f32_e32 v10, v14, v10
	v_add_f32_e32 v10, v15, v10
	v_and_b32_e32 v15, 0xffff0000, v51
	v_lshlrev_b32_e32 v14, 16, v51
	v_mul_f32_e32 v14, v14, v14
	v_mul_f32_e32 v15, v15, v15
	s_nop 0
	v_add_f32_e32 v10, v14, v10
	v_add_f32_e32 v10, v15, v10
	v_max_f32_e32 v8, v8, v10
	s_andn2_b64 exec, exec, s[6:7]
	s_cbranch_execnz .LBB0_312
	s_or_b64 exec, exec, s[6:7]

.LBB0_322:
	s_add_i32 s4, s31, -1
	s_add_i32 s5, s76, 1
	s_and_b32 s77, s4, 1
	s_cmp_gt_i32 s5, s74
	s_cbranch_scc1 .LBB0_329
	s_cmp_eq_u32 s77, 0
	v_add_u32_e32 v128, v148, v149
	v_cvt_f32_i32_e32 v64, v128
	s_cselect_b64 s[14:15], -1, 0
	s_and_b64 s[4:5], s[14:15], exec
	s_cselect_b32 s4, 0, 0x2400
	v_add_u32_e32 v135, s4, v147
	s_mov_b32 s4, 2.0
	v_mul_f32_e64 v134, -v190, v64
	s_mov_b32 s5, 0x40400000
	v_fma_f32 v82, v192, s4, v134
	v_fma_f32 v83, v193, s5, v134
	s_mov_b32 s4, 0x41000000
	s_mov_b32 s5, 0x41100000
	v_fma_f32 v84, v192, s4, v134
	v_fma_f32 v85, v193, s5, v134
	s_mov_b32 s4, 0x41200000
	s_mov_b32 s5, 0x41300000
	v_fma_f32 v86, v192, s4, v134
	v_fma_f32 v87, v193, s5, v134
	s_mov_b32 s4, 0x41800000
	s_mov_b32 s5, 0x41880000
	v_fma_f32 v88, v192, s4, v134
	v_fma_f32 v89, v193, s5, v134
	s_mov_b32 s4, 0x41900000
	s_mov_b32 s5, 0x41980000
	v_fma_f32 v90, v192, s4, v134
	v_fma_f32 v91, v193, s5, v134
	s_mov_b32 s4, 0x41c00000
	s_mov_b32 s5, 0x41c80000
	v_fma_f32 v92, v192, s4, v134
	v_fma_f32 v93, v193, s5, v134
	s_mov_b32 s4, 0x41d00000
	s_mov_b32 s5, 0x41d80000
	v_fma_f32 v94, v192, s4, v134
	v_fma_f32 v95, v193, s5, v134
	s_mov_b32 s4, 0x42680000
	v_mov_b32_e32 v191, v190
	s_mov_b32 s5, 0x426c0000
	v_fma_f32 v78, v190, s4, v134
	v_fma_f32 v79, v191, s5, v134
	s_mov_b32 s4, 0x42600000
	s_mov_b32 s5, 0x42640000
	v_fma_f32 v76, v190, s4, v134
	v_fma_f32 v77, v191, s5, v134
	s_mov_b32 s4, 0x42480000
	v_fma_f32 v81, -v190, v64, v190
	ds_read_b128 v[64:67], v135
	ds_read_b128 v[130:133], v135 offset:4608
	s_mov_b32 s5, 0x424c0000
	v_fma_f32 v74, v190, s4, v134
	v_fma_f32 v75, v191, s5, v134
	s_mov_b32 s4, 0x42400000
	s_mov_b32 s5, 0x42440000
	v_fma_f32 v72, v190, s4, v134
	v_fma_f32 v73, v191, s5, v134
	s_mov_b32 s4, 0x42280000
	s_mov_b32 s5, 0x422c0000
	v_fma_f32 v70, v190, s4, v134
	v_fma_f32 v71, v191, s5, v134
	s_mov_b32 s4, 0x42200000
	s_mov_b32 s5, 0x42240000
	v_mov_b32_e32 v80, v134
	v_fma_f32 v68, v190, s4, v134
	v_fma_f32 v69, v191, s5, v134
	s_mov_b32 s4, 0x42080000
	v_fmac_f32_e32 v80, 0, v190
	s_mov_b32 s5, 0x420c0000
	v_cmp_ge_i32_e32 vcc, s21, v150
	s_waitcnt lgkmcnt(1)
	v_mfma_f32_32x32x16_bf16 v[80:95], v[64:67], v[96:99], v[80:95]
	v_fma_f32 v66, v190, s4, v134
	v_fma_f32 v67, v191, s5, v134
	s_mov_b32 s4, 0x42000000
	s_mov_b32 s5, 0x42040000
	v_fma_f32 v64, v194, s4, v134
	v_fma_f32 v65, v195, s5, v134
	s_and_b64 vcc, exec, vcc
	s_waitcnt lgkmcnt(0)
	v_mfma_f32_32x32x16_bf16 v[64:79], v[130:133], v[96:99], v[64:79]
	ds_read_b128 v[130:133], v135 offset:32
	ds_read_b128 v[136:139], v135 offset:4640
	ds_read_b128 v[140:143], v135 offset:64
	ds_read_b128 v[152:155], v135 offset:4672
	s_waitcnt lgkmcnt(3)
	v_mfma_f32_32x32x16_bf16 v[80:95], v[130:133], v[100:103], v[80:95]
	ds_read_b128 v[130:133], v135 offset:96
	s_waitcnt lgkmcnt(3)
	v_mfma_f32_32x32x16_bf16 v[64:79], v[136:139], v[100:103], v[64:79]
	ds_read_b128 v[136:139], v135 offset:4704
	s_waitcnt lgkmcnt(3)
	v_mfma_f32_32x32x16_bf16 v[80:95], v[140:143], v[104:107], v[80:95]
	s_waitcnt lgkmcnt(2)
	v_mfma_f32_32x32x16_bf16 v[64:79], v[152:155], v[104:107], v[64:79]
	s_waitcnt lgkmcnt(1)
	v_mfma_f32_32x32x16_bf16 v[80:95], v[130:133], v[108:111], v[80:95]
	s_waitcnt lgkmcnt(0)
	v_mfma_f32_32x32x16_bf16 v[64:79], v[136:139], v[108:111], v[64:79]
	s_cbranch_vccnz .LBB0_325
	v_cmp_gt_i32_e32 vcc, 0, v128
	v_cmp_gt_i32_e64 s[4:5], 1, v128
	s_and_b64 vcc, s[4:5], vcc
	s_nop 4
	v_cndmask_b32_e32 v80, v80, v252, vcc
	v_cmp_lt_i32_e32 vcc, 1, v128
	v_cmp_gt_i32_e64 s[60:61], 58, v128
	v_cmp_gt_i32_e64 s[62:63], 59, v128
	v_cndmask_b32_e32 v82, v252, v82, vcc
	v_cmp_lt_i32_e32 vcc, 2, v128
	v_cmp_gt_i32_e64 s[58:59], 57, v128
	s_and_b64 s[60:61], s[62:63], s[60:61]
	v_cndmask_b32_e32 v83, v252, v83, vcc
	v_cmp_lt_i32_e32 vcc, 7, v128
	v_cmp_gt_i32_e64 s[56:57], 56, v128
	s_and_b64 s[58:59], s[60:61], s[58:59]
	v_cndmask_b32_e32 v84, v252, v84, vcc
	v_cmp_lt_i32_e32 vcc, 8, v128
	v_cmp_gt_i32_e64 s[54:55], 51, v128
	s_and_b64 s[56:57], s[58:59], s[56:57]
	v_cndmask_b32_e32 v85, v252, v85, vcc
	v_cmp_lt_i32_e32 vcc, 9, v128
	v_cmp_gt_i32_e64 s[52:53], 50, v128
	s_and_b64 s[54:55], s[56:57], s[54:55]
	v_cndmask_b32_e32 v86, v252, v86, vcc
	v_cmp_lt_i32_e32 vcc, 10, v128
	v_cmp_gt_i32_e64 s[50:51], 49, v128
	s_and_b64 s[52:53], s[54:55], s[52:53]
	v_cndmask_b32_e32 v87, v252, v87, vcc
	v_cmp_lt_i32_e32 vcc, 15, v128
	v_cmp_gt_i32_e64 s[48:49], 48, v128
	s_and_b64 s[50:51], s[52:53], s[50:51]
	v_cndmask_b32_e32 v88, v252, v88, vcc
	v_cmp_lt_i32_e32 vcc, 16, v128
	v_cmp_gt_i32_e64 s[46:47], 43, v128
	s_and_b64 s[48:49], s[50:51], s[48:49]
	v_cndmask_b32_e32 v89, v252, v89, vcc
	v_cmp_lt_i32_e32 vcc, 17, v128
	v_cmp_gt_i32_e64 s[44:45], 42, v128
	s_and_b64 s[46:47], s[48:49], s[46:47]
	v_cndmask_b32_e32 v90, v252, v90, vcc
	v_cmp_lt_i32_e32 vcc, 18, v128
	v_cmp_gt_i32_e64 s[42:43], 41, v128
	s_and_b64 s[44:45], s[46:47], s[44:45]
	v_cndmask_b32_e32 v91, v252, v91, vcc
	v_cmp_lt_i32_e32 vcc, 23, v128
	v_cmp_gt_i32_e64 s[10:11], 40, v128
	s_and_b64 s[42:43], s[44:45], s[42:43]
	v_cndmask_b32_e32 v92, v252, v92, vcc
	v_cmp_lt_i32_e32 vcc, 24, v128
	v_cmp_gt_i32_e64 s[8:9], 35, v128
	s_and_b64 s[10:11], s[42:43], s[10:11]
	v_cndmask_b32_e32 v93, v252, v93, vcc
	v_cmp_lt_i32_e32 vcc, 25, v128
	v_cmp_gt_i32_e64 s[6:7], 34, v128
	s_and_b64 s[8:9], s[10:11], s[8:9]
	v_cndmask_b32_e64 v81, v81, v252, s[4:5]
	v_cndmask_b32_e32 v94, v252, v94, vcc
	v_cmp_lt_i32_e32 vcc, 26, v128
	v_cmp_gt_i32_e64 s[4:5], 33, v128
	s_and_b64 s[6:7], s[8:9], s[6:7]
	v_cndmask_b32_e32 v130, v252, v95, vcc
	v_cmp_gt_i32_e32 vcc, 32, v128
	s_and_b64 s[4:5], s[6:7], s[4:5]
	s_and_b64 vcc, s[4:5], vcc
	v_cndmask_b32_e64 v79, v79, v252, s[62:63]
	v_cndmask_b32_e64 v78, v78, v252, s[60:61]
	v_cndmask_b32_e64 v77, v77, v252, s[58:59]
	v_cndmask_b32_e64 v76, v76, v252, s[56:57]
	v_cndmask_b32_e64 v75, v75, v252, s[54:55]
	v_cndmask_b32_e64 v74, v74, v252, s[52:53]
	v_cndmask_b32_e64 v73, v73, v252, s[50:51]
	v_cndmask_b32_e64 v72, v72, v252, s[48:49]
	v_cndmask_b32_e64 v71, v71, v252, s[46:47]
	v_cndmask_b32_e64 v70, v70, v252, s[44:45]
	v_cndmask_b32_e64 v69, v69, v252, s[42:43]
	v_cndmask_b32_e64 v68, v68, v252, s[10:11]
	v_cndmask_b32_e64 v67, v67, v252, s[8:9]
	v_cndmask_b32_e64 v66, v66, v252, s[6:7]
	v_cndmask_b32_e64 v65, v65, v252, s[4:5]
	v_cndmask_b32_e32 v95, v95, v130, vcc
	v_cndmask_b32_e32 v64, v64, v252, vcc
.LBB0_325:
	s_nop 7
	v_max_f32_e32 v128, v81, v81
	v_max_f32_e32 v130, v80, v80
	v_max_f32_e32 v128, v130, v128
	v_max3_f32 v128, v128, v82, v83
	v_max3_f32 v128, v128, v84, v85
	v_max3_f32 v128, v128, v86, v87
	v_max3_f32 v128, v128, v88, v89
	v_max3_f32 v128, v128, v90, v91
	v_max3_f32 v128, v128, v92, v93
	v_max3_f32 v128, v128, v94, v95
	v_max3_f32 v128, v128, v64, v65
	v_max3_f32 v128, v128, v66, v67
	v_max3_f32 v128, v128, v68, v69
	v_max3_f32 v128, v128, v70, v71
	v_max3_f32 v128, v128, v72, v73
	v_max3_f32 v128, v128, v74, v75
	v_max3_f32 v128, v128, v76, v77
	v_max3_f32 v128, v128, v78, v79
	v_mov_b32_e32 v130, v128
	v_mov_b32_e32 v131, v128
	s_nop 1
	v_permlane32_swap_b32_e32 v130, v131
	v_cndmask_b32_e64 v130, v130, v131, s[38:39]
	v_max3_f32 v130, v151, v128, v130
	v_cmp_neq_f32_e32 vcc, s2, v130
	s_nop 1
	v_cndmask_b32_e32 v131, 0, v130, vcc
	v_sub_f32_e32 v128, v151, v131
	v_exp_f32_e32 v128, v128
	s_nop 0
	v_cmp_eq_f32_e32 vcc, 1.0, v128
	s_cmp_eq_u64 vcc, exec
	s_cbranch_scc1 .LBB0_327
	v_mul_f32_e32 v62, v62, v128
	v_mul_f32_e32 v63, v63, v128
	v_mul_f32_e32 v60, v60, v128
	v_mul_f32_e32 v61, v61, v128
	v_mul_f32_e32 v58, v58, v128
	v_mul_f32_e32 v59, v59, v128
	v_mul_f32_e32 v56, v56, v128
	v_mul_f32_e32 v57, v57, v128
	v_mul_f32_e32 v54, v54, v128
	v_mul_f32_e32 v55, v55, v128
	v_mul_f32_e32 v52, v52, v128
	v_mul_f32_e32 v53, v53, v128
	v_mul_f32_e32 v50, v50, v128
	v_mul_f32_e32 v51, v51, v128
	v_mul_f32_e32 v48, v48, v128
	v_mul_f32_e32 v49, v49, v128
	v_mul_f32_e32 v46, v46, v128
	v_mul_f32_e32 v47, v47, v128
	v_mul_f32_e32 v44, v44, v128
	v_mul_f32_e32 v45, v45, v128
	v_mul_f32_e32 v42, v42, v128
	v_mul_f32_e32 v43, v43, v128
	v_mul_f32_e32 v40, v40, v128
	v_mul_f32_e32 v41, v41, v128
	v_mul_f32_e32 v38, v38, v128
	v_mul_f32_e32 v39, v39, v128
	v_mul_f32_e32 v36, v36, v128
	v_mul_f32_e32 v37, v37, v128
	v_mul_f32_e32 v34, v34, v128
	v_mul_f32_e32 v35, v35, v128
	v_mul_f32_e32 v32, v32, v128
	v_mul_f32_e32 v33, v33, v128
	v_mul_f32_e32 v30, v30, v128
	v_mul_f32_e32 v31, v31, v128
	v_mul_f32_e32 v28, v28, v128
	v_mul_f32_e32 v29, v29, v128
	v_mul_f32_e32 v26, v26, v128
	v_mul_f32_e32 v27, v27, v128
	v_mul_f32_e32 v24, v24, v128
	v_mul_f32_e32 v25, v25, v128
	v_mul_f32_e32 v22, v22, v128
	v_mul_f32_e32 v23, v23, v128
	v_mul_f32_e32 v20, v20, v128
	v_mul_f32_e32 v21, v21, v128
	v_mul_f32_e32 v18, v18, v128
	v_mul_f32_e32 v19, v19, v128
	v_mul_f32_e32 v16, v16, v128
	v_mul_f32_e32 v17, v17, v128
	v_mul_f32_e32 v14, v14, v128
	v_mul_f32_e32 v15, v15, v128
	v_mul_f32_e32 v12, v12, v128
	v_mul_f32_e32 v13, v13, v128
	v_mul_f32_e32 v10, v10, v128
	v_mul_f32_e32 v11, v11, v128
	v_mul_f32_e32 v8, v8, v128
	v_mul_f32_e32 v9, v9, v128
	v_mul_f32_e32 v6, v6, v128
	v_mul_f32_e32 v7, v7, v128
	v_mul_f32_e32 v4, v4, v128
	v_mul_f32_e32 v5, v5, v128
	v_mul_f32_e32 v2, v2, v128
	v_mul_f32_e32 v3, v3, v128
	v_mul_f32_e32 v0, v0, v128
	v_mul_f32_e32 v1, v1, v128

.LBB0_333:
	v_mov_b32_e32 v68, v241
	v_mov_b64_e32 v[64:65], s[64:65]
	v_readfirstlane_b32 s10, v68
	s_ashr_i32 s9, s10, 6
	s_lshl_b32 s8, s9, 5
	v_and_b32_e32 v66, 31, v68
	s_add_i32 s21, s8, s30
	v_bfe_u32 v67, v68, 5, 1
	v_or_b32_e32 v69, s21, v66
	s_movk_i32 s4, 0x3000
	v_mad_i64_i32 v[64:65], s[4:5], v69, s4, v[64:65]
	v_lshlrev_b32_e32 v128, 4, v67
	v_lshl_add_u64 v[64:65], v[64:65], 0, v[128:129]
	global_load_dwordx4 v[70:73], v[64:65], off offset:128
	global_load_dwordx4 v[84:87], v[64:65], off offset:160
	global_load_dwordx4 v[88:91], v[64:65], off offset:192
	global_load_dwordx4 v[92:95], v[64:65], off offset:224
	s_mov_b32 s4, 0x3e38aa3b
	v_mov_b32_e32 v203, v196
	v_mov_b32_e32 v204, v196
	s_nop 1
	v_permlane32_swap_b32_e32 v203, v204
	v_cmp_gt_i32_e32 vcc, s23, v68
	s_waitcnt vmcnt(3)
	v_and_b32_e32 v75, 0xffff0000, v70
	v_lshlrev_b32_e32 v74, 16, v70
	v_mul_f32_e32 v74, s4, v74
	v_mul_f32_e32 v75, s4, v75
	s_nop 0
	v_cvt_pk_bf16_f32 v162, v74, v75
	v_and_b32_e32 v75, 0xffff0000, v71
	v_lshlrev_b32_e32 v74, 16, v71
	v_mul_f32_e32 v70, s4, v74
	v_mul_f32_e32 v71, s4, v75
	s_nop 0
	v_cvt_pk_bf16_f32 v163, v70, v71
	v_and_b32_e32 v71, 0xffff0000, v72
	v_lshlrev_b32_e32 v70, 16, v72
	v_mul_f32_e32 v70, s4, v70
	v_mul_f32_e32 v71, s4, v71
	s_nop 0
	v_cvt_pk_bf16_f32 v164, v70, v71
	v_and_b32_e32 v71, 0xffff0000, v73
	v_lshlrev_b32_e32 v70, 16, v73
	v_mul_f32_e32 v70, s4, v70
	v_mul_f32_e32 v71, s4, v71
	s_nop 0
	v_cvt_pk_bf16_f32 v165, v70, v71
	s_waitcnt vmcnt(2)
	v_and_b32_e32 v75, 0xffff0000, v84
	v_lshlrev_b32_e32 v74, 16, v84
	v_mul_f32_e32 v74, s4, v74
	v_mul_f32_e32 v75, s4, v75
	s_nop 0
	v_cvt_pk_bf16_f32 v166, v74, v75
	v_and_b32_e32 v75, 0xffff0000, v85
	v_lshlrev_b32_e32 v74, 16, v85
	v_mul_f32_e32 v70, s4, v74
	v_mul_f32_e32 v71, s4, v75
	s_nop 0
	v_cvt_pk_bf16_f32 v167, v70, v71
	v_and_b32_e32 v71, 0xffff0000, v86
	v_lshlrev_b32_e32 v70, 16, v86
	v_mul_f32_e32 v70, s4, v70
	v_mul_f32_e32 v71, s4, v71
	s_nop 0
	v_cvt_pk_bf16_f32 v168, v70, v71
	v_and_b32_e32 v71, 0xffff0000, v87
	v_lshlrev_b32_e32 v70, 16, v87
	v_mul_f32_e32 v70, s4, v70
	v_mul_f32_e32 v71, s4, v71
	s_nop 0
	v_cvt_pk_bf16_f32 v169, v70, v71
	s_waitcnt vmcnt(1)
	v_and_b32_e32 v75, 0xffff0000, v88
	v_lshlrev_b32_e32 v74, 16, v88
	v_mul_f32_e32 v74, s4, v74
	v_mul_f32_e32 v75, s4, v75
	s_nop 0
	v_cvt_pk_bf16_f32 v170, v74, v75
	v_and_b32_e32 v75, 0xffff0000, v89
	v_lshlrev_b32_e32 v74, 16, v89
	v_mul_f32_e32 v70, s4, v74
	v_mul_f32_e32 v71, s4, v75
	s_nop 0
	v_cvt_pk_bf16_f32 v171, v70, v71
	v_and_b32_e32 v71, 0xffff0000, v90
	v_lshlrev_b32_e32 v70, 16, v90
	v_mul_f32_e32 v70, s4, v70
	v_mul_f32_e32 v71, s4, v71
	s_nop 0
	v_cvt_pk_bf16_f32 v172, v70, v71
	v_and_b32_e32 v71, 0xffff0000, v91
	v_lshlrev_b32_e32 v70, 16, v91
	v_mul_f32_e32 v70, s4, v70
	v_mul_f32_e32 v71, s4, v71
	s_nop 0
	v_cvt_pk_bf16_f32 v173, v70, v71
	s_waitcnt vmcnt(0)
	v_and_b32_e32 v65, 0xffff0000, v92
	v_lshlrev_b32_e32 v64, 16, v92
	v_mul_f32_e32 v64, s4, v64
	v_mul_f32_e32 v65, s4, v65
	s_nop 0
	v_cvt_pk_bf16_f32 v174, v64, v65
	v_and_b32_e32 v65, 0xffff0000, v93
	v_lshlrev_b32_e32 v64, 16, v93
	v_mul_f32_e32 v64, s4, v64
	v_mul_f32_e32 v65, s4, v65
	s_nop 0
	v_cvt_pk_bf16_f32 v175, v64, v65
	v_and_b32_e32 v65, 0xffff0000, v94
	v_lshlrev_b32_e32 v64, 16, v94
	v_mul_f32_e32 v64, s4, v64
	v_mul_f32_e32 v65, s4, v65
	v_mov_b32_e32 v72, 0
	v_cvt_pk_bf16_f32 v176, v64, v65
	v_and_b32_e32 v65, 0xffff0000, v95
	v_lshlrev_b32_e32 v64, 16, v95
	v_mul_f32_e32 v64, s4, v64
	v_mul_f32_e32 v65, s4, v65
	s_nop 0
	v_cvt_pk_bf16_f32 v177, v64, v65
	v_and_b32_e32 v65, 0xffff0000, v162
	v_lshlrev_b32_e32 v64, 16, v162
	v_mul_f32_e32 v69, v65, v65
	v_fmac_f32_e32 v69, v64, v64
	v_lshlrev_b32_e32 v64, 16, v163
	v_fmac_f32_e32 v69, v64, v64
	v_and_b32_e32 v64, 0xffff0000, v163
	v_fmac_f32_e32 v69, v64, v64
	v_lshlrev_b32_e32 v64, 16, v164
	v_fmac_f32_e32 v69, v64, v64
	v_and_b32_e32 v64, 0xffff0000, v164
	v_fmac_f32_e32 v69, v64, v64
	v_lshlrev_b32_e32 v64, 16, v165
	v_fmac_f32_e32 v69, v64, v64
	v_and_b32_e32 v64, 0xffff0000, v165
	v_fmac_f32_e32 v69, v64, v64
	v_lshlrev_b32_e32 v64, 16, v166
	v_fmac_f32_e32 v69, v64, v64
	v_and_b32_e32 v64, 0xffff0000, v166
	v_fmac_f32_e32 v69, v64, v64
	v_lshlrev_b32_e32 v64, 16, v167
	v_fmac_f32_e32 v69, v64, v64
	v_and_b32_e32 v64, 0xffff0000, v167
	v_fmac_f32_e32 v69, v64, v64
	v_lshlrev_b32_e32 v64, 16, v168
	v_fmac_f32_e32 v69, v64, v64
	v_and_b32_e32 v64, 0xffff0000, v168
	v_fmac_f32_e32 v69, v64, v64
	v_lshlrev_b32_e32 v64, 16, v169
	v_fmac_f32_e32 v69, v64, v64
	v_and_b32_e32 v64, 0xffff0000, v169
	v_fmac_f32_e32 v69, v64, v64
	v_lshlrev_b32_e32 v64, 16, v170
	v_fmac_f32_e32 v69, v64, v64
	v_and_b32_e32 v64, 0xffff0000, v170
	v_fmac_f32_e32 v69, v64, v64
	v_lshlrev_b32_e32 v64, 16, v171
	v_fmac_f32_e32 v69, v64, v64
	v_and_b32_e32 v64, 0xffff0000, v171
	v_fmac_f32_e32 v69, v64, v64
	v_lshlrev_b32_e32 v64, 16, v172
	v_fmac_f32_e32 v69, v64, v64
	v_and_b32_e32 v64, 0xffff0000, v172
	v_fmac_f32_e32 v69, v64, v64
	v_lshlrev_b32_e32 v64, 16, v173
	v_fmac_f32_e32 v69, v64, v64
	v_and_b32_e32 v64, 0xffff0000, v173
	v_fmac_f32_e32 v69, v64, v64
	v_lshlrev_b32_e32 v64, 16, v174
	v_fmac_f32_e32 v69, v64, v64
	v_and_b32_e32 v64, 0xffff0000, v174
	v_fmac_f32_e32 v69, v64, v64
	v_lshlrev_b32_e32 v64, 16, v175
	v_fmac_f32_e32 v69, v64, v64
	v_and_b32_e32 v64, 0xffff0000, v175
	v_fmac_f32_e32 v69, v64, v64
	v_lshlrev_b32_e32 v64, 16, v176
	v_fmac_f32_e32 v69, v64, v64
	v_and_b32_e32 v64, 0xffff0000, v176
	v_fmac_f32_e32 v69, v64, v64
	v_lshlrev_b32_e32 v64, 16, v177
	v_fmac_f32_e32 v69, v64, v64
	v_and_b32_e32 v64, 0xffff0000, v177
	v_fmac_f32_e32 v69, v64, v64
	v_mov_b32_e32 v70, v69
	v_mov_b32_e32 v71, v69
	s_nop 1
	v_permlane32_swap_b32_e32 v70, v71
	s_and_saveexec_b64 s[4:5], vcc
	s_cbranch_execz .LBB0_337
	v_readlane_b32 s6, v255, 36
	s_add_u32 s6, s6, s26
	v_readlane_b32 s7, v255, 37
	s_addc_u32 s7, s7, 0
	s_add_u32 s6, s6, s25
	s_addc_u32 s7, s7, s19
	v_mov_b64_e32 v[64:65], s[6:7]
	s_movk_i32 s6, 0x3000
	v_mad_i64_i32 v[64:65], s[6:7], v68, s6, v[64:65]
	v_mov_b32_e32 v72, 0
	s_mov_b64 s[6:7], 0
	v_mov_b32_e32 v73, v68
.LBB0_335:
	global_load_dwordx4 v[96:99], v[64:65], off offset:-112
	global_load_dwordx4 v[100:103], v[64:65], off offset:-96
	global_load_dwordx4 v[104:107], v[64:65], off offset:-80
	global_load_dwordx4 v[108:111], v[64:65], off offset:-64
	global_load_dwordx4 v[112:115], v[64:65], off offset:-48
	global_load_dwordx4 v[116:119], v[64:65], off offset:-32
	global_load_dwordx4 v[120:123], v[64:65], off offset:-16
	global_load_dwordx4 v[124:127], v[64:65], off
	v_lshl_add_u64 v[64:65], v[64:65], 0, s[82:83]
	v_add_u32_e32 v73, 0x200, v73
	v_max_f32_e32 v72, v72, v72
	v_cmp_le_i32_e32 vcc, s23, v73
	s_or_b64 s[6:7], vcc, s[6:7]
	s_waitcnt vmcnt(7)
	v_lshlrev_b32_e32 v78, 16, v96
	v_and_b32_e32 v74, 0xffff0000, v96
	v_mul_f32_e32 v74, v74, v74
	v_fmac_f32_e32 v74, v78, v78
	v_lshlrev_b32_e32 v75, 16, v97
	v_fmac_f32_e32 v74, v75, v75
	v_and_b32_e32 v75, 0xffff0000, v97
	v_fmac_f32_e32 v74, v75, v75
	v_lshlrev_b32_e32 v75, 16, v98
	v_fmac_f32_e32 v74, v75, v75
	v_and_b32_e32 v75, 0xffff0000, v98
	v_fmac_f32_e32 v74, v75, v75
	v_lshlrev_b32_e32 v75, 16, v99
	v_fmac_f32_e32 v74, v75, v75
	v_and_b32_e32 v75, 0xffff0000, v99
	v_fmac_f32_e32 v74, v75, v75
	s_waitcnt vmcnt(6)
	v_lshlrev_b32_e32 v75, 16, v100
	v_fmac_f32_e32 v74, v75, v75
	v_and_b32_e32 v75, 0xffff0000, v100
	v_fmac_f32_e32 v74, v75, v75
	v_lshlrev_b32_e32 v75, 16, v101
	v_fmac_f32_e32 v74, v75, v75
	v_and_b32_e32 v75, 0xffff0000, v101
	v_fmac_f32_e32 v74, v75, v75
	v_lshlrev_b32_e32 v75, 16, v102
	v_fmac_f32_e32 v74, v75, v75
	v_and_b32_e32 v75, 0xffff0000, v102
	v_fmac_f32_e32 v74, v75, v75
	v_lshlrev_b32_e32 v75, 16, v103
	v_fmac_f32_e32 v74, v75, v75
	v_and_b32_e32 v75, 0xffff0000, v103
	v_fmac_f32_e32 v74, v75, v75
	s_waitcnt vmcnt(5)
	v_lshlrev_b32_e32 v75, 16, v104
	v_fmac_f32_e32 v74, v75, v75
	v_and_b32_e32 v75, 0xffff0000, v104
	v_fmac_f32_e32 v74, v75, v75
	v_lshlrev_b32_e32 v75, 16, v105
	v_fmac_f32_e32 v74, v75, v75
	v_and_b32_e32 v75, 0xffff0000, v105
	v_fmac_f32_e32 v74, v75, v75
	v_lshlrev_b32_e32 v75, 16, v106
	v_fmac_f32_e32 v74, v75, v75
	v_and_b32_e32 v75, 0xffff0000, v106
	v_fmac_f32_e32 v74, v75, v75
	v_lshlrev_b32_e32 v75, 16, v107
	v_fmac_f32_e32 v74, v75, v75
	v_and_b32_e32 v75, 0xffff0000, v107
	v_fmac_f32_e32 v74, v75, v75
	s_waitcnt vmcnt(4)
	v_lshlrev_b32_e32 v75, 16, v108
	v_fmac_f32_e32 v74, v75, v75
	v_and_b32_e32 v75, 0xffff0000, v108
	v_fmac_f32_e32 v74, v75, v75
	v_lshlrev_b32_e32 v75, 16, v109
	v_fmac_f32_e32 v74, v75, v75
	v_and_b32_e32 v75, 0xffff0000, v109
	v_fmac_f32_e32 v74, v75, v75
	v_lshlrev_b32_e32 v75, 16, v110
	v_fmac_f32_e32 v74, v75, v75
	v_and_b32_e32 v75, 0xffff0000, v110
	v_fmac_f32_e32 v74, v75, v75
	v_lshlrev_b32_e32 v75, 16, v111
	v_fmac_f32_e32 v74, v75, v75
	v_and_b32_e32 v75, 0xffff0000, v111
	v_fmac_f32_e32 v74, v75, v75
	s_waitcnt vmcnt(3)
	v_lshlrev_b32_e32 v75, 16, v112
	v_fmac_f32_e32 v74, v75, v75
	v_and_b32_e32 v75, 0xffff0000, v112
	v_fmac_f32_e32 v74, v75, v75
	v_lshlrev_b32_e32 v75, 16, v113
	v_fmac_f32_e32 v74, v75, v75
	v_and_b32_e32 v75, 0xffff0000, v113
	v_fmac_f32_e32 v74, v75, v75
	v_lshlrev_b32_e32 v75, 16, v114
	v_fmac_f32_e32 v74, v75, v75
	v_and_b32_e32 v75, 0xffff0000, v114
	v_fmac_f32_e32 v74, v75, v75
	v_lshlrev_b32_e32 v75, 16, v115
	v_fmac_f32_e32 v74, v75, v75
	v_and_b32_e32 v75, 0xffff0000, v115
	v_fmac_f32_e32 v74, v75, v75
	s_waitcnt vmcnt(2)
	v_lshlrev_b32_e32 v75, 16, v116
	v_fmac_f32_e32 v74, v75, v75
	v_and_b32_e32 v75, 0xffff0000, v116
	v_fmac_f32_e32 v74, v75, v75
	v_lshlrev_b32_e32 v75, 16, v117
	v_fmac_f32_e32 v74, v75, v75
	v_and_b32_e32 v75, 0xffff0000, v117
	v_fmac_f32_e32 v74, v75, v75
	v_lshlrev_b32_e32 v75, 16, v118
	v_fmac_f32_e32 v74, v75, v75
	v_and_b32_e32 v75, 0xffff0000, v118
	v_fmac_f32_e32 v74, v75, v75
	v_lshlrev_b32_e32 v75, 16, v119
	v_fmac_f32_e32 v74, v75, v75
	v_and_b32_e32 v75, 0xffff0000, v119
	v_fmac_f32_e32 v74, v75, v75
	s_waitcnt vmcnt(1)
	v_lshlrev_b32_e32 v75, 16, v120
	v_fmac_f32_e32 v74, v75, v75
	v_and_b32_e32 v75, 0xffff0000, v120
	v_fmac_f32_e32 v74, v75, v75
	v_lshlrev_b32_e32 v75, 16, v121
	v_fmac_f32_e32 v74, v75, v75
	v_and_b32_e32 v75, 0xffff0000, v121
	v_fmac_f32_e32 v74, v75, v75
	v_and_b32_e32 v79, 0xffff0000, v122
	v_lshlrev_b32_e32 v78, 16, v122
	v_mul_f32_e32 v78, v78, v78
	v_mul_f32_e32 v79, v79, v79
	s_nop 0
	v_add_f32_e32 v74, v78, v74
	v_add_f32_e32 v74, v79, v74
	v_and_b32_e32 v79, 0xffff0000, v123
	v_lshlrev_b32_e32 v78, 16, v123
	v_mul_f32_e32 v78, v78, v78
	v_mul_f32_e32 v79, v79, v79
	s_nop 0
	v_add_f32_e32 v74, v78, v74
	v_add_f32_e32 v74, v79, v74
	s_waitcnt vmcnt(0)
	v_and_b32_e32 v79, 0xffff0000, v124
	v_lshlrev_b32_e32 v78, 16, v124
	v_mul_f32_e32 v78, v78, v78
	v_mul_f32_e32 v79, v79, v79
	s_nop 0
	v_add_f32_e32 v74, v78, v74
	v_add_f32_e32 v74, v79, v74
	v_and_b32_e32 v79, 0xffff0000, v125
	v_lshlrev_b32_e32 v78, 16, v125
	v_mul_f32_e32 v78, v78, v78
	v_mul_f32_e32 v79, v79, v79
	s_nop 0
	v_add_f32_e32 v74, v78, v74
	v_add_f32_e32 v74, v79, v74
	v_and_b32_e32 v79, 0xffff0000, v126
	v_lshlrev_b32_e32 v78, 16, v126
	v_mul_f32_e32 v78, v78, v78
	v_mul_f32_e32 v79, v79, v79
	s_nop 0
	v_add_f32_e32 v74, v78, v74
	v_add_f32_e32 v74, v79, v74
	v_and_b32_e32 v79, 0xffff0000, v127
	v_lshlrev_b32_e32 v78, 16, v127
	v_mul_f32_e32 v78, v78, v78
	v_mul_f32_e32 v79, v79, v79
	s_nop 0
	v_add_f32_e32 v74, v78, v74
	v_add_f32_e32 v74, v79, v74
	v_max_f32_e32 v72, v72, v74
	s_andn2_b64 exec, exec, s[6:7]
	s_cbranch_execnz .LBB0_335
	s_or_b64 exec, exec, s[6:7]

.LBB0_345:
	s_add_i32 s4, s23, -1
	s_add_i32 s5, s18, 1
	s_and_b32 s24, s4, 1
	s_cmp_gt_i32 s5, s19
	s_cbranch_scc1 .LBB0_352
	s_cmp_eq_u32 s24, 0
	v_add_u32_e32 v128, v209, v210
	v_cvt_f32_i32_e32 v130, v128
	s_cselect_b64 s[14:15], -1, 0
	s_and_b64 s[4:5], s[14:15], exec
	s_cselect_b32 s4, 0, 0x2400
	v_add_u32_e32 v213, s4, v208
	s_mov_b32 s4, 2.0
	v_mul_f32_e64 v218, -v190, v130
	s_mov_b32 s5, 0x40400000
	v_fma_f32 v148, v192, s4, v218
	v_fma_f32 v149, v193, s5, v218
	s_mov_b32 s4, 0x41000000
	s_mov_b32 s5, 0x41100000
	v_fma_f32 v150, v192, s4, v218
	v_fma_f32 v151, v193, s5, v218
	s_mov_b32 s4, 0x41200000
	s_mov_b32 s5, 0x41300000
	v_fma_f32 v152, v192, s4, v218
	v_fma_f32 v153, v193, s5, v218
	s_mov_b32 s4, 0x41800000
	s_mov_b32 s5, 0x41880000
	v_fma_f32 v154, v192, s4, v218
	v_fma_f32 v155, v193, s5, v218
	s_mov_b32 s4, 0x41900000
	s_mov_b32 s5, 0x41980000
	v_fma_f32 v156, v192, s4, v218
	v_fma_f32 v157, v193, s5, v218
	s_mov_b32 s4, 0x41c00000
	s_mov_b32 s5, 0x41c80000
	v_fma_f32 v158, v192, s4, v218
	v_fma_f32 v159, v193, s5, v218
	s_mov_b32 s4, 0x41d00000
	s_mov_b32 s5, 0x41d80000
	v_fma_f32 v160, v192, s4, v218
	v_fma_f32 v161, v193, s5, v218
	s_mov_b32 s4, 0x42680000
	v_mov_b32_e32 v191, v190
	s_mov_b32 s5, 0x426c0000
	v_fma_f32 v144, v190, s4, v218
	v_fma_f32 v145, v191, s5, v218
	s_mov_b32 s4, 0x42600000
	s_mov_b32 s5, 0x42640000
	v_fma_f32 v142, v190, s4, v218
	v_fma_f32 v143, v191, s5, v218
	s_mov_b32 s4, 0x42480000
	v_fma_f32 v147, -v190, v130, v190
	ds_read_b128 v[130:133], v213
	ds_read_b128 v[214:217], v213 offset:4608
	s_mov_b32 s5, 0x424c0000
	v_fma_f32 v140, v190, s4, v218
	v_fma_f32 v141, v191, s5, v218
	s_mov_b32 s4, 0x42400000
	s_mov_b32 s5, 0x42440000
	v_fma_f32 v138, v190, s4, v218
	v_fma_f32 v139, v191, s5, v218
	s_mov_b32 s4, 0x42280000
	s_mov_b32 s5, 0x422c0000
	v_fma_f32 v136, v190, s4, v218
	v_fma_f32 v137, v191, s5, v218
	s_mov_b32 s4, 0x42200000
	s_mov_b32 s5, 0x42240000
	v_mov_b32_e32 v146, v218
	v_fma_f32 v134, v190, s4, v218
	v_fma_f32 v135, v191, s5, v218
	s_mov_b32 s4, 0x42080000
	v_fmac_f32_e32 v146, 0, v190
	s_mov_b32 s5, 0x420c0000
	v_cmp_ge_i32_e32 vcc, s21, v211
	s_waitcnt lgkmcnt(1)
	v_mfma_f32_32x32x16_bf16 v[146:161], v[130:133], v[162:165], v[146:161]
	v_fma_f32 v132, v190, s4, v218
	v_fma_f32 v133, v191, s5, v218
	s_mov_b32 s4, 0x42000000
	s_mov_b32 s5, 0x42040000
	v_fma_f32 v130, v194, s4, v218
	v_fma_f32 v131, v195, s5, v218
	s_and_b64 vcc, exec, vcc
	s_waitcnt lgkmcnt(0)
	v_mfma_f32_32x32x16_bf16 v[130:145], v[214:217], v[162:165], v[130:145]
	ds_read_b128 v[214:217], v213 offset:32
	ds_read_b128 v[220:223], v213 offset:4640
	ds_read_b128 v[244:247], v213 offset:64
	s_waitcnt lgkmcnt(2)
	v_mfma_f32_32x32x16_bf16 v[146:161], v[214:217], v[166:169], v[146:161]
	ds_read_b128 v[214:217], v213 offset:4672
	s_waitcnt lgkmcnt(2)
	v_mfma_f32_32x32x16_bf16 v[130:145], v[220:223], v[166:169], v[130:145]
	ds_read_b128 v[220:223], v213 offset:96
	s_waitcnt lgkmcnt(2)
	v_mfma_f32_32x32x16_bf16 v[146:161], v[244:247], v[170:173], v[146:161]
	ds_read_b128 v[244:247], v213 offset:4704
	s_waitcnt lgkmcnt(2)
	v_mfma_f32_32x32x16_bf16 v[130:145], v[214:217], v[170:173], v[130:145]
	s_waitcnt lgkmcnt(1)
	v_mfma_f32_32x32x16_bf16 v[146:161], v[220:223], v[174:177], v[146:161]
	s_waitcnt lgkmcnt(0)
	v_mfma_f32_32x32x16_bf16 v[130:145], v[244:247], v[174:177], v[130:145]
	s_cbranch_vccnz .LBB0_348
	v_cmp_gt_i32_e32 vcc, 0, v128
	v_cmp_gt_i32_e64 s[4:5], 1, v128
	s_and_b64 vcc, s[4:5], vcc
	s_nop 4
	v_cndmask_b32_e32 v146, v146, v252, vcc
	v_cmp_lt_i32_e32 vcc, 1, v128
	v_cmp_gt_i32_e64 s[62:63], 58, v128
	v_cmp_gt_i32_e64 s[64:65], 59, v128
	v_cndmask_b32_e32 v148, v252, v148, vcc
	v_cmp_lt_i32_e32 vcc, 2, v128
	v_cmp_gt_i32_e64 s[60:61], 57, v128
	s_and_b64 s[62:63], s[64:65], s[62:63]
	v_cndmask_b32_e32 v149, v252, v149, vcc
	v_cmp_lt_i32_e32 vcc, 7, v128
	v_cmp_gt_i32_e64 s[58:59], 56, v128
	s_and_b64 s[60:61], s[62:63], s[60:61]
	v_cndmask_b32_e32 v150, v252, v150, vcc
	v_cmp_lt_i32_e32 vcc, 8, v128
	v_cmp_gt_i32_e64 s[56:57], 51, v128
	s_and_b64 s[58:59], s[60:61], s[58:59]
	v_cndmask_b32_e32 v151, v252, v151, vcc
	v_cmp_lt_i32_e32 vcc, 9, v128
	v_cmp_gt_i32_e64 s[54:55], 50, v128
	s_and_b64 s[56:57], s[58:59], s[56:57]
	v_cndmask_b32_e32 v152, v252, v152, vcc
	v_cmp_lt_i32_e32 vcc, 10, v128
	v_cmp_gt_i32_e64 s[52:53], 49, v128
	s_and_b64 s[54:55], s[56:57], s[54:55]
	v_cndmask_b32_e32 v153, v252, v153, vcc
	v_cmp_lt_i32_e32 vcc, 15, v128
	v_cmp_gt_i32_e64 s[50:51], 48, v128
	s_and_b64 s[52:53], s[54:55], s[52:53]
	v_cndmask_b32_e32 v154, v252, v154, vcc
	v_cmp_lt_i32_e32 vcc, 16, v128
	v_cmp_gt_i32_e64 s[48:49], 43, v128
	s_and_b64 s[50:51], s[52:53], s[50:51]
	v_cndmask_b32_e32 v155, v252, v155, vcc
	v_cmp_lt_i32_e32 vcc, 17, v128
	v_cmp_gt_i32_e64 s[46:47], 42, v128
	s_and_b64 s[48:49], s[50:51], s[48:49]
	v_cndmask_b32_e32 v156, v252, v156, vcc
	v_cmp_lt_i32_e32 vcc, 18, v128
	v_cmp_gt_i32_e64 s[44:45], 41, v128
	s_and_b64 s[46:47], s[48:49], s[46:47]
	v_cndmask_b32_e32 v157, v252, v157, vcc
	v_cmp_lt_i32_e32 vcc, 23, v128
	v_cmp_gt_i32_e64 s[10:11], 40, v128
	s_and_b64 s[44:45], s[46:47], s[44:45]
	v_cndmask_b32_e32 v158, v252, v158, vcc
	v_cmp_lt_i32_e32 vcc, 24, v128
	v_cmp_gt_i32_e64 s[8:9], 35, v128
	s_and_b64 s[10:11], s[44:45], s[10:11]
	v_cndmask_b32_e32 v159, v252, v159, vcc
	v_cmp_lt_i32_e32 vcc, 25, v128
	v_cmp_gt_i32_e64 s[6:7], 34, v128
	s_and_b64 s[8:9], s[10:11], s[8:9]
	v_cndmask_b32_e64 v147, v147, v252, s[4:5]
	v_cndmask_b32_e32 v160, v252, v160, vcc
	v_cmp_lt_i32_e32 vcc, 26, v128
	v_cmp_gt_i32_e64 s[4:5], 33, v128
	s_and_b64 s[6:7], s[8:9], s[6:7]
	v_cndmask_b32_e32 v191, v252, v161, vcc
	v_cmp_gt_i32_e32 vcc, 32, v128
	s_and_b64 s[4:5], s[6:7], s[4:5]
	s_and_b64 vcc, s[4:5], vcc
	v_cndmask_b32_e64 v145, v145, v252, s[64:65]
	v_cndmask_b32_e64 v144, v144, v252, s[62:63]
	v_cndmask_b32_e64 v143, v143, v252, s[60:61]
	v_cndmask_b32_e64 v142, v142, v252, s[58:59]
	v_cndmask_b32_e64 v141, v141, v252, s[56:57]
	v_cndmask_b32_e64 v140, v140, v252, s[54:55]
	v_cndmask_b32_e64 v139, v139, v252, s[52:53]
	v_cndmask_b32_e64 v138, v138, v252, s[50:51]
	v_cndmask_b32_e64 v137, v137, v252, s[48:49]
	v_cndmask_b32_e64 v136, v136, v252, s[46:47]
	v_cndmask_b32_e64 v135, v135, v252, s[44:45]
	v_cndmask_b32_e64 v134, v134, v252, s[10:11]
	v_cndmask_b32_e64 v133, v133, v252, s[8:9]
	v_cndmask_b32_e64 v132, v132, v252, s[6:7]
	v_cndmask_b32_e64 v131, v131, v252, s[4:5]
	v_cndmask_b32_e32 v161, v161, v191, vcc
	v_cndmask_b32_e32 v130, v130, v252, vcc
.LBB0_348:
	s_nop 7
	v_max_f32_e32 v128, v147, v147
	v_max_f32_e32 v191, v146, v146
	v_max_f32_e32 v128, v191, v128
	v_max3_f32 v128, v128, v148, v149
	v_max3_f32 v128, v128, v150, v151
	v_max3_f32 v128, v128, v152, v153
	v_max3_f32 v128, v128, v154, v155
	v_max3_f32 v128, v128, v156, v157
	v_max3_f32 v128, v128, v158, v159
	v_max3_f32 v128, v128, v160, v161
	v_max3_f32 v128, v128, v130, v131
	v_max3_f32 v128, v128, v132, v133
	v_max3_f32 v128, v128, v134, v135
	v_max3_f32 v128, v128, v136, v137
	v_max3_f32 v128, v128, v138, v139
	v_max3_f32 v128, v128, v140, v141
	v_max3_f32 v128, v128, v142, v143
	v_max3_f32 v128, v128, v144, v145
	v_mov_b32_e32 v191, v128
	v_mov_b32_e32 v213, v128
	s_nop 1
	v_permlane32_swap_b32_e32 v191, v213
	v_cndmask_b32_e64 v191, v191, v213, s[42:43]
	v_max3_f32 v191, v212, v128, v191
	v_cmp_neq_f32_e32 vcc, s2, v191
	s_nop 1
	v_cndmask_b32_e32 v213, 0, v191, vcc
	v_sub_f32_e32 v128, v212, v213
	v_exp_f32_e32 v128, v128
	s_nop 0
	v_cmp_eq_f32_e32 vcc, 1.0, v128
	s_cmp_eq_u64 vcc, exec
	s_cbranch_scc1 .LBB0_350
	v_mul_f32_e32 v126, v126, v128
	v_mul_f32_e32 v127, v127, v128
	v_mul_f32_e32 v124, v124, v128
	v_mul_f32_e32 v125, v125, v128
	v_mul_f32_e32 v122, v122, v128
	v_mul_f32_e32 v123, v123, v128
	v_mul_f32_e32 v120, v120, v128
	v_mul_f32_e32 v121, v121, v128
	v_mul_f32_e32 v118, v118, v128
	v_mul_f32_e32 v119, v119, v128
	v_mul_f32_e32 v116, v116, v128
	v_mul_f32_e32 v117, v117, v128
	v_mul_f32_e32 v114, v114, v128
	v_mul_f32_e32 v115, v115, v128
	v_mul_f32_e32 v112, v112, v128
	v_mul_f32_e32 v113, v113, v128
	v_mul_f32_e32 v110, v110, v128
	v_mul_f32_e32 v111, v111, v128
	v_mul_f32_e32 v108, v108, v128
	v_mul_f32_e32 v109, v109, v128
	v_mul_f32_e32 v106, v106, v128
	v_mul_f32_e32 v107, v107, v128
	v_mul_f32_e32 v104, v104, v128
	v_mul_f32_e32 v105, v105, v128
	v_mul_f32_e32 v102, v102, v128
	v_mul_f32_e32 v103, v103, v128
	v_mul_f32_e32 v100, v100, v128
	v_mul_f32_e32 v101, v101, v128
	v_mul_f32_e32 v98, v98, v128
	v_mul_f32_e32 v99, v99, v128
	v_mul_f32_e32 v96, v96, v128
	v_mul_f32_e32 v97, v97, v128
	v_mul_f32_e32 v94, v94, v128
	v_mul_f32_e32 v95, v95, v128
	v_mul_f32_e32 v92, v92, v128
	v_mul_f32_e32 v93, v93, v128
	v_mul_f32_e32 v90, v90, v128
	v_mul_f32_e32 v91, v91, v128
	v_mul_f32_e32 v88, v88, v128
	v_mul_f32_e32 v89, v89, v128
	v_mul_f32_e32 v86, v86, v128
	v_mul_f32_e32 v87, v87, v128
	v_mul_f32_e32 v84, v84, v128
	v_mul_f32_e32 v85, v85, v128
	v_mul_f32_e32 v82, v82, v128
	v_mul_f32_e32 v83, v83, v128
	v_mul_f32_e32 v80, v80, v128
	v_mul_f32_e32 v81, v81, v128
	v_mul_f32_e32 v78, v78, v128
	v_mul_f32_e32 v79, v79, v128
	v_mul_f32_e32 v76, v76, v128
	v_mul_f32_e32 v77, v77, v128
	v_mul_f32_e32 v74, v74, v128
	v_mul_f32_e32 v75, v75, v128
	v_mul_f32_e32 v72, v72, v128
	v_mul_f32_e32 v73, v73, v128
	v_mul_f32_e32 v70, v70, v128
	v_mul_f32_e32 v71, v71, v128
	v_mul_f32_e32 v68, v68, v128
	v_mul_f32_e32 v69, v69, v128
	v_mul_f32_e32 v66, v66, v128
	v_mul_f32_e32 v67, v67, v128
	v_mul_f32_e32 v64, v64, v128
	v_mul_f32_e32 v65, v65, v128

.LBB0_356:
	v_cndmask_b32_e64 v128, v203, v204, s[38:39]
	v_add_f32_e32 v128, v196, v128
	v_div_scale_f32 v130, s[4:5], v128, v128, 1.0
	v_rcp_f32_e32 v131, v130
	v_readlane_b32 s4, v255, 22
	v_readlane_b32 s5, v255, 23
	s_mov_b32 s6, 0x42b17218
	v_fma_f32 v132, -v130, v131, 1.0
	v_fmac_f32_e32 v131, v132, v131
	v_div_scale_f32 v132, vcc, 1.0, v128, 1.0
	v_mul_f32_e32 v133, v132, v131
	v_fma_f32 v134, -v130, v133, v132
	v_fmac_f32_e32 v133, v134, v131
	v_fma_f32 v130, -v130, v133, v132
	v_div_fmas_f32 v130, v130, v131, v133
	v_div_fixup_f32 v128, v130, v128, 1.0
	v_mov_b32_e32 v130, v197
	v_mov_b32_e32 v131, v197
	v_and_b32_e32 v132, 63, v202
	s_nop 0
	v_permlane32_swap_b32_e32 v130, v131
	v_cndmask_b32_e64 v131, v130, v131, s[42:43]
	v_lshlrev_b32_e32 v130, 2, v132
	global_load_dword v133, v130, s[4:5]
	v_readlane_b32 s4, v255, 24
	v_readlane_b32 s5, v255, 25
	v_xor_b32_e32 v136, 4, v130
	v_readlane_b32 s22, v255, 16
	v_readlane_b32 s23, v255, 17
	s_nop 1
	global_load_dword v134, v130, s[4:5]
	v_readlane_b32 s4, v255, 26
	v_readlane_b32 s5, v255, 27
	s_waitcnt vmcnt(0)
	v_mul_f32_e32 v135, v133, v134
	ds_bpermute_b32 v135, v136, v135
	s_waitcnt lgkmcnt(0)
	v_fmac_f32_e32 v135, v133, v134
	v_xor_b32_e32 v133, 8, v130
	ds_bpermute_b32 v134, v133, v135
	s_waitcnt lgkmcnt(0)
	v_add_f32_e32 v134, v135, v134
	v_xor_b32_e32 v135, 16, v130
	ds_bpermute_b32 v137, v135, v134
	s_waitcnt lgkmcnt(0)
	v_add_f32_e32 v134, v134, v137
	v_xor_b32_e32 v137, 32, v130
	ds_bpermute_b32 v138, v137, v134
	s_waitcnt lgkmcnt(0)
	v_add_f32_e32 v134, v134, v138
	v_xor_b32_e32 v138, 64, v130
	ds_bpermute_b32 v139, v138, v134
	s_waitcnt lgkmcnt(0)
	v_add_f32_e32 v134, v134, v139
	v_xor_b32_e32 v139, 0x80, v130
	ds_bpermute_b32 v140, v139, v134
	s_waitcnt lgkmcnt(0)
	v_add_f32_e32 v134, v134, v140
	global_load_dword v140, v130, s[4:5]
	v_readlane_b32 s4, v255, 28
	v_readlane_b32 s5, v255, 29
	s_nop 4
	global_load_dword v130, v130, s[4:5]
	s_mov_b32 s4, 0x3fb8aa3b
	s_mov_b32 s5, 0xc2ce8ed0
	v_cmp_ngt_f32_e32 vcc, s5, v134
	s_waitcnt vmcnt(0)
	v_mul_f32_e32 v141, v140, v130
	ds_bpermute_b32 v136, v136, v141
	s_waitcnt lgkmcnt(0)
	v_fmac_f32_e32 v136, v140, v130
	ds_bpermute_b32 v130, v133, v136
	s_waitcnt lgkmcnt(0)
	v_add_f32_e32 v130, v136, v130
	ds_bpermute_b32 v133, v135, v130
	s_waitcnt lgkmcnt(0)
	v_add_f32_e32 v130, v130, v133
	ds_bpermute_b32 v133, v137, v130
	v_mov_b32_e32 v137, 0x7f800000
	s_waitcnt lgkmcnt(0)
	v_add_f32_e32 v130, v130, v133
	ds_bpermute_b32 v133, v138, v130
	s_waitcnt lgkmcnt(0)
	v_add_f32_e32 v130, v130, v133
	ds_bpermute_b32 v133, v139, v130
	s_waitcnt lgkmcnt(0)
	v_add_f32_e32 v130, v130, v133
	v_mul_f32_e32 v133, 0x3fb8aa3b, v134
	v_fma_f32 v135, v134, s4, -v133
	v_rndne_f32_e32 v136, v133
	v_fmac_f32_e32 v135, 0x32a5705f, v134
	v_sub_f32_e32 v133, v133, v136
	v_add_f32_e32 v133, v133, v135
	v_exp_f32_e32 v133, v133
	v_cvt_i32_f32_e32 v135, v136
	v_ldexp_f32 v133, v133, v135
	v_cndmask_b32_e32 v133, 0, v133, vcc
	v_cmp_nlt_f32_e32 vcc, s6, v134
	v_mul_f32_e32 v134, 0x3fb8aa3b, v130
	v_fma_f32 v135, v130, s4, -v134
	v_rndne_f32_e32 v136, v134
	v_fmac_f32_e32 v135, 0x32a5705f, v130
	v_sub_f32_e32 v134, v134, v136
	v_add_f32_e32 v134, v134, v135
	v_exp_f32_e32 v134, v134
	v_cvt_i32_f32_e32 v135, v136
	v_cndmask_b32_e32 v133, v137, v133, vcc
	v_cmp_ngt_f32_e32 vcc, s5, v130
	v_readlane_b32 s4, v255, 30
	v_ldexp_f32 v134, v134, v135
	v_cndmask_b32_e32 v134, 0, v134, vcc
	v_cmp_nlt_f32_e32 vcc, s6, v130
	v_mov_b32_e32 v196, s4
	s_nop 0
	v_cndmask_b32_e32 v130, v137, v134, vcc
	v_sub_f32_e32 v130, v133, v130
	v_add_f32_e32 v130, v196, v130
	v_add_f32_e32 v131, v197, v131
	s_nop 0
	v_div_scale_f32 v133, s[4:5], v131, v131, v130
	v_rcp_f32_e32 v134, v133
	s_mov_b32 s4, 0xf800000
	v_fma_f32 v135, -v133, v134, 1.0
	v_fmac_f32_e32 v134, v135, v134
	v_div_scale_f32 v135, vcc, v130, v131, v130
	v_mul_f32_e32 v136, v135, v134
	v_fma_f32 v137, -v133, v136, v135
	v_fmac_f32_e32 v136, v137, v134
	v_fma_f32 v133, -v133, v136, v135
	v_div_fmas_f32 v133, v133, v134, v136
	v_div_fixup_f32 v130, v133, v131, v130
	v_mul_f32_e32 v112, v112, v130
	v_mul_f32_e32 v113, v113, v130
	v_mul_f32_e32 v114, v114, v130
	v_mul_f32_e32 v115, v115, v130
	v_fma_f32 v48, v48, v128, -v112
	v_fma_f32 v49, v49, v128, -v113
	v_fma_f32 v50, v50, v128, -v114
	v_fma_f32 v51, v51, v128, -v115
	v_mul_f32_e32 v112, v49, v49
	v_fmac_f32_e32 v112, v48, v48
	v_mul_f32_e32 v116, v116, v130
	v_mul_f32_e32 v117, v117, v130
	v_fmac_f32_e32 v112, v50, v50
	v_fma_f32 v52, v52, v128, -v116
	v_fma_f32 v53, v53, v128, -v117
	v_fmac_f32_e32 v112, v51, v51
	v_mul_f32_e32 v118, v118, v130
	v_mul_f32_e32 v119, v119, v130
	v_fmac_f32_e32 v112, v52, v52
	v_fma_f32 v54, v54, v128, -v118
	v_fma_f32 v55, v55, v128, -v119
	v_fmac_f32_e32 v112, v53, v53
	v_mul_f32_e32 v120, v120, v130
	v_mul_f32_e32 v121, v121, v130
	v_fmac_f32_e32 v112, v54, v54
	v_fma_f32 v56, v56, v128, -v120
	v_fma_f32 v57, v57, v128, -v121
	v_fmac_f32_e32 v112, v55, v55
	v_mul_f32_e32 v122, v122, v130
	v_mul_f32_e32 v123, v123, v130
	v_fmac_f32_e32 v112, v56, v56
	v_fma_f32 v58, v58, v128, -v122
	v_fma_f32 v59, v59, v128, -v123
	v_fmac_f32_e32 v112, v57, v57
	v_mul_f32_e32 v124, v124, v130
	v_mul_f32_e32 v125, v125, v130
	v_fmac_f32_e32 v112, v58, v58
	v_fma_f32 v60, v60, v128, -v124
	v_fma_f32 v61, v61, v128, -v125
	v_fmac_f32_e32 v112, v59, v59
	v_mul_f32_e32 v126, v126, v130
	v_mul_f32_e32 v127, v127, v130
	v_fmac_f32_e32 v112, v60, v60
	v_fma_f32 v62, v62, v128, -v126
	v_fma_f32 v63, v63, v128, -v127
	v_fmac_f32_e32 v112, v61, v61
	v_fmac_f32_e32 v112, v62, v62
	v_mul_f32_e32 v96, v96, v130
	v_mul_f32_e32 v97, v97, v130
	v_fmac_f32_e32 v112, v63, v63
	v_fma_f32 v32, v32, v128, -v96
	v_fma_f32 v33, v33, v128, -v97
	v_mul_f32_e32 v98, v98, v130
	v_mul_f32_e32 v99, v99, v130
	v_fmac_f32_e32 v112, v32, v32
	v_fma_f32 v34, v34, v128, -v98
	v_fma_f32 v35, v35, v128, -v99
	v_fmac_f32_e32 v112, v33, v33
	v_mul_f32_e32 v100, v100, v130
	v_mul_f32_e32 v101, v101, v130
	v_fmac_f32_e32 v112, v34, v34
	v_fma_f32 v36, v36, v128, -v100
	v_fma_f32 v37, v37, v128, -v101
	v_fmac_f32_e32 v112, v35, v35
	v_mul_f32_e32 v102, v102, v130
	v_mul_f32_e32 v103, v103, v130
	v_fmac_f32_e32 v112, v36, v36
	v_fma_f32 v38, v38, v128, -v102
	v_fma_f32 v39, v39, v128, -v103
	v_fmac_f32_e32 v112, v37, v37
	v_mul_f32_e32 v104, v104, v130
	v_mul_f32_e32 v105, v105, v130
	v_fmac_f32_e32 v112, v38, v38
	v_fma_f32 v40, v40, v128, -v104
	v_fma_f32 v41, v41, v128, -v105
	v_fmac_f32_e32 v112, v39, v39
	v_mul_f32_e32 v106, v106, v130
	v_mul_f32_e32 v107, v107, v130
	v_fmac_f32_e32 v112, v40, v40
	v_fma_f32 v42, v42, v128, -v106
	v_fma_f32 v43, v43, v128, -v107
	v_fmac_f32_e32 v112, v41, v41
	v_mul_f32_e32 v108, v108, v130
	v_mul_f32_e32 v109, v109, v130
	v_fmac_f32_e32 v112, v42, v42
	v_fma_f32 v44, v44, v128, -v108
	v_fma_f32 v45, v45, v128, -v109
	v_fmac_f32_e32 v112, v43, v43
	v_mul_f32_e32 v110, v110, v130
	v_mul_f32_e32 v111, v111, v130
	v_fmac_f32_e32 v112, v44, v44
	v_fma_f32 v46, v46, v128, -v110
	v_fma_f32 v47, v47, v128, -v111
	v_fmac_f32_e32 v112, v45, v45
	v_fmac_f32_e32 v112, v46, v46
	v_mul_f32_e32 v96, v80, v130
	v_mul_f32_e32 v97, v81, v130
	v_mul_f32_e32 v80, v84, v130
	v_mul_f32_e32 v81, v85, v130
	v_mul_f32_e32 v84, v86, v130
	v_mul_f32_e32 v85, v87, v130
	v_fmac_f32_e32 v112, v47, v47
	v_fma_f32 v22, v22, v128, -v84
	v_fma_f32 v23, v23, v128, -v85
	v_fma_f32 v84, v16, v128, -v96
	v_fma_f32 v85, v17, v128, -v97
	v_mul_f32_e32 v82, v82, v130
	v_mul_f32_e32 v83, v83, v130
	v_fmac_f32_e32 v112, v84, v84
	v_fma_f32 v82, v18, v128, -v82
	v_fma_f32 v83, v19, v128, -v83
	v_fmac_f32_e32 v112, v85, v85
	v_fmac_f32_e32 v112, v82, v82
	v_fma_f32 v80, v20, v128, -v80
	v_fma_f32 v81, v21, v128, -v81
	v_fmac_f32_e32 v112, v83, v83
	v_fmac_f32_e32 v112, v80, v80
	v_fmac_f32_e32 v112, v81, v81
	v_mul_f32_e32 v86, v88, v130
	v_mul_f32_e32 v87, v89, v130
	v_fmac_f32_e32 v112, v22, v22
	v_fma_f32 v24, v24, v128, -v86
	v_fma_f32 v25, v25, v128, -v87
	v_fmac_f32_e32 v112, v23, v23
	v_mul_f32_e32 v88, v90, v130
	v_mul_f32_e32 v89, v91, v130
	v_fmac_f32_e32 v112, v24, v24
	v_fma_f32 v26, v26, v128, -v88
	v_fma_f32 v27, v27, v128, -v89
	v_fmac_f32_e32 v112, v25, v25
	v_mul_f32_e32 v90, v92, v130
	v_mul_f32_e32 v91, v93, v130
	v_fmac_f32_e32 v112, v26, v26
	v_fma_f32 v28, v28, v128, -v90
	v_fma_f32 v29, v29, v128, -v91
	v_fmac_f32_e32 v112, v27, v27
	v_mul_f32_e32 v92, v94, v130
	v_mul_f32_e32 v93, v95, v130
	v_fmac_f32_e32 v112, v28, v28
	v_fma_f32 v30, v30, v128, -v92
	v_fma_f32 v31, v31, v128, -v93
	v_fmac_f32_e32 v112, v29, v29
	v_fmac_f32_e32 v112, v30, v30
	v_mul_f32_e32 v16, v64, v130
	v_mul_f32_e32 v17, v65, v130
	v_fmac_f32_e32 v112, v31, v31
	v_fma_f32 v0, v0, v128, -v16
	v_fma_f32 v1, v1, v128, -v17
	v_mul_f32_e32 v86, v66, v130
	v_mul_f32_e32 v87, v67, v130
	v_fmac_f32_e32 v112, v0, v0
	v_fma_f32 v2, v2, v128, -v86
	v_fma_f32 v3, v3, v128, -v87
	v_fmac_f32_e32 v112, v1, v1
	v_mul_f32_e32 v66, v68, v130
	v_mul_f32_e32 v67, v69, v130
	v_fmac_f32_e32 v112, v2, v2
	v_fma_f32 v66, v4, v128, -v66
	v_fma_f32 v67, v5, v128, -v67
	v_fmac_f32_e32 v112, v3, v3
	v_mul_f32_e32 v64, v70, v130
	v_mul_f32_e32 v65, v71, v130
	v_fmac_f32_e32 v112, v66, v66
	v_fma_f32 v64, v6, v128, -v64
	v_fma_f32 v65, v7, v128, -v65
	v_fmac_f32_e32 v112, v67, v67
	v_mul_f32_e32 v20, v72, v130
	v_mul_f32_e32 v21, v73, v130
	v_fmac_f32_e32 v112, v64, v64
	v_mul_f32_e32 v18, v74, v130
	v_mul_f32_e32 v19, v75, v130
	v_fma_f32 v20, v8, v128, -v20
	v_fma_f32 v21, v9, v128, -v21
	v_fmac_f32_e32 v112, v65, v65
	v_fma_f32 v18, v10, v128, -v18
	v_fma_f32 v19, v11, v128, -v19
	v_fmac_f32_e32 v112, v20, v20
	v_mul_f32_e32 v70, v76, v130
	v_mul_f32_e32 v71, v77, v130
	v_fmac_f32_e32 v112, v21, v21
	v_mul_f32_e32 v8, v18, v18
	v_mul_f32_e32 v9, v19, v19
	v_fma_f32 v12, v12, v128, -v70
	v_fma_f32 v13, v13, v128, -v71
	v_add_f32_e32 v8, v8, v112
	v_mul_f32_e32 v68, v78, v130
	v_mul_f32_e32 v69, v79, v130
	v_mul_f32_e32 v6, v12, v12
	v_mul_f32_e32 v7, v13, v13
	v_add_f32_e32 v8, v9, v8
	v_fma_f32 v10, v14, v128, -v68
	v_fma_f32 v11, v15, v128, -v69
	v_add_f32_e32 v6, v6, v8
	v_mul_f32_e32 v4, v10, v10
	v_mul_f32_e32 v5, v11, v11
	v_add_f32_e32 v6, v7, v6
	v_add_f32_e32 v4, v4, v6
	v_add_f32_e32 v4, v5, v4
	v_mov_b32_e32 v5, v4
	v_mov_b32_e32 v6, v4
	s_nop 1
	v_permlane32_swap_b32_e32 v5, v6
	v_cmp_gt_u32_e32 vcc, 32, v132
	s_nop 1
	v_cndmask_b32_e32 v5, v5, v6, vcc
	v_add_f32_e32 v4, v4, v5
	v_mov_b32_e32 v5, 0x3727c5ac
	v_fmamk_f32 v4, v4, 0x3c000000, v5
	v_cmp_gt_f32_e32 vcc, s4, v4
	v_mul_f32_e32 v5, 0x4f800000, v4
	s_nop 0
	v_cndmask_b32_e32 v4, v4, v5, vcc
	v_sqrt_f32_e32 v5, v4
	s_nop 0
	v_add_u32_e32 v6, -1, v5
	v_fma_f32 v7, -v6, v5, v4
	v_cmp_ge_f32_e64 s[4:5], 0, v7
	v_add_u32_e32 v7, 1, v5
	s_nop 0
	v_cndmask_b32_e64 v6, v5, v6, s[4:5]
	v_fma_f32 v5, -v7, v5, v4
	v_cmp_lt_f32_e64 s[4:5], 0, v5
	s_nop 1
	v_cndmask_b32_e64 v5, v6, v7, s[4:5]
	v_mul_f32_e32 v6, 0x37800000, v5
	v_cndmask_b32_e32 v5, v5, v6, vcc
	v_cmp_class_f32_e32 vcc, v4, v233
	s_nop 1
	v_cndmask_b32_e32 v4, v5, v4, vcc
	v_div_scale_f32 v5, s[4:5], v4, v4, 1.0
	v_rcp_f32_e32 v6, v5
	v_readlane_b32 s4, v255, 31
	s_ashr_i32 s5, s17, 1
	s_andn2_b32 s5, s5, 31
	v_fma_f32 v7, -v5, v6, 1.0
	v_fmac_f32_e32 v6, v7, v6
	v_div_scale_f32 v7, vcc, 1.0, v4, 1.0
	v_mul_f32_e32 v8, v7, v6
	v_fma_f32 v9, -v5, v8, v7
	v_fmac_f32_e32 v8, v9, v6
	v_fma_f32 v5, -v5, v8, v7
	v_div_fmas_f32 v5, v5, v6, v8
	v_div_fixup_f32 v4, v5, v4, 1.0
	v_lshrrev_b32_e32 v5, 3, v202
	v_and_b32_e32 v5, 4, v5
	v_lshlrev_b32_e32 v70, 2, v5
	global_load_dwordx4 v[6:9], v70, s[0:1]
	global_load_dwordx4 v[14:17], v70, s[0:1] offset:32
	v_mul_f32_e32 v4, s4, v4
	s_lshl_b32 s4, s27, 11
	s_add_i32 s4, s4, s30
	v_lshlrev_b32_e32 v128, 1, v5
	v_readlane_b32 s30, v255, 3
	v_readlane_b32 s31, v255, 4
	global_load_dwordx4 v[72:75], v70, s[0:1] offset:320
	s_waitcnt vmcnt(2)
	v_mul_f32_e32 v6, v6, v4
	v_mul_f32_e32 v7, v7, v4
	v_mul_f32_e32 v8, v8, v4
	v_mul_f32_e32 v9, v9, v4
	v_mul_f32_e32 v6, v48, v6
	v_mul_f32_e32 v7, v49, v7
	v_mul_f32_e32 v8, v50, v8
	v_mul_f32_e32 v9, v51, v9
	global_load_dwordx4 v[48:51], v70, s[0:1] offset:64
	s_waitcnt vmcnt(2)
	v_mul_f32_e32 v14, v14, v4
	v_mul_f32_e32 v15, v15, v4
	v_mul_f32_e32 v16, v16, v4
	v_mul_f32_e32 v17, v17, v4
	v_mul_f32_e32 v14, v52, v14
	v_mul_f32_e32 v15, v53, v15
	v_mul_f32_e32 v16, v54, v16
	v_mul_f32_e32 v17, v55, v17
	global_load_dwordx4 v[52:55], v70, s[0:1] offset:96
	v_cvt_pk_bf16_f32 v6, v6, v7
	v_cvt_pk_bf16_f32 v7, v8, v9
	s_waitcnt vmcnt(1)
	v_mul_f32_e32 v48, v48, v4
	v_mul_f32_e32 v49, v49, v4
	v_mul_f32_e32 v50, v50, v4
	v_mul_f32_e32 v51, v51, v4
	v_mul_f32_e32 v48, v56, v48
	v_mul_f32_e32 v49, v57, v49
	v_mul_f32_e32 v50, v58, v50
	v_mul_f32_e32 v51, v59, v51
	global_load_dwordx4 v[56:59], v70, s[0:1] offset:128
	s_waitcnt vmcnt(1)
	v_mul_f32_e32 v52, v52, v4
	v_mul_f32_e32 v53, v53, v4
	v_mul_f32_e32 v54, v54, v4
	v_mul_f32_e32 v55, v55, v4
	v_mul_f32_e32 v52, v60, v52
	v_mul_f32_e32 v53, v61, v53
	v_mul_f32_e32 v54, v62, v54
	v_mul_f32_e32 v55, v63, v55
	global_load_dwordx4 v[60:63], v70, s[0:1] offset:288
	s_waitcnt vmcnt(1)
	v_mul_f32_e32 v56, v56, v4
	v_mul_f32_e32 v57, v57, v4
	s_nop 0
	v_mul_f32_e32 v32, v32, v56
	v_mul_f32_e32 v33, v33, v57
	v_mul_f32_e32 v56, v58, v4
	v_mul_f32_e32 v57, v59, v4
	s_waitcnt vmcnt(0)
	v_mul_f32_e32 v62, v62, v4
	v_mul_f32_e32 v63, v63, v4
	v_mul_f32_e32 v34, v34, v56
	v_mul_f32_e32 v35, v35, v57
	global_load_dwordx4 v[56:59], v70, s[0:1] offset:160
	v_mul_f32_e32 v22, v22, v62
	v_mul_f32_e32 v23, v23, v63
	v_mul_f32_e32 v62, v72, v4
	v_mul_f32_e32 v63, v73, v4
	v_mul_f32_e32 v60, v60, v4
	v_mul_f32_e32 v61, v61, v4
	v_mul_f32_e32 v24, v24, v62
	v_mul_f32_e32 v25, v25, v63
	v_mul_f32_e32 v62, v74, v4
	v_mul_f32_e32 v63, v75, v4
	global_load_dwordx4 v[72:75], v70, s[0:1] offset:352
	v_mul_f32_e32 v26, v26, v62
	v_mul_f32_e32 v27, v27, v63
	v_mul_f32_e32 v60, v80, v60
	v_mul_f32_e32 v61, v81, v61
	s_waitcnt vmcnt(1)
	v_mul_f32_e32 v56, v56, v4
	v_mul_f32_e32 v57, v57, v4
	s_nop 0
	v_mul_f32_e32 v36, v36, v56
	v_mul_f32_e32 v37, v37, v57
	v_mul_f32_e32 v56, v58, v4
	v_mul_f32_e32 v57, v59, v4
	s_waitcnt vmcnt(0)
	v_mul_f32_e32 v62, v72, v4
	v_mul_f32_e32 v63, v73, v4
	v_mul_f32_e32 v38, v38, v56
	v_mul_f32_e32 v39, v39, v57
	global_load_dwordx4 v[56:59], v70, s[0:1] offset:192
	v_mul_f32_e32 v28, v28, v62
	v_mul_f32_e32 v29, v29, v63
	v_mul_f32_e32 v62, v74, v4
	v_mul_f32_e32 v63, v75, v4
	global_load_dwordx4 v[72:75], v70, s[0:1] offset:384
	v_mul_f32_e32 v30, v30, v62
	v_mul_f32_e32 v31, v31, v63
	s_waitcnt vmcnt(1)
	v_mul_f32_e32 v56, v56, v4
	v_mul_f32_e32 v57, v57, v4
	s_nop 0
	v_mul_f32_e32 v40, v40, v56
	v_mul_f32_e32 v41, v41, v57
	v_mul_f32_e32 v56, v58, v4
	v_mul_f32_e32 v57, v59, v4
	s_waitcnt vmcnt(0)
	v_mul_f32_e32 v62, v72, v4
	v_mul_f32_e32 v63, v73, v4
	v_mul_f32_e32 v42, v42, v56
	v_mul_f32_e32 v43, v43, v57
	global_load_dwordx4 v[56:59], v70, s[0:1] offset:224
	v_mul_f32_e32 v62, v0, v62
	v_mul_f32_e32 v63, v1, v63
	v_mul_f32_e32 v0, v74, v4
	v_mul_f32_e32 v1, v75, v4
	s_waitcnt vmcnt(0)
	v_mul_f32_e32 v56, v56, v4
	v_mul_f32_e32 v57, v57, v4
	s_nop 0
	v_mul_f32_e32 v44, v44, v56
	v_mul_f32_e32 v45, v45, v57
	v_mul_f32_e32 v56, v58, v4
	v_mul_f32_e32 v57, v59, v4
	v_mul_f32_e32 v68, v2, v0
	v_mul_f32_e32 v69, v3, v1
	v_mul_f32_e32 v46, v46, v56
	v_mul_f32_e32 v47, v47, v57
	global_load_dwordx4 v[56:59], v70, s[0:1] offset:256
	global_load_dwordx4 v[0:3], v70, s[0:1] offset:416
	s_waitcnt vmcnt(1)
	v_mul_f32_e32 v56, v56, v4
	v_mul_f32_e32 v57, v57, v4
	s_waitcnt vmcnt(0)
	v_mul_f32_e32 v0, v0, v4
	v_mul_f32_e32 v1, v1, v4
	v_mul_f32_e32 v58, v58, v4
	v_mul_f32_e32 v59, v59, v4
	v_mul_f32_e32 v66, v66, v0
	v_mul_f32_e32 v67, v67, v1
	v_mul_f32_e32 v0, v2, v4
	v_mul_f32_e32 v1, v3, v4
	v_mul_f32_e32 v56, v84, v56
	v_mul_f32_e32 v57, v85, v57
	v_mul_f32_e32 v64, v64, v0
	v_mul_f32_e32 v65, v65, v1
	global_load_dwordx4 v[0:3], v70, s[0:1] offset:448
	v_mul_f32_e32 v58, v82, v58
	v_mul_f32_e32 v59, v83, v59
	s_waitcnt vmcnt(0)
	v_mul_f32_e32 v0, v0, v4
	v_mul_f32_e32 v1, v1, v4
	s_nop 0
	v_mul_f32_e32 v20, v20, v0
	v_mul_f32_e32 v21, v21, v1
	v_mul_f32_e32 v0, v2, v4
	v_mul_f32_e32 v1, v3, v4
	s_nop 0
	v_mul_f32_e32 v18, v18, v0
	v_mul_f32_e32 v19, v19, v1
	global_load_dwordx4 v[0:3], v70, s[0:1] offset:480
	s_waitcnt vmcnt(0)
	v_mul_f32_e32 v0, v0, v4
	v_mul_f32_e32 v1, v1, v4
	v_mul_f32_e32 v2, v2, v4
	v_mul_f32_e32 v3, v3, v4
	v_and_or_b32 v4, v202, 31, s4
	v_mul_f32_e32 v2, v10, v2
	v_mul_f32_e32 v3, v11, v3
	v_add_u32_e32 v10, s5, v4
	v_ashrrev_i32_e32 v11, 31, v10
	v_readlane_b32 s4, v255, 13
	v_lshlrev_b64 v[10:11], 12, v[10:11]
	v_readlane_b32 s5, v255, 14
	v_mul_f32_e32 v0, v12, v0
	v_mul_f32_e32 v1, v13, v1
	s_nop 0
	v_lshl_add_u64 v[10:11], s[4:5], 0, v[10:11]
	v_readlane_b32 s4, v254, 19
	v_readlane_b32 s5, v254, 20
	v_cvt_pk_bf16_f32 v0, v0, v1
	v_cvt_pk_bf16_f32 v1, v2, v3
	v_lshl_add_u64 v[10:11], v[10:11], 0, s[4:5]
	v_lshl_add_u64 v[4:5], v[10:11], 0, v[128:129]
	global_store_dwordx2 v[4:5], v[6:7], off offset:2048
	v_cvt_pk_bf16_f32 v6, v14, v15
	v_cvt_pk_bf16_f32 v7, v16, v17
	global_store_dwordx2 v[4:5], v[6:7], off offset:2064
	v_cvt_pk_bf16_f32 v6, v48, v49
	v_cvt_pk_bf16_f32 v7, v50, v51
	global_store_dwordx2 v[4:5], v[6:7], off offset:2080
	v_cvt_pk_bf16_f32 v6, v52, v53
	v_cvt_pk_bf16_f32 v7, v54, v55
	global_store_dwordx2 v[4:5], v[6:7], off offset:2096
	v_cvt_pk_bf16_f32 v6, v32, v33
	v_cvt_pk_bf16_f32 v7, v34, v35
	global_store_dwordx2 v[4:5], v[6:7], off offset:2112
	v_cvt_pk_bf16_f32 v6, v36, v37
	v_cvt_pk_bf16_f32 v7, v38, v39
	global_store_dwordx2 v[4:5], v[6:7], off offset:2128
	v_cvt_pk_bf16_f32 v6, v40, v41
	v_cvt_pk_bf16_f32 v7, v42, v43
	global_store_dwordx2 v[4:5], v[6:7], off offset:2144
	v_cvt_pk_bf16_f32 v6, v44, v45
	v_cvt_pk_bf16_f32 v7, v46, v47
	global_store_dwordx2 v[4:5], v[6:7], off offset:2160
	v_cvt_pk_bf16_f32 v6, v56, v57
	v_cvt_pk_bf16_f32 v7, v58, v59
	global_store_dwordx2 v[4:5], v[6:7], off offset:2176
	v_cvt_pk_bf16_f32 v6, v60, v61
	v_cvt_pk_bf16_f32 v7, v22, v23
	global_store_dwordx2 v[4:5], v[6:7], off offset:2192
	v_cvt_pk_bf16_f32 v6, v24, v25
	v_cvt_pk_bf16_f32 v7, v26, v27
	global_store_dwordx2 v[4:5], v[6:7], off offset:2208
	v_cvt_pk_bf16_f32 v6, v28, v29
	v_cvt_pk_bf16_f32 v7, v30, v31
	global_store_dwordx2 v[4:5], v[6:7], off offset:2224
	v_cvt_pk_bf16_f32 v6, v62, v63
	v_cvt_pk_bf16_f32 v7, v68, v69
	global_store_dwordx2 v[4:5], v[6:7], off offset:2240
	v_cvt_pk_bf16_f32 v6, v66, v67
	v_cvt_pk_bf16_f32 v7, v64, v65
	global_store_dwordx2 v[4:5], v[6:7], off offset:2256
	v_cvt_pk_bf16_f32 v6, v20, v21
	v_cvt_pk_bf16_f32 v7, v18, v19
	s_mov_b64 s[4:5], 0x8f0
	global_store_dwordx2 v[4:5], v[6:7], off offset:2272
	v_lshl_add_u64 v[2:3], v[4:5], 0, s[4:5]
	s_mov_b64 s[4:5], -1

.LBB0_371:
	v_readlane_b32 s4, v255, 11
	v_readlane_b32 s5, v255, 12
	s_add_u32 s4, s4, s10
	s_addc_u32 s5, s5, s9
	s_lshl_b32 s6, s29, 7
	s_add_u32 s8, s4, s6
	s_addc_u32 s9, s5, 0
	s_add_u32 s96, s8, 0x400
	v_add_f32_e32 v2, v2, v4
	v_add_f32_e32 v3, v3, v4
	v_add_f32_e32 v0, v0, v4
	v_add_f32_e32 v1, v1, v4
	v_lshl_add_u32 v4, v246, 4, 0
	s_addc_u32 s97, s9, 0
	v_mov_b32_e32 v8, v241
	ds_write_b128 v4, v[0:3] offset:55296
	s_waitcnt lgkmcnt(0)
	s_barrier
	s_add_u32 s36, s8, 0x800
	s_addc_u32 s37, s9, 0
	v_readfirstlane_b32 s5, v8
	s_ashr_i32 s4, s5, 6
	s_lshl_b32 s30, s28, 8
	s_lshl_b32 s6, s4, 5
	v_and_b32_e32 v34, 31, v8
	s_add_i32 s31, s6, s30
	v_bfe_u32 v35, v8, 5, 1
	v_or_b32_e32 v10, s31, v34
	v_mov_b64_e32 v[0:1], s[8:9]
	s_movk_i32 s7, 0x3000
	v_mad_i64_i32 v[0:1], s[8:9], v10, s7, v[0:1]
	v_lshlrev_b32_e32 v128, 4, v35
	v_lshl_add_u64 v[0:1], v[0:1], 0, v[128:129]
	global_load_dwordx4 v[2:5], v[0:1], off
	global_load_dwordx4 v[16:19], v[0:1], off offset:32
	global_load_dwordx4 v[20:23], v[0:1], off offset:64
	global_load_dwordx4 v[24:27], v[0:1], off offset:96
	s_mov_b32 s8, 0x3e38aa3b
	v_and_b32_e32 v33, 63, v8
	s_ashr_i32 s21, s5, 7
	s_movk_i32 s5, 0x90
	s_lshl_b32 s24, s28, 2
	s_mul_i32 s19, s28, 0x300000
	v_mov_b32_e32 v249, v241
	v_mul_u32_u24_e32 v243, 0x90, v34
	s_waitcnt vmcnt(3)
	v_and_b32_e32 v7, 0xffff0000, v2
	v_lshlrev_b32_e32 v6, 16, v2
	v_mul_f32_e32 v6, s8, v6
	v_mul_f32_e32 v7, s8, v7
	s_nop 0
	v_cvt_pk_bf16_f32 v192, v6, v7
	v_and_b32_e32 v7, 0xffff0000, v3
	v_lshlrev_b32_e32 v6, 16, v3
	v_mul_f32_e32 v2, s8, v6
	v_mul_f32_e32 v3, s8, v7
	s_nop 0
	v_cvt_pk_bf16_f32 v193, v2, v3
	v_and_b32_e32 v3, 0xffff0000, v4
	v_lshlrev_b32_e32 v2, 16, v4
	v_mul_f32_e32 v2, s8, v2
	v_mul_f32_e32 v3, s8, v3
	s_nop 0
	v_cvt_pk_bf16_f32 v194, v2, v3
	v_and_b32_e32 v3, 0xffff0000, v5
	v_lshlrev_b32_e32 v2, 16, v5
	v_mul_f32_e32 v2, s8, v2
	v_mul_f32_e32 v3, s8, v3
	s_nop 0
	v_cvt_pk_bf16_f32 v195, v2, v3
	s_waitcnt vmcnt(2)
	v_and_b32_e32 v7, 0xffff0000, v16
	v_lshlrev_b32_e32 v6, 16, v16
	v_mul_f32_e32 v6, s8, v6
	v_mul_f32_e32 v7, s8, v7
	s_nop 0
	v_cvt_pk_bf16_f32 v196, v6, v7
	v_and_b32_e32 v7, 0xffff0000, v17
	v_lshlrev_b32_e32 v6, 16, v17
	v_mul_f32_e32 v2, s8, v6
	v_mul_f32_e32 v3, s8, v7
	s_nop 0
	v_cvt_pk_bf16_f32 v197, v2, v3
	v_and_b32_e32 v3, 0xffff0000, v18
	v_lshlrev_b32_e32 v2, 16, v18
	v_mul_f32_e32 v2, s8, v2
	v_mul_f32_e32 v3, s8, v3
	s_nop 0
	v_cvt_pk_bf16_f32 v198, v2, v3
	v_and_b32_e32 v3, 0xffff0000, v19
	v_lshlrev_b32_e32 v2, 16, v19
	v_mul_f32_e32 v2, s8, v2
	v_mul_f32_e32 v3, s8, v3
	s_nop 0
	v_cvt_pk_bf16_f32 v199, v2, v3
	s_waitcnt vmcnt(1)
	v_and_b32_e32 v7, 0xffff0000, v20
	v_lshlrev_b32_e32 v6, 16, v20
	v_mul_f32_e32 v6, s8, v6
	v_mul_f32_e32 v7, s8, v7
	s_nop 0
	v_cvt_pk_bf16_f32 v200, v6, v7
	v_and_b32_e32 v7, 0xffff0000, v21
	v_lshlrev_b32_e32 v6, 16, v21
	v_mul_f32_e32 v2, s8, v6
	v_mul_f32_e32 v3, s8, v7
	s_nop 0
	v_cvt_pk_bf16_f32 v201, v2, v3
	v_and_b32_e32 v3, 0xffff0000, v22
	v_lshlrev_b32_e32 v2, 16, v22
	v_mul_f32_e32 v2, s8, v2
	v_mul_f32_e32 v3, s8, v3
	s_nop 0
	v_cvt_pk_bf16_f32 v202, v2, v3
	v_and_b32_e32 v3, 0xffff0000, v23
	v_lshlrev_b32_e32 v2, 16, v23
	v_mul_f32_e32 v2, s8, v2
	v_mul_f32_e32 v3, s8, v3
	s_nop 0
	v_cvt_pk_bf16_f32 v203, v2, v3
	s_waitcnt vmcnt(0)
	v_and_b32_e32 v5, 0xffff0000, v24
	v_lshlrev_b32_e32 v4, 16, v24
	v_mul_f32_e32 v4, s8, v4
	v_mul_f32_e32 v5, s8, v5
	s_nop 0
	v_cvt_pk_bf16_f32 v204, v4, v5
	v_and_b32_e32 v5, 0xffff0000, v25
	v_lshlrev_b32_e32 v4, 16, v25
	v_mul_f32_e32 v0, s8, v4
	v_mul_f32_e32 v1, s8, v5
	s_nop 0
	v_cvt_pk_bf16_f32 v205, v0, v1
	v_and_b32_e32 v1, 0xffff0000, v26
	v_lshlrev_b32_e32 v0, 16, v26
	v_mul_f32_e32 v0, s8, v0
	v_mul_f32_e32 v1, s8, v1
	v_lshlrev_b32_e32 v2, 1, v8
	v_cvt_pk_bf16_f32 v206, v0, v1
	v_and_b32_e32 v1, 0xffff0000, v27
	v_lshlrev_b32_e32 v0, 16, v27
	v_mul_f32_e32 v0, s8, v0
	v_mul_f32_e32 v1, s8, v1
	s_nop 0
	v_cvt_pk_bf16_f32 v207, v0, v1
	v_lshlrev_b32_e32 v1, 4, v8
	v_and_b32_e32 v32, 0x70, v1
	v_mul_u32_u24_e32 v1, 0x3000, v33
	v_lshl_add_u32 v240, s4, 4, v1
	v_and_b32_e32 v1, 51, v8
	v_ashrrev_i32_e32 v0, 3, v8
	v_and_or_b32 v1, v2, 8, v1
	v_lshlrev_b32_e32 v1, 1, v1
	v_and_b32_e32 v2, 8, v8
	v_mad_u64_u32 v[8:9], s[8:9], v0, s5, v[32:33]
	s_mulk_i32 s4, 0x480
	v_mul_lo_u32 v36, v0, s7
	v_or3_b32 v9, v1, v2, s4
	s_or_b32 s4, s24, 3
	v_or_b32_e32 v11, v32, v36
	v_lshl_add_u32 v0, v10, 2, 0
	s_mul_i32 s5, s4, 0xc0000
	ds_read_b32 v144, v0 offset:55296
	v_add_u32_e32 v0, s5, v11
	global_load_dwordx4 v[4:7], v0, s[96:97]
	v_add_u32_e32 v10, s5, v240
	s_add_i32 s5, s19, 0x180000
	v_add_u32_e32 v0, s5, v11
	v_add_u32_e32 v11, s19, v11
	v_add_u32_e32 v11, 0xc0000, v11
	global_load_dwordx4 v[208:211], v11, s[96:97]
	v_add_u32_e32 v11, s5, v240
	v_add_u32_e32 v241, 0, v8
	global_load_dwordx4 v[0:3], v0, s[96:97]
	v_add_u32_e32 v242, 0, v9
	global_load_dwordx4 v[212:215], v11, s[36:37]
	s_cmp_gt_i32 s21, 2
	s_waitcnt vmcnt(3)
	ds_write_b128 v241, v[4:7]
	global_load_dwordx4 v[4:7], v10, s[36:37]
	s_waitcnt vmcnt(0)
	ds_write_b16 v242, v4 offset:18432
	ds_write_b16_d16_hi v242, v4 offset:18576
	ds_write_b16 v242, v5 offset:18720
	ds_write_b16_d16_hi v242, v5 offset:18864
	ds_write_b16 v242, v6 offset:19008
	ds_write_b16_d16_hi v242, v6 offset:19152
	ds_write_b16 v242, v7 offset:19296
	ds_write_b16_d16_hi v242, v7 offset:19440
	ds_write_b128 v241, v[0:3] offset:9216
	s_waitcnt lgkmcnt(0)
	s_barrier
	s_cbranch_scc0 .LBB0_379
	s_lshl_b32 s4, s4, 8
	s_add_i32 s4, s4, 0
	v_add_u32_e32 v24, s4, v128
	ds_read_b128 v[0:3], v24 offset:55392
	ds_read_b128 v[16:19], v24 offset:55296
	ds_read_b128 v[4:7], v24 offset:55328
	ds_read_b128 v[8:11], v24 offset:55360
	v_add3_u32 v37, v128, v243, 0
	s_waitcnt lgkmcnt(3)
	v_sub_f32_e32 v15, v144, v3
	v_sub_f32_e32 v14, v144, v2
	v_sub_f32_e32 v13, v144, v1
	v_sub_f32_e32 v12, v144, v0
	s_waitcnt lgkmcnt(0)
	v_sub_f32_e32 v11, v144, v11
	v_sub_f32_e32 v10, v144, v10
	v_sub_f32_e32 v9, v144, v9
	v_sub_f32_e32 v8, v144, v8
	v_sub_f32_e32 v7, v144, v7
	v_sub_f32_e32 v6, v144, v6
	v_sub_f32_e32 v5, v144, v5
	v_sub_f32_e32 v4, v144, v4
	v_sub_f32_e32 v3, v144, v19
	v_sub_f32_e32 v2, v144, v18
	v_sub_f32_e32 v1, v144, v17
	v_sub_f32_e32 v0, v144, v16
	ds_read_b128 v[16:19], v24 offset:55520
	ds_read_b128 v[38:41], v24 offset:55424
	ds_read_b128 v[20:23], v24 offset:55456
	ds_read_b128 v[24:27], v24 offset:55488
	s_waitcnt lgkmcnt(3)
	v_sub_f32_e32 v31, v144, v19
	v_sub_f32_e32 v30, v144, v18
	v_sub_f32_e32 v29, v144, v17
	v_sub_f32_e32 v28, v144, v16
	s_waitcnt lgkmcnt(0)
	v_sub_f32_e32 v27, v144, v27
	v_sub_f32_e32 v26, v144, v26
	v_sub_f32_e32 v25, v144, v25
	v_sub_f32_e32 v24, v144, v24
	v_sub_f32_e32 v23, v144, v23
	v_sub_f32_e32 v22, v144, v22
	v_sub_f32_e32 v21, v144, v21
	v_sub_f32_e32 v20, v144, v20
	v_sub_f32_e32 v19, v144, v41
	v_sub_f32_e32 v18, v144, v40
	v_sub_f32_e32 v17, v144, v39
	v_sub_f32_e32 v16, v144, v38
	ds_read_b128 v[38:41], v37
	ds_read_b128 v[44:47], v37 offset:4608
	ds_read_b128 v[48:51], v37 offset:32
	ds_read_b128 v[52:55], v37 offset:4640
	s_waitcnt lgkmcnt(3)
	v_mfma_f32_32x32x16_bf16 v[0:15], v[38:41], v[192:195], v[0:15]
	ds_read_b128 v[38:41], v37 offset:64
	s_waitcnt lgkmcnt(3)
	v_mfma_f32_32x32x16_bf16 v[16:31], v[44:47], v[192:195], v[16:31]
	ds_read_b128 v[44:47], v37 offset:4672
	s_waitcnt lgkmcnt(3)
	v_mfma_f32_32x32x16_bf16 v[0:15], v[48:51], v[196:199], v[0:15]
	ds_read_b128 v[48:51], v37 offset:96
	s_waitcnt lgkmcnt(3)
	v_mfma_f32_32x32x16_bf16 v[16:31], v[52:55], v[196:199], v[16:31]
	ds_read_b128 v[52:55], v37 offset:4704
	s_waitcnt lgkmcnt(3)
	v_mfma_f32_32x32x16_bf16 v[0:15], v[38:41], v[200:203], v[0:15]
	s_waitcnt lgkmcnt(2)
	v_mfma_f32_32x32x16_bf16 v[16:31], v[44:47], v[200:203], v[16:31]
	s_waitcnt lgkmcnt(1)
	v_mfma_f32_32x32x16_bf16 v[0:15], v[48:51], v[204:207], v[0:15]
	s_waitcnt lgkmcnt(0)
	v_mfma_f32_32x32x16_bf16 v[16:31], v[52:55], v[204:207], v[16:31]
	s_cbranch_execz .LBB0_380
	s_branch .LBB0_381

.LBB0_395:
	v_max_f32_e32 v64, v1, v1
	v_max_f32_e32 v65, v0, v0
	v_max_f32_e32 v64, v65, v64
	v_max3_f32 v64, v64, v2, v3
	v_max3_f32 v64, v64, v4, v5
	v_max3_f32 v64, v64, v6, v7
	v_max3_f32 v64, v64, v8, v9
	v_max3_f32 v64, v64, v10, v11
	v_max3_f32 v64, v64, v12, v13
	v_max3_f32 v64, v64, v14, v15
	v_max3_f32 v64, v64, v16, v17
	v_max3_f32 v64, v64, v18, v19
	v_max3_f32 v64, v64, v20, v21
	v_max3_f32 v64, v64, v22, v23
	v_max3_f32 v64, v64, v24, v25
	v_max3_f32 v64, v64, v26, v27
	v_max3_f32 v64, v64, v28, v29
	v_max3_f32 v64, v64, v30, v31
	v_mov_b32_e32 v65, v64
	v_mov_b32_e32 v66, v64
	s_nop 1
	v_permlane32_swap_b32_e32 v65, v66
	v_cndmask_b32_e64 v65, v65, v66, s[38:39]
	v_max3_f32 v96, v97, v64, v65
	v_cmp_neq_f32_e32 vcc, s2, v96
	s_nop 1
	v_cndmask_b32_e32 v65, 0, v96, vcc
	v_sub_f32_e32 v64, v97, v65
	v_exp_f32_e32 v64, v64
	s_nop 0
	v_cmp_eq_f32_e32 vcc, 1.0, v64
	s_cmp_eq_u64 vcc, exec
	s_cbranch_scc1 .LBB0_397
	v_mul_f32_e32 v46, v46, v64
	v_mul_f32_e32 v47, v47, v64
	v_mul_f32_e32 v44, v44, v64
	v_mul_f32_e32 v45, v45, v64
	v_mul_f32_e32 v42, v42, v64
	v_mul_f32_e32 v43, v43, v64
	v_mul_f32_e32 v40, v40, v64
	v_mul_f32_e32 v41, v41, v64
	v_mul_f32_e32 v38, v38, v64
	v_mul_f32_e32 v39, v39, v64
	v_mul_f32_e32 v36, v36, v64
	v_mul_f32_e32 v37, v37, v64
	v_mul_f32_e32 v34, v34, v64
	v_mul_f32_e32 v35, v35, v64
	v_mul_f32_e32 v32, v32, v64
	v_mul_f32_e32 v33, v33, v64
	v_mul_f32_e32 v62, v62, v64
	v_mul_f32_e32 v63, v63, v64
	v_mul_f32_e32 v60, v60, v64
	v_mul_f32_e32 v61, v61, v64
	v_mul_f32_e32 v58, v58, v64
	v_mul_f32_e32 v59, v59, v64
	v_mul_f32_e32 v56, v56, v64
	v_mul_f32_e32 v57, v57, v64
	v_mul_f32_e32 v54, v54, v64
	v_mul_f32_e32 v55, v55, v64
	v_mul_f32_e32 v52, v52, v64
	v_mul_f32_e32 v53, v53, v64
	v_mul_f32_e32 v50, v50, v64
	v_mul_f32_e32 v51, v51, v64
	v_mul_f32_e32 v48, v48, v64
	v_mul_f32_e32 v49, v49, v64

.LBB0_415:
	v_max_f32_e32 v97, v161, v161
	v_max_f32_e32 v98, v160, v160
	v_max_f32_e32 v97, v98, v97
	v_max3_f32 v97, v97, v162, v163
	v_max3_f32 v97, v97, v164, v165
	v_max3_f32 v97, v97, v166, v167
	v_max3_f32 v97, v97, v168, v169
	v_max3_f32 v97, v97, v170, v171
	v_max3_f32 v97, v97, v172, v173
	v_max3_f32 v97, v97, v174, v175
	v_max3_f32 v97, v97, v176, v177
	v_max3_f32 v97, v97, v178, v179
	v_max3_f32 v97, v97, v180, v181
	v_max3_f32 v97, v97, v182, v183
	v_max3_f32 v97, v97, v184, v185
	v_max3_f32 v97, v97, v186, v187
	v_max3_f32 v97, v97, v188, v189
	v_max3_f32 v97, v97, v190, v191
	v_mov_b32_e32 v98, v97
	v_mov_b32_e32 v99, v97
	s_nop 1
	v_permlane32_swap_b32_e32 v98, v99
	v_cndmask_b32_e64 v98, v98, v99, s[38:39]
	v_max3_f32 v97, v96, v97, v98
	v_cmp_neq_f32_e32 vcc, s2, v97
	s_nop 1
	v_cndmask_b32_e32 v98, 0, v97, vcc
	v_sub_f32_e32 v96, v96, v98
	v_exp_f32_e32 v96, v96
	s_nop 0
	v_cmp_eq_f32_e32 vcc, 1.0, v96
	s_cmp_eq_u64 vcc, exec
	s_cbranch_scc1 .LBB0_417
	v_mul_f32_e32 v46, v46, v96
	v_mul_f32_e32 v47, v47, v96
	v_mul_f32_e32 v44, v44, v96
	v_mul_f32_e32 v45, v45, v96
	v_mul_f32_e32 v42, v42, v96
	v_mul_f32_e32 v43, v43, v96
	v_mul_f32_e32 v40, v40, v96
	v_mul_f32_e32 v41, v41, v96
	v_mul_f32_e32 v38, v38, v96
	v_mul_f32_e32 v39, v39, v96
	v_mul_f32_e32 v36, v36, v96
	v_mul_f32_e32 v37, v37, v96
	v_mul_f32_e32 v34, v34, v96
	v_mul_f32_e32 v35, v35, v96
	v_mul_f32_e32 v32, v32, v96
	v_mul_f32_e32 v33, v33, v96
	v_mul_f32_e32 v62, v62, v96
	v_mul_f32_e32 v63, v63, v96
	v_mul_f32_e32 v60, v60, v96
	v_mul_f32_e32 v61, v61, v96
	v_mul_f32_e32 v58, v58, v96
	v_mul_f32_e32 v59, v59, v96
	v_mul_f32_e32 v56, v56, v96
	v_mul_f32_e32 v57, v57, v96
	v_mul_f32_e32 v54, v54, v96
	v_mul_f32_e32 v55, v55, v96
	v_mul_f32_e32 v52, v52, v96
	v_mul_f32_e32 v53, v53, v96
	v_mul_f32_e32 v50, v50, v96
	v_mul_f32_e32 v51, v51, v96
	v_mul_f32_e32 v48, v48, v96
	v_mul_f32_e32 v49, v49, v96

.LBB0_434:
	v_max_f32_e32 v48, v1, v1
	v_max_f32_e32 v49, v0, v0
	v_max_f32_e32 v48, v49, v48
	v_max3_f32 v48, v48, v2, v3
	v_max3_f32 v48, v48, v4, v5
	v_max3_f32 v48, v48, v6, v7
	v_max3_f32 v48, v48, v8, v9
	v_max3_f32 v48, v48, v10, v11
	v_max3_f32 v48, v48, v12, v13
	v_max3_f32 v48, v48, v14, v15
	v_max3_f32 v48, v48, v16, v17
	v_max3_f32 v48, v48, v18, v19
	v_max3_f32 v48, v48, v20, v21
	v_max3_f32 v48, v48, v22, v23
	v_max3_f32 v48, v48, v24, v25
	v_max3_f32 v48, v48, v26, v27
	v_max3_f32 v48, v48, v28, v29
	v_max3_f32 v48, v48, v30, v31
	v_mov_b32_e32 v49, v48
	v_mov_b32_e32 v50, v48
	s_nop 1
	v_permlane32_swap_b32_e32 v49, v50
	v_cndmask_b32_e64 v49, v49, v50, s[38:39]
	v_max3_f32 v131, v97, v48, v49
	v_cmp_neq_f32_e32 vcc, s2, v131
	s_nop 1
	v_cndmask_b32_e32 v49, 0, v131, vcc
	v_sub_f32_e32 v48, v97, v49
	v_exp_f32_e32 v48, v48
	s_nop 0
	v_cmp_eq_f32_e32 vcc, 1.0, v48
	s_cmp_eq_u64 vcc, exec
	s_cbranch_scc1 .LBB0_436
	v_mul_f32_e32 v46, v46, v48
	v_mul_f32_e32 v47, v47, v48
	v_mul_f32_e32 v44, v44, v48
	v_mul_f32_e32 v45, v45, v48
	v_mul_f32_e32 v42, v42, v48
	v_mul_f32_e32 v43, v43, v48
	v_mul_f32_e32 v40, v40, v48
	v_mul_f32_e32 v41, v41, v48
	v_mul_f32_e32 v38, v38, v48
	v_mul_f32_e32 v39, v39, v48
	v_mul_f32_e32 v36, v36, v48
	v_mul_f32_e32 v37, v37, v48
	v_mul_f32_e32 v34, v34, v48
	v_mul_f32_e32 v35, v35, v48
	v_mul_f32_e32 v32, v32, v48
	v_mul_f32_e32 v33, v33, v48
	v_mul_f32_e32 v94, v94, v48
	v_mul_f32_e32 v95, v95, v48
	v_mul_f32_e32 v92, v92, v48
	v_mul_f32_e32 v93, v93, v48
	v_mul_f32_e32 v90, v90, v48
	v_mul_f32_e32 v91, v91, v48
	v_mul_f32_e32 v88, v88, v48
	v_mul_f32_e32 v89, v89, v48
	v_mul_f32_e32 v86, v86, v48
	v_mul_f32_e32 v87, v87, v48
	v_mul_f32_e32 v84, v84, v48
	v_mul_f32_e32 v85, v85, v48
	v_mul_f32_e32 v82, v82, v48
	v_mul_f32_e32 v83, v83, v48
	v_mul_f32_e32 v80, v80, v48
	v_mul_f32_e32 v81, v81, v48

.LBB0_453:
	v_max_f32_e32 v96, v161, v161
	v_max_f32_e32 v97, v160, v160
	v_max_f32_e32 v96, v97, v96
	v_max3_f32 v96, v96, v162, v163
	v_max3_f32 v96, v96, v164, v165
	v_max3_f32 v96, v96, v166, v167
	v_max3_f32 v96, v96, v168, v169
	v_max3_f32 v96, v96, v170, v171
	v_max3_f32 v96, v96, v172, v173
	v_max3_f32 v96, v96, v174, v175
	v_max3_f32 v96, v96, v176, v177
	v_max3_f32 v96, v96, v178, v179
	v_max3_f32 v96, v96, v180, v181
	v_max3_f32 v96, v96, v182, v183
	v_max3_f32 v96, v96, v184, v185
	v_max3_f32 v96, v96, v186, v187
	v_max3_f32 v96, v96, v188, v189
	v_max3_f32 v96, v96, v190, v191
	v_mov_b32_e32 v97, v96
	v_mov_b32_e32 v98, v96
	s_nop 1
	v_permlane32_swap_b32_e32 v97, v98
	v_cndmask_b32_e64 v97, v97, v98, s[38:39]
	v_max3_f32 v97, v131, v96, v97
	v_cmp_neq_f32_e32 vcc, s2, v97
	s_nop 1
	v_cndmask_b32_e32 v98, 0, v97, vcc
	v_sub_f32_e32 v96, v131, v98
	v_exp_f32_e32 v96, v96
	s_nop 0
	v_cmp_eq_f32_e32 vcc, 1.0, v96
	s_cmp_eq_u64 vcc, exec
	s_cbranch_scc1 .LBB0_455
	v_mul_f32_e32 v46, v46, v96
	v_mul_f32_e32 v47, v47, v96
	v_mul_f32_e32 v44, v44, v96
	v_mul_f32_e32 v45, v45, v96
	v_mul_f32_e32 v42, v42, v96
	v_mul_f32_e32 v43, v43, v96
	v_mul_f32_e32 v40, v40, v96
	v_mul_f32_e32 v41, v41, v96
	v_mul_f32_e32 v38, v38, v96
	v_mul_f32_e32 v39, v39, v96
	v_mul_f32_e32 v36, v36, v96
	v_mul_f32_e32 v37, v37, v96
	v_mul_f32_e32 v34, v34, v96
	v_mul_f32_e32 v35, v35, v96
	v_mul_f32_e32 v32, v32, v96
	v_mul_f32_e32 v33, v33, v96
	v_mul_f32_e32 v62, v62, v96
	v_mul_f32_e32 v63, v63, v96
	v_mul_f32_e32 v60, v60, v96
	v_mul_f32_e32 v61, v61, v96
	v_mul_f32_e32 v58, v58, v96
	v_mul_f32_e32 v59, v59, v96
	v_mul_f32_e32 v56, v56, v96
	v_mul_f32_e32 v57, v57, v96
	v_mul_f32_e32 v54, v54, v96
	v_mul_f32_e32 v55, v55, v96
	v_mul_f32_e32 v52, v52, v96
	v_mul_f32_e32 v53, v53, v96
	v_mul_f32_e32 v50, v50, v96
	v_mul_f32_e32 v51, v51, v96
	v_mul_f32_e32 v48, v48, v96
	v_mul_f32_e32 v49, v49, v96

.LBB0_460:
	v_mov_b32_e32 v0, v250
	v_mov_b32_e32 v1, v250
	s_nop 1
	v_permlane32_swap_b32_e32 v0, v1
	v_cndmask_b32_e64 v0, v0, v1, s[38:39]
	v_add_f32_e32 v0, v250, v0
	v_div_scale_f32 v1, s[4:5], v0, v0, 1.0
	v_rcp_f32_e32 v2, v1
	v_readlane_b32 s4, v255, 38
	s_add_i32 s4, s4, s30
	v_lshrrev_b32_e32 v66, 2, v246
	v_fma_f32 v3, -v1, v2, 1.0
	v_fmac_f32_e32 v2, v3, v2
	v_div_scale_f32 v3, vcc, 1.0, v0, 1.0
	v_and_or_b32 v64, v246, 31, s4
	v_mul_f32_e32 v4, v3, v2
	v_lshl_add_u32 v64, s26, 5, v64
	v_fma_f32 v5, -v1, v4, v3
	v_ashrrev_i32_e32 v65, 31, v64
	v_readlane_b32 s4, v255, 13
	v_fmac_f32_e32 v4, v5, v2
	v_lshlrev_b64 v[64:65], 12, v[64:65]
	v_readlane_b32 s5, v255, 14
	v_fma_f32 v1, -v1, v4, v3
	v_div_fmas_f32 v1, v1, v2, v4
	v_lshl_add_u64 v[64:65], s[4:5], 0, v[64:65]
	v_readlane_b32 s4, v254, 19
	v_readlane_b32 s5, v254, 20
	v_readlane_b32 s4, v255, 39
	v_div_fixup_f32 v0, v1, v0, 1.0
	s_mov_b32 s7, s5
	s_lshl_b32 s6, s4, 1
	v_mul_f32_e32 v2, v46, v0
	v_mul_f32_e32 v3, v47, v0
	v_mul_f32_e32 v4, v44, v0
	v_mul_f32_e32 v5, v45, v0
	v_mul_f32_e32 v6, v42, v0
	v_mul_f32_e32 v7, v43, v0
	v_mul_f32_e32 v8, v40, v0
	v_mul_f32_e32 v9, v41, v0
	v_mul_f32_e32 v10, v38, v0
	v_mul_f32_e32 v11, v39, v0
	v_mul_f32_e32 v12, v36, v0
	v_mul_f32_e32 v13, v37, v0
	v_mul_f32_e32 v14, v34, v0
	v_mul_f32_e32 v15, v35, v0
	v_mul_f32_e32 v16, v32, v0
	v_mul_f32_e32 v17, v33, v0
	v_mul_f32_e32 v18, v62, v0
	v_mul_f32_e32 v19, v63, v0
	v_mul_f32_e32 v20, v60, v0
	v_mul_f32_e32 v21, v61, v0
	v_mul_f32_e32 v22, v58, v0
	v_mul_f32_e32 v23, v59, v0
	v_mul_f32_e32 v24, v56, v0
	v_mul_f32_e32 v25, v57, v0
	v_mul_f32_e32 v26, v54, v0
	v_mul_f32_e32 v27, v55, v0
	v_mul_f32_e32 v28, v52, v0
	v_mul_f32_e32 v29, v53, v0
	v_mul_f32_e32 v30, v50, v0
	v_mul_f32_e32 v31, v51, v0
	v_mul_f32_e32 v1, v49, v0
	v_mul_f32_e32 v0, v48, v0
	v_lshl_add_u64 v[64:65], v[64:65], 0, s[6:7]
	v_and_b32_e32 v128, 8, v66
	v_lshl_add_u64 v[64:65], v[64:65], 0, v[128:129]
	v_cvt_pk_bf16_f32 v0, v0, v1
	v_cvt_pk_bf16_f32 v1, v30, v31
	v_writelane_b32 v254, s4, 19
	global_store_dwordx2 v[64:65], v[0:1], off offset:64
	v_cvt_pk_bf16_f32 v0, v28, v29
	v_cvt_pk_bf16_f32 v1, v26, v27
	v_writelane_b32 v254, s5, 20
	v_cvt_pk_bf16_f32 v16, v16, v17
	v_cvt_pk_bf16_f32 v17, v14, v15
	v_cvt_pk_bf16_f32 v12, v12, v13
	v_cvt_pk_bf16_f32 v13, v10, v11
	v_cvt_pk_bf16_f32 v8, v8, v9
	v_cvt_pk_bf16_f32 v9, v6, v7
	v_cvt_pk_bf16_f32 v4, v4, v5
	v_cvt_pk_bf16_f32 v5, v2, v3
	global_store_dwordx2 v[64:65], v[0:1], off offset:80
	v_cvt_pk_bf16_f32 v0, v24, v25
	v_cvt_pk_bf16_f32 v1, v22, v23
	s_mov_b64 s[4:5], 0x70
	v_readlane_b32 s30, v255, 3
	v_readlane_b32 s22, v255, 16
	global_store_dwordx2 v[64:65], v[16:17], off
	global_store_dwordx2 v[64:65], v[12:13], off offset:16
	global_store_dwordx2 v[64:65], v[8:9], off offset:32
	global_store_dwordx2 v[64:65], v[4:5], off offset:48
	global_store_dwordx2 v[64:65], v[0:1], off offset:96
	v_cvt_pk_bf16_f32 v0, v20, v21
	v_cvt_pk_bf16_f32 v1, v18, v19
	v_lshl_add_u64 v[2:3], v[64:65], 0, s[4:5]
	s_mov_b64 s[4:5], 0
	v_readlane_b32 s31, v255, 4
	v_readlane_b32 s23, v255, 17
	s_mul_hi_i32 s9, s27, 0x1800000
	s_mul_i32 s10, s27, 0x1800000
	s_waitcnt vmcnt(7)
	v_mov_b32_e32 v232, 1
	v_mov_b32_e32 v233, 0x260
	v_mov_b64_e32 v[234:235], 0x100
	v_mov_b64_e32 v[236:237], 0xff
	v_mov_b32_e32 v238, 0x42800000
	v_mov_b32_e32 v239, 6
	v_mov_b32_e32 v240, 4
	v_mov_b32_e32 v241, v249
	v_mov_b32_e32 v242, 12
.LBB0_461:
	s_and_b64 vcc, exec, s[4:5]
	s_cbranch_vccz .LBB0_477
	s_lshl_b32 s17, s28, 8
	s_lshl_b32 s8, s28, 2
	v_readlane_b32 s4, v255, 11
	v_readlane_b32 s5, v255, 12
	s_add_u32 s4, s4, s10
	s_addc_u32 s5, s5, s9
	s_lshl_b32 s16, s29, 6
	s_lshl_b32 s6, s29, 7
	s_add_u32 s4, s4, s6
	v_mov_b32_e32 v94, v241
	s_addc_u32 s5, s5, 0
	v_mov_b32_e32 v30, v241
	s_add_u32 s6, s4, 0x1000
	s_addc_u32 s7, s5, 0
	v_readfirstlane_b32 s11, v30
	s_ashr_i32 s10, s11, 6
	s_lshl_b32 s9, s10, 5
	v_and_b32_e32 v31, 31, v30
	s_add_i32 s18, s9, s17
	v_bfe_u32 v32, v30, 5, 1
	v_or_b32_e32 v2, s18, v31
	v_mov_b64_e32 v[0:1], s[4:5]
	s_movk_i32 s19, 0x3000
	v_mad_i64_i32 v[0:1], s[14:15], v2, s19, v[0:1]
	v_lshlrev_b32_e32 v128, 4, v32
	v_lshl_add_u64 v[12:13], v[0:1], 0, v[128:129]
	global_load_dwordx4 v[0:3], v[12:13], off offset:3072
	global_load_dwordx4 v[4:7], v[12:13], off offset:3104
	global_load_dwordx4 v[8:11], v[12:13], off offset:3136
	s_nop 0
	global_load_dwordx4 v[12:15], v[12:13], off offset:3168
	v_and_b32_e32 v33, 63, v30
	v_lshlrev_b32_e32 v16, 4, v30
	v_mul_u32_u24_e32 v20, 0x1800, v33
	v_mov_b32_e32 v17, v129
	v_and_b32_e32 v18, 0x70, v16
	v_lshlrev_b32_e32 v16, 1, v20
	v_ashrrev_i32_e32 v34, 3, v30
	v_lshl_add_u64 v[16:17], s[4:5], 0, v[16:17]
	s_lshl_b32 s4, s10, 3
	v_mov_b64_e32 v[20:21], s[6:7]
	v_mov_b32_e32 v19, v129
	s_ashr_i32 s5, s4, 31
	v_mad_i64_i32 v[20:21], s[6:7], v34, s19, v[20:21]
	s_or_b32 s14, s8, 3
	v_lshl_add_u64 v[88:89], v[20:21], 0, v[18:19]
	v_lshl_add_u64 v[16:17], s[4:5], 1, v[16:17]
	s_mov_b64 s[4:5], 0x1400
	v_lshl_add_u64 v[90:91], v[16:17], 0, s[4:5]
	v_mad_u64_u32 v[16:17], s[4:5], s14, v248, v[88:89]
	global_load_dwordx4 v[68:71], v[16:17], off
	v_mad_u64_u32 v[16:17], s[4:5], s14, v248, v[90:91]
	global_load_dwordx4 v[76:79], v[16:17], off
	s_mov_b32 s4, 0x3e38aa3b
	s_addk_i32 s9, 0xff40
	s_ashr_i32 s21, s11, 7
	v_mov_b32_e32 v93, 0
	v_readfirstlane_b32 s19, v94
	s_mov_b32 s23, 1
	s_add_i32 s20, s8, 4
	s_add_i32 s21, s21, s8
	v_cmp_gt_u32_e64 s[38:39], 32, v33
	v_cmp_eq_u32_e64 s[40:41], 0, v33
	s_or_b32 s24, s8, 2
	v_mov_b32_e32 v19, v93
	s_waitcnt vmcnt(5)
	v_and_b32_e32 v17, 0xffff0000, v0
	v_lshlrev_b32_e32 v16, 16, v0
	v_and_b32_e32 v21, 0xffff0000, v1
	v_lshlrev_b32_e32 v20, 16, v1
	v_and_b32_e32 v1, 0xffff0000, v2
	v_lshlrev_b32_e32 v0, 16, v2
	v_mul_f32_e32 v0, s4, v0
	v_mul_f32_e32 v1, s4, v1
	v_and_b32_e32 v23, 0xffff0000, v3
	v_cvt_pk_bf16_f32 v66, v0, v1
	s_waitcnt vmcnt(3)
	v_and_b32_e32 v1, 0xffff0000, v10
	v_lshlrev_b32_e32 v0, 16, v10
	v_mul_f32_e32 v0, s4, v0
	v_mul_f32_e32 v1, s4, v1
	v_lshlrev_b32_e32 v22, 16, v3
	v_cvt_pk_bf16_f32 v82, v0, v1
	v_and_b32_e32 v1, 0xffff0000, v11
	v_lshlrev_b32_e32 v0, 16, v11
	v_mul_f32_e32 v0, s4, v0
	v_mul_f32_e32 v1, s4, v1
	v_and_b32_e32 v3, 0xffff0000, v4
	v_cvt_pk_bf16_f32 v83, v0, v1
	s_waitcnt vmcnt(2)
	v_and_b32_e32 v1, 0xffff0000, v12
	v_lshlrev_b32_e32 v0, 16, v12
	v_mul_f32_e32 v0, s4, v0
	v_mul_f32_e32 v1, s4, v1
	v_lshlrev_b32_e32 v2, 16, v4
	v_cvt_pk_bf16_f32 v84, v0, v1
	v_and_b32_e32 v1, 0xffff0000, v13
	v_lshlrev_b32_e32 v0, 16, v13
	v_mul_f32_e32 v0, s4, v0
	v_mul_f32_e32 v1, s4, v1
	v_and_b32_e32 v25, 0xffff0000, v5
	v_cvt_pk_bf16_f32 v85, v0, v1
	v_and_b32_e32 v1, 0xffff0000, v14
	v_lshlrev_b32_e32 v0, 16, v14
	v_mul_f32_e32 v0, s4, v0
	v_mul_f32_e32 v1, s4, v1
	v_lshlrev_b32_e32 v24, 16, v5
	v_cvt_pk_bf16_f32 v86, v0, v1
	v_and_b32_e32 v1, 0xffff0000, v15
	v_lshlrev_b32_e32 v0, 16, v15
	v_mul_f32_e32 v0, s4, v0
	v_mul_f32_e32 v1, s4, v1
	v_and_b32_e32 v5, 0xffff0000, v6
	v_cvt_pk_bf16_f32 v87, v0, v1
	v_and_b32_e32 v0, 51, v30
	v_lshlrev_b32_e32 v1, 1, v30
	v_lshlrev_b32_e32 v4, 16, v6
	v_and_b32_e32 v27, 0xffff0000, v7
	v_lshlrev_b32_e32 v26, 16, v7
	v_and_b32_e32 v7, 0xffff0000, v8
	v_lshlrev_b32_e32 v6, 16, v8
	v_and_b32_e32 v29, 0xffff0000, v9
	v_lshlrev_b32_e32 v28, 16, v9
	v_and_or_b32 v0, v1, 8, v0
	v_mul_f32_e32 v8, s4, v16
	v_mul_f32_e32 v9, s4, v17
	v_mul_f32_e32 v16, s4, v20
	v_mul_f32_e32 v17, s4, v21
	v_mul_f32_e32 v20, s4, v22
	v_mul_f32_e32 v21, s4, v23
	v_mul_f32_e32 v2, s4, v2
	v_mul_f32_e32 v3, s4, v3
	v_mul_f32_e32 v22, s4, v24
	v_mul_f32_e32 v23, s4, v25
	v_mul_f32_e32 v4, s4, v4
	v_mul_f32_e32 v5, s4, v5
	v_mul_f32_e32 v24, s4, v26
	v_mul_f32_e32 v25, s4, v27
	v_mul_f32_e32 v6, s4, v6
	v_mul_f32_e32 v7, s4, v7
	v_mul_f32_e32 v26, s4, v28
	v_mul_f32_e32 v27, s4, v29
	s_mul_i32 s4, s10, 0x480
	v_lshlrev_b32_e32 v0, 1, v0
	v_and_b32_e32 v1, 8, v30
	v_or3_b32 v0, v0, v1, s4
	s_movk_i32 s4, 0x90
	v_mul_lo_u32 v1, v34, s4
	v_add_u32_e32 v96, 0, v0
	s_lshl_b32 s4, s10, 2
	v_mul_u32_u24_e32 v0, 0x90, v31
	v_add3_u32 v95, 0, v1, v18
	s_add_i32 s22, s4, 0
	v_add3_u32 v97, 0, v0, v128
	v_lshlrev_b32_e32 v0, 2, v32
	v_or_b32_e32 v1, s9, v31
	s_or_b32 s4, s17, 0xff
	v_cvt_pk_bf16_f32 v64, v8, v9
	v_cvt_pk_bf16_f32 v65, v16, v17
	v_cvt_pk_bf16_f32 v67, v20, v21
	v_cvt_pk_bf16_f32 v72, v2, v3
	v_cvt_pk_bf16_f32 v73, v22, v23
	v_cvt_pk_bf16_f32 v74, v4, v5
	v_cvt_pk_bf16_f32 v75, v24, v25
	v_cvt_pk_bf16_f32 v80, v6, v7
	v_cvt_pk_bf16_f32 v81, v26, v27
	v_sub_u32_e32 v98, v1, v0
	v_mov_b32_e32 v99, s4
	v_mov_b32_e32 v16, v93
	v_mov_b32_e32 v17, v93
	v_mov_b32_e32 v18, v93
	v_mov_b32_e32 v20, v93
	v_mov_b32_e32 v21, v93
	v_mov_b32_e32 v22, v93
	v_mov_b32_e32 v23, v93
	v_mov_b32_e32 v24, v93
	v_mov_b32_e32 v25, v93
	v_mov_b32_e32 v26, v93
	v_mov_b32_e32 v27, v93
	v_mov_b32_e32 v28, v93
	v_mov_b32_e32 v29, v93
	v_mov_b32_e32 v30, v93
	v_mov_b32_e32 v31, v93
	v_mov_b32_e32 v0, v93
	v_mov_b32_e32 v1, v93
	v_mov_b32_e32 v2, v93
	v_mov_b32_e32 v3, v93
	v_mov_b32_e32 v4, v93
	v_mov_b32_e32 v5, v93
	v_mov_b32_e32 v6, v93
	v_mov_b32_e32 v7, v93
	v_mov_b32_e32 v8, v93
	v_mov_b32_e32 v9, v93
	v_mov_b32_e32 v10, v93
	v_mov_b32_e32 v11, v93
	v_mov_b32_e32 v12, v93
	v_mov_b32_e32 v13, v93
	v_mov_b32_e32 v14, v93
	v_mov_b32_e32 v15, v93
	s_waitcnt vmcnt(1)
	ds_write_b128 v95, v[68:71]
	s_waitcnt vmcnt(0)
	ds_write_b16 v96, v76 offset:18432
	ds_write_b16_d16_hi v96, v76 offset:18576
	ds_write_b16 v96, v77 offset:18720
	ds_write_b16_d16_hi v96, v77 offset:18864
	ds_write_b16 v96, v78 offset:19008
	ds_write_b16_d16_hi v96, v78 offset:19152
	ds_write_b16 v96, v79 offset:19296
	ds_write_b16_d16_hi v96, v79 offset:19440
	s_waitcnt lgkmcnt(0)
	s_barrier
	s_branch .LBB0_464

.LBB0_467:
	s_add_i32 s4, s23, -1
	s_add_i32 s5, s24, 1
	s_and_b32 s25, s4, 1
	s_cmp_gt_i32 s5, s21
	s_cbranch_scc1 .LBB0_471
	s_cmp_eq_u32 s25, 0
	s_cselect_b64 s[14:15], -1, 0
	s_and_b64 s[4:5], s[14:15], exec
	s_cselect_b32 s4, 0, 0x2400
	v_add_u32_e32 v92, s4, v97
	ds_read_b128 v[32:35], v92
	ds_read_b128 v[100:103], v92 offset:32
	v_cmp_lt_i32_e64 s[42:43], 0, v98
	v_cmp_lt_i32_e64 s[44:45], 1, v98
	v_cmp_lt_i32_e32 vcc, s18, v99
	s_waitcnt lgkmcnt(1)
	v_mfma_f32_32x32x16_bf16 v[48:63], v[32:35], v[64:67], 0
	ds_read_b128 v[32:35], v92 offset:4608
	ds_read_b128 v[104:107], v92 offset:4640
	v_cmp_lt_i32_e64 s[46:47], 2, v98
	v_cmp_lt_i32_e64 s[48:49], 3, v98
	v_cmp_lt_i32_e64 s[50:51], 8, v98
	v_cmp_lt_i32_e64 s[52:53], 9, v98
	v_cmp_lt_i32_e64 s[54:55], 10, v98
	v_cmp_lt_i32_e64 s[56:57], 11, v98
	s_waitcnt lgkmcnt(2)
	v_mfma_f32_32x32x16_bf16 v[48:63], v[100:103], v[72:75], v[48:63]
	ds_read_b128 v[100:103], v92 offset:64
	ds_read_b128 v[108:111], v92 offset:96
	v_cmp_lt_i32_e64 s[58:59], 16, v98
	v_cmp_lt_i32_e64 s[60:61], 17, v98
	v_cmp_lt_i32_e64 s[62:63], 18, v98
	v_cmp_lt_i32_e64 s[66:67], 19, v98
	v_cmp_lt_i32_e64 s[68:69], 24, v98
	v_cmp_lt_i32_e64 s[72:73], 25, v98
	s_waitcnt lgkmcnt(1)
	v_mfma_f32_32x32x16_bf16 v[48:63], v[100:103], v[80:83], v[48:63]
	ds_read_b128 v[100:103], v92 offset:4672
	ds_read_b128 v[112:115], v92 offset:4704
	v_cmp_lt_i32_e64 s[76:77], 26, v98
	v_cmp_lt_i32_e64 s[64:65], 27, v98
	v_cmp_lt_i32_e64 s[70:71], 32, v98
	v_cmp_lt_i32_e64 s[74:75], 33, v98
	v_cmp_lt_i32_e64 s[78:79], 34, v98
	v_cmp_lt_i32_e64 s[80:81], 35, v98
	s_waitcnt lgkmcnt(2)
	v_mfma_f32_32x32x16_bf16 v[48:63], v[108:111], v[84:87], v[48:63]
	v_cmp_lt_i32_e64 s[82:83], 40, v98
	v_cmp_lt_i32_e64 s[84:85], 41, v98
	v_cmp_lt_i32_e64 s[86:87], 42, v98
	v_cmp_lt_i32_e64 s[88:89], 43, v98
	v_cmp_lt_i32_e64 s[90:91], 48, v98
	v_cmp_lt_i32_e64 s[92:93], 49, v98
	v_cmp_lt_i32_e64 s[94:95], 50, v98
	v_mfma_f32_32x32x16_bf16 v[32:47], v[32:35], v[64:67], 0
	s_nop 3
	v_exp_f32_e64 v92, -|v48|
	v_exp_f32_e64 v109, -|v49|
	v_exp_f32_e64 v111, -|v50|
	v_max_f32_e32 v108, v48, v48
	v_exp_f32_e64 v117, -|v51|
	v_add_f32_e32 v92, 1.0, v92
	v_log_f32_e32 v92, v92
	v_mfma_f32_32x32x16_bf16 v[32:47], v[104:107], v[72:75], v[32:47]
	v_min_f32_e32 v104, 0, v108
	v_add_f32_e32 v108, 1.0, v109
	v_log_f32_e32 v108, v108
	v_max_f32_e32 v110, v49, v49
	v_add_f32_e32 v109, 1.0, v111
	v_min_f32_e32 v105, 0, v110
	v_add_f32_e32 v110, 1.0, v117
	v_log_f32_e32 v109, v109
	v_exp_f32_e64 v119, -|v52|
	v_log_f32_e32 v110, v110
	v_max_f32_e32 v116, v50, v50
	s_waitcnt lgkmcnt(1)
	v_mfma_f32_32x32x16_bf16 v[32:47], v[100:103], v[80:83], v[32:47]
	v_sub_f32_e32 v100, v104, v92
	v_sub_f32_e32 v101, v105, v108
	v_max_f32_e32 v118, v51, v51
	v_min_f32_e32 v106, 0, v116
	v_sub_f32_e32 v48, v100, v48
	v_sub_f32_e32 v49, v101, v49
	v_min_f32_e32 v107, 0, v118
	v_sub_f32_e32 v102, v106, v109
	v_cndmask_b32_e64 v92, 0, v48, s[42:43]
	v_cndmask_b32_e64 v104, 0, v49, s[44:45]
	v_sub_f32_e32 v103, v107, v110
	v_sub_f32_e32 v50, v102, v50
	v_cndmask_b32_e32 v92, v48, v92, vcc
	v_cndmask_b32_e32 v48, v49, v104, vcc
	v_add_f32_e32 v104, 1.0, v119
	v_sub_f32_e32 v51, v103, v51
	v_cndmask_b32_e64 v105, 0, v50, s[46:47]
	v_log_f32_e32 v104, v104
	v_cndmask_b32_e32 v49, v50, v105, vcc
	v_cndmask_b32_e64 v50, 0, v51, s[48:49]
	v_cndmask_b32_e32 v50, v51, v50, vcc
	v_max_f32_e32 v51, v52, v52
	v_min_f32_e32 v51, 0, v51
	v_sub_f32_e32 v51, v51, v104
	v_exp_f32_e64 v104, -|v53|
	v_sub_f32_e32 v52, v51, v52
	v_cndmask_b32_e64 v105, 0, v52, s[50:51]
	v_cndmask_b32_e32 v107, v52, v105, vcc
	v_add_f32_e32 v104, 1.0, v104
	v_log_f32_e32 v104, v104
	v_max_f32_e32 v52, v53, v53
	v_min_f32_e32 v52, 0, v52
	s_waitcnt lgkmcnt(0)
	v_mfma_f32_32x32x16_bf16 v[32:47], v[112:115], v[84:87], v[32:47]
	v_sub_f32_e32 v52, v52, v104
	v_exp_f32_e64 v104, -|v54|
	v_sub_f32_e32 v53, v52, v53
	v_cndmask_b32_e64 v105, 0, v53, s[52:53]
	v_cndmask_b32_e32 v53, v53, v105, vcc
	v_add_f32_e32 v104, 1.0, v104
	v_log_f32_e32 v104, v104
	v_max_f32_e32 v105, v54, v54
	v_min_f32_e32 v105, 0, v105
	v_cmp_lt_i32_e64 s[96:97], 51, v98
	v_sub_f32_e32 v104, v105, v104
	v_exp_f32_e64 v105, -|v55|
	v_sub_f32_e32 v54, v104, v54
	v_cndmask_b32_e64 v106, 0, v54, s[54:55]
	v_cndmask_b32_e32 v54, v54, v106, vcc
	v_add_f32_e32 v105, 1.0, v105
	v_log_f32_e32 v105, v105
	v_max_f32_e32 v106, v55, v55
	v_min_f32_e32 v106, 0, v106
	v_cmp_lt_i32_e64 s[4:5], 56, v98
	v_sub_f32_e32 v105, v106, v105
	v_exp_f32_e64 v106, -|v56|
	v_sub_f32_e32 v55, v105, v55
	v_cndmask_b32_e64 v108, 0, v55, s[56:57]
	v_cndmask_b32_e32 v55, v55, v108, vcc
	v_add_f32_e32 v106, 1.0, v106
	v_log_f32_e32 v106, v106
	v_max_f32_e32 v108, v56, v56
	v_min_f32_e32 v108, 0, v108
	v_cmp_lt_i32_e64 s[6:7], 57, v98
	v_sub_f32_e32 v106, v108, v106
	v_exp_f32_e64 v108, -|v57|
	v_sub_f32_e32 v56, v106, v56
	v_cndmask_b32_e64 v109, 0, v56, s[58:59]
	v_cndmask_b32_e32 v109, v56, v109, vcc
	v_add_f32_e32 v108, 1.0, v108
	v_log_f32_e32 v108, v108
	v_max_f32_e32 v56, v57, v57
	v_min_f32_e32 v56, 0, v56
	v_cmp_lt_i32_e64 s[8:9], 58, v98
	v_sub_f32_e32 v56, v56, v108
	v_exp_f32_e64 v108, -|v58|
	v_sub_f32_e32 v57, v56, v57
	v_cndmask_b32_e64 v110, 0, v57, s[60:61]
	v_cndmask_b32_e32 v111, v57, v110, vcc
	v_add_f32_e32 v108, 1.0, v108
	v_log_f32_e32 v108, v108
	v_max_f32_e32 v57, v58, v58
	v_min_f32_e32 v57, 0, v57
	v_cmp_lt_i32_e64 s[10:11], 59, v98
	v_sub_f32_e32 v118, v57, v108
	v_exp_f32_e64 v57, -|v59|
	v_sub_f32_e32 v58, v118, v58
	v_cndmask_b32_e64 v108, 0, v58, s[62:63]
	v_cndmask_b32_e32 v119, v58, v108, vcc
	v_add_f32_e32 v57, 1.0, v57
	v_log_f32_e32 v57, v57
	v_max_f32_e32 v58, v59, v59
	v_min_f32_e32 v58, 0, v58
	v_sub_f32_e32 v120, v58, v57
	v_exp_f32_e64 v57, -|v60|
	v_sub_f32_e32 v58, v120, v59
	v_cndmask_b32_e64 v59, 0, v58, s[66:67]
	v_cndmask_b32_e32 v121, v58, v59, vcc
	v_add_f32_e32 v57, 1.0, v57
	v_log_f32_e32 v57, v57
	v_max_f32_e32 v58, v60, v60
	v_min_f32_e32 v58, 0, v58
	v_sub_f32_e32 v113, v58, v57
	v_exp_f32_e64 v57, -|v61|
	v_sub_f32_e32 v58, v113, v60
	v_cndmask_b32_e64 v59, 0, v58, s[68:69]
	v_cndmask_b32_e32 v58, v58, v59, vcc
	v_add_f32_e32 v57, 1.0, v57
	v_log_f32_e32 v57, v57
	v_max_f32_e32 v59, v61, v61
	v_min_f32_e32 v59, 0, v59
	v_sub_f32_e32 v115, v59, v57
	v_exp_f32_e64 v57, -|v62|
	v_sub_f32_e32 v59, v115, v61
	v_cndmask_b32_e64 v60, 0, v59, s[72:73]
	v_cndmask_b32_e32 v122, v59, v60, vcc
	v_add_f32_e32 v57, 1.0, v57
	v_log_f32_e32 v57, v57
	v_max_f32_e32 v59, v62, v62
	v_min_f32_e32 v59, 0, v59
	v_sub_f32_e32 v123, v59, v57
	v_exp_f32_e64 v57, -|v63|
	v_sub_f32_e32 v59, v123, v62
	v_cndmask_b32_e64 v60, 0, v59, s[76:77]
	v_cndmask_b32_e32 v124, v59, v60, vcc
	v_add_f32_e32 v57, 1.0, v57
	v_log_f32_e32 v57, v57
	v_max_f32_e32 v59, v63, v63
	v_min_f32_e32 v59, 0, v59
	v_sub_f32_e32 v125, v59, v57
	v_exp_f32_e64 v57, -|v32|
	v_sub_f32_e32 v59, v125, v63
	v_cndmask_b32_e64 v60, 0, v59, s[64:65]
	v_cndmask_b32_e32 v126, v59, v60, vcc
	v_add_f32_e32 v57, 1.0, v57
	v_log_f32_e32 v57, v57
	v_max_f32_e32 v59, v32, v32
	v_min_f32_e32 v59, 0, v59
	v_sub_f32_e32 v61, v59, v57
	v_exp_f32_e64 v57, -|v33|
	v_sub_f32_e32 v32, v61, v32
	v_cndmask_b32_e64 v59, 0, v32, s[70:71]
	v_cndmask_b32_e32 v59, v32, v59, vcc
	v_add_f32_e32 v57, 1.0, v57
	v_log_f32_e32 v57, v57
	v_max_f32_e32 v32, v33, v33
	v_min_f32_e32 v32, 0, v32
	v_sub_f32_e32 v57, v32, v57
	v_exp_f32_e64 v32, -|v34|
	v_sub_f32_e32 v33, v57, v33
	v_cndmask_b32_e64 v60, 0, v33, s[74:75]
	v_cndmask_b32_e32 v63, v33, v60, vcc
	v_add_f32_e32 v32, 1.0, v32
	v_log_f32_e32 v32, v32
	v_max_f32_e32 v33, v34, v34
	v_min_f32_e32 v33, 0, v33
	v_sub_f32_e32 v127, v33, v32
	v_exp_f32_e64 v32, -|v35|
	v_sub_f32_e32 v33, v127, v34
	v_cndmask_b32_e64 v34, 0, v33, s[78:79]
	v_cndmask_b32_e32 v128, v33, v34, vcc
	v_add_f32_e32 v32, 1.0, v32
	v_log_f32_e32 v32, v32
	v_max_f32_e32 v33, v35, v35
	v_min_f32_e32 v33, 0, v33
	v_sub_f32_e32 v130, v33, v32
	v_exp_f32_e64 v32, -|v36|
	v_sub_f32_e32 v33, v130, v35
	v_cndmask_b32_e64 v34, 0, v33, s[80:81]
	v_cndmask_b32_e32 v131, v33, v34, vcc
	v_add_f32_e32 v32, 1.0, v32
	v_log_f32_e32 v32, v32
	v_max_f32_e32 v33, v36, v36
	v_min_f32_e32 v33, 0, v33
	v_sub_f32_e32 v132, v33, v32
	v_exp_f32_e64 v32, -|v37|
	v_sub_f32_e32 v33, v132, v36
	v_cndmask_b32_e64 v34, 0, v33, s[82:83]
	v_cndmask_b32_e32 v35, v33, v34, vcc
	v_add_f32_e32 v32, 1.0, v32
	v_log_f32_e32 v32, v32
	v_max_f32_e32 v33, v37, v37
	v_min_f32_e32 v33, 0, v33
	v_sub_f32_e32 v133, v33, v32
	v_exp_f32_e64 v32, -|v38|
	v_sub_f32_e32 v33, v133, v37
	v_cndmask_b32_e64 v34, 0, v33, s[84:85]
	v_cndmask_b32_e32 v134, v33, v34, vcc
	v_add_f32_e32 v32, 1.0, v32
	v_log_f32_e32 v32, v32
	v_max_f32_e32 v33, v38, v38
	v_min_f32_e32 v33, 0, v33
	v_add_f32_e32 v35, v35, v134
	v_sub_f32_e32 v135, v33, v32
	v_exp_f32_e64 v32, -|v39|
	v_sub_f32_e32 v33, v135, v38
	v_cndmask_b32_e64 v34, 0, v33, s[86:87]
	v_cndmask_b32_e32 v136, v33, v34, vcc
	v_add_f32_e32 v32, 1.0, v32
	v_log_f32_e32 v32, v32
	v_max_f32_e32 v33, v39, v39
	v_min_f32_e32 v33, 0, v33
	v_sub_f32_e32 v137, v33, v32
	v_exp_f32_e64 v32, -|v40|
	v_sub_f32_e32 v33, v137, v39
	v_cndmask_b32_e64 v34, 0, v33, s[88:89]
	v_cndmask_b32_e32 v138, v33, v34, vcc
	v_add_f32_e32 v32, 1.0, v32
	v_log_f32_e32 v32, v32
	v_max_f32_e32 v33, v40, v40
	v_min_f32_e32 v33, 0, v33
	v_add_f32_e32 v39, v54, v55
	v_sub_f32_e32 v139, v33, v32
	v_exp_f32_e64 v32, -|v41|
	v_sub_f32_e32 v33, v139, v40
	v_cndmask_b32_e64 v34, 0, v33, s[90:91]
	v_cndmask_b32_e32 v34, v33, v34, vcc
	v_add_f32_e32 v32, 1.0, v32
	v_log_f32_e32 v32, v32
	v_max_f32_e32 v33, v41, v41
	v_min_f32_e32 v33, 0, v33
	v_sub_f32_e32 v140, v33, v32
	v_exp_f32_e64 v32, -|v42|
	v_sub_f32_e32 v33, v140, v41
	v_cndmask_b32_e64 v36, 0, v33, s[92:93]
	v_cndmask_b32_e32 v38, v33, v36, vcc
	v_add_f32_e32 v32, 1.0, v32
	v_log_f32_e32 v32, v32
	v_max_f32_e32 v33, v42, v42
	v_min_f32_e32 v33, 0, v33
	v_sub_f32_e32 v141, v33, v32
	v_exp_f32_e64 v32, -|v43|
	v_sub_f32_e32 v33, v141, v42
	v_cndmask_b32_e64 v36, 0, v33, s[94:95]
	v_cndmask_b32_e32 v142, v33, v36, vcc
	v_add_f32_e32 v32, 1.0, v32
	v_log_f32_e32 v32, v32
	v_max_f32_e32 v33, v43, v43
	v_min_f32_e32 v33, 0, v33
	v_sub_f32_e32 v143, v33, v32
	v_exp_f32_e64 v32, -|v44|
	v_sub_f32_e32 v33, v143, v43
	v_cndmask_b32_e64 v36, 0, v33, s[96:97]
	v_cndmask_b32_e32 v43, v33, v36, vcc
	v_add_f32_e32 v32, 1.0, v32
	v_log_f32_e32 v32, v32
	v_max_f32_e32 v33, v44, v44
	v_min_f32_e32 v33, 0, v33
	v_sub_f32_e32 v116, v33, v32
	v_exp_f32_e64 v32, -|v45|
	v_sub_f32_e32 v33, v116, v44
	v_cndmask_b32_e64 v36, 0, v33, s[4:5]
	v_cndmask_b32_e32 v37, v33, v36, vcc
	v_add_f32_e32 v32, 1.0, v32
	v_log_f32_e32 v32, v32
	v_max_f32_e32 v33, v45, v45
	v_min_f32_e32 v33, 0, v33
	v_sub_f32_e32 v117, v33, v32
	v_exp_f32_e64 v32, -|v46|
	v_sub_f32_e32 v33, v117, v45
	v_cndmask_b32_e64 v36, 0, v33, s[6:7]
	v_cndmask_b32_e32 v45, v33, v36, vcc
	v_add_f32_e32 v32, 1.0, v32
	v_log_f32_e32 v32, v32
	v_max_f32_e32 v33, v46, v46
	v_min_f32_e32 v33, 0, v33
	v_sub_f32_e32 v144, v33, v32
	v_exp_f32_e64 v32, -|v47|
	v_sub_f32_e32 v33, v144, v46
	v_cndmask_b32_e64 v36, 0, v33, s[8:9]
	v_cndmask_b32_e32 v145, v33, v36, vcc
	v_add_f32_e32 v32, 1.0, v32
	v_log_f32_e32 v32, v32
	v_max_f32_e32 v33, v47, v47
	v_min_f32_e32 v33, 0, v33
	v_sub_f32_e32 v146, v33, v32
	v_sub_f32_e32 v32, v146, v47
	v_cndmask_b32_e64 v33, 0, v32, s[10:11]
	v_cndmask_b32_e32 v47, v32, v33, vcc
	v_add_f32_e32 v32, v92, v48
	v_add_f32_e32 v33, v49, v50
	v_add_f32_e32 v32, v32, v33
	v_mov_b32_e32 v33, v32
	v_mov_b32_e32 v36, v32
	s_nop 1
	v_permlane32_swap_b32_e32 v33, v36
	v_cndmask_b32_e64 v33, v33, v36, s[38:39]
	v_add_f32_e32 v36, v107, v53
	v_add_f32_e32 v108, v36, v39
	v_mov_b32_e32 v36, v108
	v_mov_b32_e32 v39, v108
	s_nop 1
	v_permlane32_swap_b32_e32 v36, v39
	v_cndmask_b32_e64 v110, v36, v39, s[38:39]
	v_add_f32_e32 v36, v109, v111
	v_add_f32_e32 v39, v119, v121
	v_add_f32_e32 v112, v36, v39
	v_mov_b32_e32 v36, v112
	v_mov_b32_e32 v39, v112
	s_nop 1
	v_permlane32_swap_b32_e32 v36, v39
	v_cndmask_b32_e64 v114, v36, v39, s[38:39]
	v_add_f32_e32 v36, v58, v122
	v_add_f32_e32 v39, v124, v126
	v_add_f32_e32 v60, v36, v39
	v_mov_b32_e32 v36, v60
	v_mov_b32_e32 v39, v60
	s_nop 1
	v_permlane32_swap_b32_e32 v36, v39
	v_cndmask_b32_e64 v62, v36, v39, s[38:39]
	v_add_f32_e32 v36, v59, v63
	v_add_f32_e32 v39, v128, v131
	v_add_f32_e32 v46, v36, v39
	v_mov_b32_e32 v36, v46
	v_mov_b32_e32 v39, v46
	s_nop 1
	v_permlane32_swap_b32_e32 v36, v39
	v_cndmask_b32_e64 v58, v36, v39, s[38:39]
	v_add_f32_e32 v36, v136, v138
	v_add_f32_e32 v42, v35, v36
	v_mov_b32_e32 v35, v42
	v_mov_b32_e32 v36, v42
	s_nop 1
	v_permlane32_swap_b32_e32 v35, v36
	v_cndmask_b32_e64 v44, v35, v36, s[38:39]
	v_add_f32_e32 v35, v37, v45
	v_add_f32_e32 v39, v145, v47
	v_add_f32_e32 v34, v34, v38
	v_add_f32_e32 v35, v35, v39
	v_add_f32_e32 v36, v142, v43
	v_mov_b32_e32 v37, v35
	v_mov_b32_e32 v39, v35
	s_nop 1
	v_permlane32_swap_b32_e32 v37, v39
	v_cndmask_b32_e64 v37, v37, v39, s[38:39]
	v_add_f32_e32 v40, v34, v36
	v_add_f32_e32 v41, v35, v37
	v_cmp_ge_i32_e32 vcc, s18, v99
	v_mov_b32_e32 v34, v40
	v_mov_b32_e32 v35, v40
	s_nop 1
	v_permlane32_swap_b32_e32 v34, v35
	v_cndmask_b32_e64 v92, v34, v35, s[38:39]
	v_cndmask_b32_e64 v34, 0, v37, s[38:39]
	v_add_f32_e32 v34, v93, v34
	v_add_f32_e32 v35, v47, v34
	v_add_f32_e32 v36, v145, v35
	v_add_f32_e32 v37, v45, v36
	v_add_f32_e32 v36, v117, v36
	v_add_f32_e32 v37, v116, v37
	v_add_f32_e32 v116, v40, v92
	v_add_f32_e32 v117, v41, v93
	v_cndmask_b32_e64 v39, 0, v92, s[38:39]
	v_add_f32_e32 v39, v39, v117
	v_add_f32_e32 v40, v43, v39
	v_add_f32_e32 v41, v142, v40
	v_add_f32_e32 v43, v38, v41
	v_add_f32_e32 v38, v143, v39
	v_add_f32_e32 v39, v141, v40
	v_add_f32_e32 v40, v140, v41
	v_add_f32_e32 v41, v139, v43
	v_mov_b32_e32 v43, v116
	v_mov_b32_e32 v45, v117
	v_add_f32_e32 v92, v42, v44
	v_add_f32_e32 v93, v43, v45
	v_cndmask_b32_e64 v42, 0, v44, s[38:39]
	v_mov_b32_e32 v47, v92
	v_mov_b32_e32 v59, v93
	v_add_f32_e32 v42, v42, v93
	v_add_f32_e32 v92, v46, v58
	v_add_f32_e32 v93, v47, v59
	v_cndmask_b32_e64 v46, 0, v58, s[38:39]
	v_add_f32_e32 v46, v46, v93
	v_add_f32_e32 v47, v131, v46
	v_add_f32_e32 v58, v128, v47
	v_add_f32_e32 v59, v63, v58
	v_add_f32_e32 v57, v57, v58
	v_add_f32_e32 v58, v61, v59
	v_mov_b32_e32 v61, v92
	v_mov_b32_e32 v63, v93
	v_add_f32_e32 v92, v60, v62
	v_add_f32_e32 v93, v61, v63
	v_cndmask_b32_e64 v59, 0, v62, s[38:39]
	v_add_f32_e32 v59, v59, v93
	v_add_f32_e32 v60, v126, v59
	v_add_f32_e32 v61, v124, v60
	v_add_f32_e32 v62, v122, v61
	v_add_f32_e32 v61, v115, v61
	v_add_f32_e32 v62, v113, v62
	v_mov_b32_e32 v113, v92
	v_mov_b32_e32 v115, v93
	v_add_f32_e32 v112, v112, v114
	v_add_f32_e32 v113, v113, v115
	v_cndmask_b32_e64 v63, 0, v114, s[38:39]
	v_add_f32_e32 v63, v63, v113
	v_add_f32_e32 v92, v121, v63
	v_add_f32_e32 v93, v119, v92
	v_add_f32_e32 v107, v111, v93
	v_mov_b32_e32 v109, v112
	v_mov_b32_e32 v111, v113
	v_add_f32_e32 v56, v56, v93
	v_add_f32_e32 v93, v106, v107
	v_add_f32_e32 v106, v108, v110
	v_add_f32_e32 v107, v109, v111
	v_cndmask_b32_e64 v108, 0, v110, s[38:39]
	v_add_f32_e32 v108, v108, v107
	v_add_f32_e32 v55, v55, v108
	v_add_f32_e32 v109, v54, v55
	v_add_f32_e32 v110, v53, v109
	v_add_f32_e32 v51, v51, v110
	v_add_f32_e32 v54, v104, v55
	v_exp_f32_e32 v55, v51
	v_add_f32_e32 v51, v106, v107
	v_cndmask_b32_e64 v104, 0, v33, s[38:39]
	v_add_f32_e32 v104, v104, v51
	v_add_f32_e32 v43, v138, v42
	v_add_f32_e32 v50, v50, v104
	v_add_f32_e32 v44, v136, v43
	v_add_f32_e32 v53, v105, v108
	v_add_f32_e32 v105, v49, v50
	v_add_f32_e32 v45, v134, v44
	v_add_f32_e32 v106, v48, v105
	v_add_f32_e32 v34, v146, v34
	v_add_f32_e32 v35, v144, v35
	v_add_f32_e32 v42, v137, v42
	v_add_f32_e32 v43, v135, v43
	v_add_f32_e32 v44, v133, v44
	v_add_f32_e32 v45, v132, v45
	v_add_f32_e32 v46, v130, v46
	v_add_f32_e32 v47, v127, v47
	v_add_f32_e32 v59, v125, v59
	v_add_f32_e32 v60, v123, v60
	v_add_f32_e32 v63, v120, v63
	v_add_f32_e32 v92, v118, v92
	v_add_f32_e32 v52, v52, v109
	v_add_f32_e32 v48, v103, v104
	v_add_f32_e32 v49, v102, v50
	v_add_f32_e32 v50, v101, v105
	v_add_f32_e32 v100, v100, v106
	v_exp_f32_e32 v34, v34
	v_exp_f32_e32 v35, v35
	v_exp_f32_e32 v36, v36
	v_exp_f32_e32 v37, v37
	v_exp_f32_e32 v38, v38
	v_exp_f32_e32 v39, v39
	v_exp_f32_e32 v40, v40
	v_exp_f32_e32 v41, v41
	v_exp_f32_e32 v42, v42
	v_exp_f32_e32 v43, v43
	v_exp_f32_e32 v44, v44
	v_exp_f32_e32 v45, v45
	v_exp_f32_e32 v46, v46
	v_exp_f32_e32 v47, v47
	v_exp_f32_e32 v57, v57
	v_exp_f32_e32 v58, v58
	v_exp_f32_e32 v59, v59
	v_exp_f32_e32 v60, v60
	v_exp_f32_e32 v61, v61
	v_exp_f32_e32 v62, v62
	v_exp_f32_e32 v63, v63
	v_exp_f32_e32 v92, v92
	v_exp_f32_e32 v56, v56
	v_exp_f32_e32 v93, v93
	v_exp_f32_e32 v53, v53
	v_exp_f32_e32 v54, v54
	v_exp_f32_e32 v52, v52
	v_exp_f32_e32 v48, v48
	v_exp_f32_e32 v49, v49
	v_exp_f32_e32 v50, v50
	v_exp_f32_e32 v100, v100
	s_cbranch_vccnz .LBB0_470
	s_or_b64 vcc, s[44:45], s[42:43]
	v_cndmask_b32_e32 v100, 0, v100, vcc
	s_or_b64 vcc, s[10:11], s[8:9]
	v_cndmask_b32_e32 v35, 0, v35, vcc
	s_or_b64 vcc, vcc, s[6:7]
	v_cndmask_b32_e32 v36, 0, v36, vcc
	s_or_b64 vcc, vcc, s[4:5]
	v_cndmask_b32_e32 v37, 0, v37, vcc
	s_or_b64 vcc, vcc, s[96:97]
	v_cndmask_b32_e32 v38, 0, v38, vcc
	s_or_b64 vcc, vcc, s[94:95]
	v_cndmask_b32_e32 v39, 0, v39, vcc
	s_or_b64 vcc, vcc, s[92:93]
	v_cndmask_b32_e32 v40, 0, v40, vcc
	s_or_b64 vcc, vcc, s[90:91]
	v_cndmask_b32_e32 v41, 0, v41, vcc
	s_or_b64 vcc, vcc, s[88:89]
	v_cndmask_b32_e32 v42, 0, v42, vcc
	s_or_b64 vcc, vcc, s[86:87]
	v_cndmask_b32_e32 v43, 0, v43, vcc
	s_or_b64 vcc, vcc, s[84:85]
	v_cndmask_b32_e32 v44, 0, v44, vcc
	s_or_b64 vcc, vcc, s[82:83]
	v_cndmask_b32_e32 v45, 0, v45, vcc
	s_or_b64 vcc, vcc, s[80:81]
	v_cndmask_b32_e32 v46, 0, v46, vcc
	s_or_b64 vcc, vcc, s[78:79]
	v_cndmask_b32_e32 v47, 0, v47, vcc
	s_or_b64 vcc, vcc, s[74:75]
	v_cndmask_b32_e32 v57, 0, v57, vcc
	s_or_b64 vcc, vcc, s[70:71]
	v_cndmask_b32_e32 v58, 0, v58, vcc
	s_or_b64 vcc, vcc, s[64:65]
	v_cndmask_b32_e64 v50, 0, v50, s[44:45]
	v_cndmask_b32_e64 v49, 0, v49, s[46:47]
	v_cndmask_b32_e64 v48, 0, v48, s[48:49]
	v_cndmask_b32_e64 v55, 0, v55, s[50:51]
	v_cndmask_b32_e64 v52, 0, v52, s[52:53]
	v_cndmask_b32_e64 v54, 0, v54, s[54:55]
	v_cndmask_b32_e64 v53, 0, v53, s[56:57]
	v_cndmask_b32_e64 v93, 0, v93, s[58:59]
	v_cndmask_b32_e64 v56, 0, v56, s[60:61]
	v_cndmask_b32_e64 v92, 0, v92, s[62:63]
	v_cndmask_b32_e64 v63, 0, v63, s[66:67]
	v_cndmask_b32_e64 v62, 0, v62, s[68:69]
	v_cndmask_b32_e64 v61, 0, v61, s[72:73]
	v_cndmask_b32_e64 v60, 0, v60, s[76:77]
	v_cndmask_b32_e64 v34, 0, v34, s[10:11]
	v_cndmask_b32_e32 v59, 0, v59, vcc
